# GEMM epilogue output stores of P1/P3/P4/P6 made write-through (sc1) so the L2 writeback at the grid barrier is short
# speedup vs baseline: 1.0031x; 1.0031x over previous
.LBB0_102:
	v_readlane_b32 s0, v250, 19
	s_cmp_eq_u32 s2, 2
	v_readlane_b32 s1, v250, 20
	s_cselect_b32 s1, s91, s1
	s_cselect_b32 s0, s90, s0
	s_lshl_b32 s2, s15, 3
	v_lshlrev_b32_e32 v132, 1, v136
	s_lshr_b32 s24, s13, 5
	v_lshl_add_u64 v[142:143], s[0:1], 0, v[132:133]
	s_or_b32 s0, s24, s2
	v_lshlrev_b32_e32 v132, 1, v134
	s_ashr_i32 s1, s0, 31
	v_lshl_add_u64 v[142:143], v[142:143], 0, v[132:133]
	s_lshl_b64 s[0:1], s[0:1], 10
	v_lshl_add_u64 v[168:169], v[142:143], 0, s[0:1]
	v_cvt_pk_bf16_f32 v148, v148, v149
	v_cvt_pk_bf16_f32 v149, v144, v145
	v_cvt_pk_bf16_f32 v150, v150, v151
	v_cvt_pk_bf16_f32 v151, v146, v147
	v_cndmask_b32_e64 v132, 0, 1, s[22:23]
	global_store_dwordx4 v[168:169], v[148:151], off sc1
	v_cmp_ne_u32_e64 s[0:1], 1, v132
	s_andn2_b64 vcc, exec, s[22:23]
	v_mov_b32_e32 v147, v115
	v_mov_b32_e32 v146, v114
	v_mov_b32_e32 v151, v113
	v_mov_b32_e32 v150, v112
	v_mov_b32_e32 v145, v119
	v_mov_b32_e32 v144, v118
	v_mov_b32_e32 v149, v117
	v_mov_b32_e32 v148, v116
	s_cbranch_vccnz .LBB0_104
	v_mul_f32_e32 v132, 0xbfb8aa3b, v116
	v_exp_f32_e32 v132, v132
	v_mul_f32_e32 v144, 0xbfb8aa3b, v112
	v_mul_f32_e32 v145, 0xbfb8aa3b, v117
	v_exp_f32_e32 v144, v144
	v_exp_f32_e32 v145, v145
	v_add_f32_e32 v132, 1.0, v132
	v_rcp_f32_e32 v146, v132
	v_add_f32_e32 v132, 1.0, v144
	v_rcp_f32_e32 v150, v132
	v_add_f32_e32 v132, 1.0, v145
	v_mul_f32_e32 v145, 0xbfb8aa3b, v114
	v_rcp_f32_e32 v147, v132
	v_mul_f32_e32 v132, 0xbfb8aa3b, v113
	v_mul_f32_e32 v144, 0xbfb8aa3b, v118
	v_exp_f32_e32 v145, v145
	v_mul_f32_e32 v148, 0xbfb8aa3b, v119
	v_mul_f32_e32 v149, 0xbfb8aa3b, v115
	v_exp_f32_e32 v132, v132
	v_exp_f32_e32 v144, v144
	v_exp_f32_e32 v148, v148
	v_exp_f32_e32 v149, v149
	v_add_f32_e32 v145, 1.0, v145
	v_add_f32_e32 v132, 1.0, v132
	v_add_f32_e32 v144, 1.0, v144
	v_rcp_f32_e32 v168, v145
	v_add_f32_e32 v145, 1.0, v148
	v_add_f32_e32 v148, 1.0, v149
	v_rcp_f32_e32 v144, v144
	v_rcp_f32_e32 v145, v145
	v_rcp_f32_e32 v169, v148
	v_rcp_f32_e32 v151, v132
	v_pk_mul_f32 v[148:149], v[116:117], v[146:147]
	v_pk_mul_f32 v[144:145], v[118:119], v[144:145]
	v_pk_mul_f32 v[146:147], v[114:115], v[168:169]
	v_pk_mul_f32 v[150:151], v[112:113], v[150:151]
.LBB0_104:
	s_or_b32 s22, s24, 4
	s_or_b32 s26, s22, s2
	s_ashr_i32 s27, s26, 31
	s_lshl_b64 s[26:27], s[26:27], 10
	v_lshl_add_u64 v[168:169], v[142:143], 0, s[26:27]
	v_cvt_pk_bf16_f32 v148, v148, v149
	v_cvt_pk_bf16_f32 v149, v144, v145
	v_cvt_pk_bf16_f32 v150, v150, v151
	v_cvt_pk_bf16_f32 v151, v146, v147
	global_store_dwordx4 v[168:169], v[148:151], off sc1
	s_and_b64 vcc, exec, s[0:1]
	v_mov_b32_e32 v147, v107
	v_mov_b32_e32 v146, v106
	v_mov_b32_e32 v151, v105
	v_mov_b32_e32 v150, v104
	v_mov_b32_e32 v145, v111
	v_mov_b32_e32 v144, v110
	v_mov_b32_e32 v149, v109
	v_mov_b32_e32 v148, v108
	s_cbranch_vccnz .LBB0_106
	v_mul_f32_e32 v132, 0xbfb8aa3b, v108
	v_exp_f32_e32 v132, v132
	v_mul_f32_e32 v144, 0xbfb8aa3b, v104
	v_mul_f32_e32 v145, 0xbfb8aa3b, v109
	v_exp_f32_e32 v144, v144
	v_exp_f32_e32 v145, v145
	v_add_f32_e32 v132, 1.0, v132
	v_rcp_f32_e32 v146, v132
	v_add_f32_e32 v132, 1.0, v144
	v_rcp_f32_e32 v150, v132
	v_add_f32_e32 v132, 1.0, v145
	v_mul_f32_e32 v145, 0xbfb8aa3b, v106
	v_rcp_f32_e32 v147, v132
	v_mul_f32_e32 v132, 0xbfb8aa3b, v105
	v_mul_f32_e32 v144, 0xbfb8aa3b, v110
	v_exp_f32_e32 v145, v145
	v_mul_f32_e32 v148, 0xbfb8aa3b, v111
	v_mul_f32_e32 v149, 0xbfb8aa3b, v107
	v_exp_f32_e32 v132, v132
	v_exp_f32_e32 v144, v144
	v_exp_f32_e32 v148, v148
	v_exp_f32_e32 v149, v149
	v_add_f32_e32 v145, 1.0, v145
	v_add_f32_e32 v132, 1.0, v132
	v_add_f32_e32 v144, 1.0, v144
	v_rcp_f32_e32 v168, v145
	v_add_f32_e32 v145, 1.0, v148
	v_add_f32_e32 v148, 1.0, v149
	v_rcp_f32_e32 v144, v144
	v_rcp_f32_e32 v145, v145
	v_rcp_f32_e32 v169, v148
	v_rcp_f32_e32 v151, v132
	v_pk_mul_f32 v[148:149], v[108:109], v[146:147]
	v_pk_mul_f32 v[144:145], v[110:111], v[144:145]
	v_pk_mul_f32 v[146:147], v[106:107], v[168:169]
	v_pk_mul_f32 v[150:151], v[104:105], v[150:151]
.LBB0_106:
	s_or_b32 s23, s2, 0x80
	s_or_b32 s26, s23, s24
	s_ashr_i32 s27, s26, 31
	s_lshl_b64 s[26:27], s[26:27], 10
	v_lshl_add_u64 v[168:169], v[142:143], 0, s[26:27]
	v_cvt_pk_bf16_f32 v148, v148, v149
	v_cvt_pk_bf16_f32 v149, v144, v145
	v_cvt_pk_bf16_f32 v150, v150, v151
	v_cvt_pk_bf16_f32 v151, v146, v147
	global_store_dwordx4 v[168:169], v[148:151], off sc1
	s_and_b64 vcc, exec, s[0:1]
	v_mov_b32_e32 v147, v99
	v_mov_b32_e32 v146, v98
	v_mov_b32_e32 v151, v97
	v_mov_b32_e32 v150, v96
	v_mov_b32_e32 v145, v103
	v_mov_b32_e32 v144, v102
	v_mov_b32_e32 v149, v101
	v_mov_b32_e32 v148, v100
	s_cbranch_vccnz .LBB0_108
	v_mul_f32_e32 v132, 0xbfb8aa3b, v100
	v_exp_f32_e32 v132, v132
	v_mul_f32_e32 v144, 0xbfb8aa3b, v96
	v_mul_f32_e32 v145, 0xbfb8aa3b, v101
	v_exp_f32_e32 v144, v144
	v_exp_f32_e32 v145, v145
	v_add_f32_e32 v132, 1.0, v132
	v_rcp_f32_e32 v146, v132
	v_add_f32_e32 v132, 1.0, v144
	v_rcp_f32_e32 v150, v132
	v_add_f32_e32 v132, 1.0, v145
	v_mul_f32_e32 v145, 0xbfb8aa3b, v98
	v_rcp_f32_e32 v147, v132
	v_mul_f32_e32 v132, 0xbfb8aa3b, v97
	v_mul_f32_e32 v144, 0xbfb8aa3b, v102
	v_exp_f32_e32 v145, v145
	v_mul_f32_e32 v148, 0xbfb8aa3b, v103
	v_mul_f32_e32 v149, 0xbfb8aa3b, v99
	v_exp_f32_e32 v132, v132
	v_exp_f32_e32 v144, v144
	v_exp_f32_e32 v148, v148
	v_exp_f32_e32 v149, v149
	v_add_f32_e32 v145, 1.0, v145
	v_add_f32_e32 v132, 1.0, v132
	v_add_f32_e32 v144, 1.0, v144
	v_rcp_f32_e32 v168, v145
	v_add_f32_e32 v145, 1.0, v148
	v_add_f32_e32 v148, 1.0, v149
	v_rcp_f32_e32 v144, v144
	v_rcp_f32_e32 v145, v145
	v_rcp_f32_e32 v169, v148
	v_rcp_f32_e32 v151, v132
	v_pk_mul_f32 v[148:149], v[100:101], v[146:147]
	v_pk_mul_f32 v[144:145], v[102:103], v[144:145]
	v_pk_mul_f32 v[146:147], v[98:99], v[168:169]
	v_pk_mul_f32 v[150:151], v[96:97], v[150:151]
.LBB0_108:
	s_or_b32 s26, s22, s23
	s_ashr_i32 s27, s26, 31
	s_lshl_b64 s[26:27], s[26:27], 10
	v_lshl_add_u64 v[168:169], v[142:143], 0, s[26:27]
	v_cvt_pk_bf16_f32 v148, v148, v149
	v_cvt_pk_bf16_f32 v149, v144, v145
	v_cvt_pk_bf16_f32 v150, v150, v151
	v_cvt_pk_bf16_f32 v151, v146, v147
	global_store_dwordx4 v[168:169], v[148:151], off sc1
	s_and_b64 vcc, exec, s[0:1]
	v_mov_b32_e32 v147, v91
	v_mov_b32_e32 v146, v90
	v_mov_b32_e32 v151, v89
	v_mov_b32_e32 v150, v88
	v_mov_b32_e32 v145, v95
	v_mov_b32_e32 v144, v94
	v_mov_b32_e32 v149, v93
	v_mov_b32_e32 v148, v92
	s_cbranch_vccnz .LBB0_110
	v_mul_f32_e32 v132, 0xbfb8aa3b, v92
	v_exp_f32_e32 v132, v132
	v_mul_f32_e32 v144, 0xbfb8aa3b, v88
	v_mul_f32_e32 v145, 0xbfb8aa3b, v93
	v_exp_f32_e32 v144, v144
	v_exp_f32_e32 v145, v145
	v_add_f32_e32 v132, 1.0, v132
	v_rcp_f32_e32 v146, v132
	v_add_f32_e32 v132, 1.0, v144
	v_rcp_f32_e32 v150, v132
	v_add_f32_e32 v132, 1.0, v145
	v_mul_f32_e32 v145, 0xbfb8aa3b, v90
	v_rcp_f32_e32 v147, v132
	v_mul_f32_e32 v132, 0xbfb8aa3b, v89
	v_mul_f32_e32 v144, 0xbfb8aa3b, v94
	v_exp_f32_e32 v145, v145
	v_mul_f32_e32 v148, 0xbfb8aa3b, v95
	v_mul_f32_e32 v149, 0xbfb8aa3b, v91
	v_exp_f32_e32 v132, v132
	v_exp_f32_e32 v144, v144
	v_exp_f32_e32 v148, v148
	v_exp_f32_e32 v149, v149
	v_add_f32_e32 v145, 1.0, v145
	v_add_f32_e32 v132, 1.0, v132
	v_add_f32_e32 v144, 1.0, v144
	v_rcp_f32_e32 v168, v145
	v_add_f32_e32 v145, 1.0, v148
	v_add_f32_e32 v148, 1.0, v149
	v_rcp_f32_e32 v144, v144
	v_rcp_f32_e32 v145, v145
	v_rcp_f32_e32 v169, v148
	v_rcp_f32_e32 v151, v132
	v_pk_mul_f32 v[148:149], v[92:93], v[146:147]
	v_pk_mul_f32 v[144:145], v[94:95], v[144:145]
	v_pk_mul_f32 v[146:147], v[90:91], v[168:169]
	v_pk_mul_f32 v[150:151], v[88:89], v[150:151]
.LBB0_110:
	s_or_b32 s23, s2, 0x100
	s_or_b32 s26, s23, s24
	s_ashr_i32 s27, s26, 31
	s_lshl_b64 s[26:27], s[26:27], 10
	v_lshl_add_u64 v[168:169], v[142:143], 0, s[26:27]
	v_cvt_pk_bf16_f32 v148, v148, v149
	v_cvt_pk_bf16_f32 v149, v144, v145
	v_cvt_pk_bf16_f32 v150, v150, v151
	v_cvt_pk_bf16_f32 v151, v146, v147
	global_store_dwordx4 v[168:169], v[148:151], off sc1
	s_and_b64 vcc, exec, s[0:1]
	v_mov_b32_e32 v147, v83
	v_mov_b32_e32 v146, v82
	v_mov_b32_e32 v151, v81
	v_mov_b32_e32 v150, v80
	v_mov_b32_e32 v145, v87
	v_mov_b32_e32 v144, v86
	v_mov_b32_e32 v149, v85
	v_mov_b32_e32 v148, v84
	s_cbranch_vccnz .LBB0_112
	v_mul_f32_e32 v132, 0xbfb8aa3b, v84
	v_exp_f32_e32 v132, v132
	v_mul_f32_e32 v144, 0xbfb8aa3b, v80
	v_mul_f32_e32 v145, 0xbfb8aa3b, v85
	v_exp_f32_e32 v144, v144
	v_exp_f32_e32 v145, v145
	v_add_f32_e32 v132, 1.0, v132
	v_rcp_f32_e32 v146, v132
	v_add_f32_e32 v132, 1.0, v144
	v_rcp_f32_e32 v150, v132
	v_add_f32_e32 v132, 1.0, v145
	v_mul_f32_e32 v145, 0xbfb8aa3b, v82
	v_rcp_f32_e32 v147, v132
	v_mul_f32_e32 v132, 0xbfb8aa3b, v81
	v_mul_f32_e32 v144, 0xbfb8aa3b, v86
	v_exp_f32_e32 v145, v145
	v_mul_f32_e32 v148, 0xbfb8aa3b, v87
	v_mul_f32_e32 v149, 0xbfb8aa3b, v83
	v_exp_f32_e32 v132, v132
	v_exp_f32_e32 v144, v144
	v_exp_f32_e32 v148, v148
	v_exp_f32_e32 v149, v149
	v_add_f32_e32 v145, 1.0, v145
	v_add_f32_e32 v132, 1.0, v132
	v_add_f32_e32 v144, 1.0, v144
	v_rcp_f32_e32 v168, v145
	v_add_f32_e32 v145, 1.0, v148
	v_add_f32_e32 v148, 1.0, v149
	v_rcp_f32_e32 v144, v144
	v_rcp_f32_e32 v145, v145
	v_rcp_f32_e32 v169, v148
	v_rcp_f32_e32 v151, v132
	v_pk_mul_f32 v[148:149], v[84:85], v[146:147]
	v_pk_mul_f32 v[144:145], v[86:87], v[144:145]
	v_pk_mul_f32 v[146:147], v[82:83], v[168:169]
	v_pk_mul_f32 v[150:151], v[80:81], v[150:151]
.LBB0_112:
	s_or_b32 s26, s22, s23
	s_ashr_i32 s27, s26, 31
	s_lshl_b64 s[26:27], s[26:27], 10
	v_lshl_add_u64 v[168:169], v[142:143], 0, s[26:27]
	v_cvt_pk_bf16_f32 v148, v148, v149
	v_cvt_pk_bf16_f32 v149, v144, v145
	v_cvt_pk_bf16_f32 v150, v150, v151
	v_cvt_pk_bf16_f32 v151, v146, v147
	global_store_dwordx4 v[168:169], v[148:151], off sc1
	s_and_b64 vcc, exec, s[0:1]
	v_mov_b32_e32 v147, v75
	v_mov_b32_e32 v146, v74
	v_mov_b32_e32 v151, v73
	v_mov_b32_e32 v150, v72
	v_mov_b32_e32 v145, v79
	v_mov_b32_e32 v144, v78
	v_mov_b32_e32 v149, v77
	v_mov_b32_e32 v148, v76
	s_cbranch_vccnz .LBB0_114
	v_mul_f32_e32 v132, 0xbfb8aa3b, v76
	v_exp_f32_e32 v132, v132
	v_mul_f32_e32 v144, 0xbfb8aa3b, v72
	v_mul_f32_e32 v145, 0xbfb8aa3b, v77
	v_exp_f32_e32 v144, v144
	v_exp_f32_e32 v145, v145
	v_add_f32_e32 v132, 1.0, v132
	v_rcp_f32_e32 v146, v132
	v_add_f32_e32 v132, 1.0, v144
	v_rcp_f32_e32 v150, v132
	v_add_f32_e32 v132, 1.0, v145
	v_mul_f32_e32 v145, 0xbfb8aa3b, v74
	v_rcp_f32_e32 v147, v132
	v_mul_f32_e32 v132, 0xbfb8aa3b, v73
	v_mul_f32_e32 v144, 0xbfb8aa3b, v78
	v_exp_f32_e32 v145, v145
	v_mul_f32_e32 v148, 0xbfb8aa3b, v79
	v_mul_f32_e32 v149, 0xbfb8aa3b, v75
	v_exp_f32_e32 v132, v132
	v_exp_f32_e32 v144, v144
	v_exp_f32_e32 v148, v148
	v_exp_f32_e32 v149, v149
	v_add_f32_e32 v145, 1.0, v145
	v_add_f32_e32 v132, 1.0, v132
	v_add_f32_e32 v144, 1.0, v144
	v_rcp_f32_e32 v168, v145
	v_add_f32_e32 v145, 1.0, v148
	v_add_f32_e32 v148, 1.0, v149
	v_rcp_f32_e32 v144, v144
	v_rcp_f32_e32 v145, v145
	v_rcp_f32_e32 v169, v148
	v_rcp_f32_e32 v151, v132
	v_pk_mul_f32 v[148:149], v[76:77], v[146:147]
	v_pk_mul_f32 v[144:145], v[78:79], v[144:145]
	v_pk_mul_f32 v[146:147], v[74:75], v[168:169]
	v_pk_mul_f32 v[150:151], v[72:73], v[150:151]
.LBB0_114:
	s_or_b32 s23, s2, 0x180
	s_or_b32 s26, s23, s24
	s_ashr_i32 s27, s26, 31
	s_lshl_b64 s[26:27], s[26:27], 10
	v_lshl_add_u64 v[168:169], v[142:143], 0, s[26:27]
	v_cvt_pk_bf16_f32 v148, v148, v149
	v_cvt_pk_bf16_f32 v149, v144, v145
	v_cvt_pk_bf16_f32 v150, v150, v151
	v_cvt_pk_bf16_f32 v151, v146, v147
	global_store_dwordx4 v[168:169], v[148:151], off sc1
	s_and_b64 vcc, exec, s[0:1]
	v_mov_b32_e32 v147, v67
	v_mov_b32_e32 v146, v66
	v_mov_b32_e32 v151, v65
	v_mov_b32_e32 v150, v64
	v_mov_b32_e32 v145, v71
	v_mov_b32_e32 v144, v70
	v_mov_b32_e32 v149, v69
	v_mov_b32_e32 v148, v68
	s_cbranch_vccnz .LBB0_116
	v_mul_f32_e32 v132, 0xbfb8aa3b, v68
	v_exp_f32_e32 v132, v132
	v_mul_f32_e32 v144, 0xbfb8aa3b, v64
	v_mul_f32_e32 v145, 0xbfb8aa3b, v69
	v_exp_f32_e32 v144, v144
	v_exp_f32_e32 v145, v145
	v_add_f32_e32 v132, 1.0, v132
	v_rcp_f32_e32 v146, v132
	v_add_f32_e32 v132, 1.0, v144
	v_rcp_f32_e32 v150, v132
	v_add_f32_e32 v132, 1.0, v145
	v_mul_f32_e32 v145, 0xbfb8aa3b, v66
	v_rcp_f32_e32 v147, v132
	v_mul_f32_e32 v132, 0xbfb8aa3b, v65
	v_mul_f32_e32 v144, 0xbfb8aa3b, v70
	v_exp_f32_e32 v145, v145
	v_mul_f32_e32 v148, 0xbfb8aa3b, v71
	v_mul_f32_e32 v149, 0xbfb8aa3b, v67
	v_exp_f32_e32 v132, v132
	v_exp_f32_e32 v144, v144
	v_exp_f32_e32 v148, v148
	v_exp_f32_e32 v149, v149
	v_add_f32_e32 v145, 1.0, v145
	v_add_f32_e32 v132, 1.0, v132
	v_add_f32_e32 v144, 1.0, v144
	v_rcp_f32_e32 v168, v145
	v_add_f32_e32 v145, 1.0, v148
	v_add_f32_e32 v148, 1.0, v149
	v_rcp_f32_e32 v144, v144
	v_rcp_f32_e32 v145, v145
	v_rcp_f32_e32 v169, v148
	v_rcp_f32_e32 v151, v132
	v_pk_mul_f32 v[148:149], v[68:69], v[146:147]
	v_pk_mul_f32 v[144:145], v[70:71], v[144:145]
	v_pk_mul_f32 v[146:147], v[66:67], v[168:169]
	v_pk_mul_f32 v[150:151], v[64:65], v[150:151]
.LBB0_116:
	s_or_b32 s26, s22, s23
	s_ashr_i32 s27, s26, 31
	s_lshl_b64 s[26:27], s[26:27], 10
	v_lshl_add_u64 v[168:169], v[142:143], 0, s[26:27]
	v_cvt_pk_bf16_f32 v148, v148, v149
	v_cvt_pk_bf16_f32 v149, v144, v145
	v_cvt_pk_bf16_f32 v150, v150, v151
	v_cvt_pk_bf16_f32 v151, v146, v147
	global_store_dwordx4 v[168:169], v[148:151], off sc1
	s_and_b64 vcc, exec, s[0:1]
	v_mov_b32_e32 v147, v59
	v_mov_b32_e32 v146, v58
	v_mov_b32_e32 v151, v57
	v_mov_b32_e32 v150, v56
	v_mov_b32_e32 v145, v63
	v_mov_b32_e32 v144, v62
	v_mov_b32_e32 v149, v61
	v_mov_b32_e32 v148, v60
	s_cbranch_vccnz .LBB0_118
	v_mul_f32_e32 v132, 0xbfb8aa3b, v60
	v_exp_f32_e32 v132, v132
	v_mul_f32_e32 v144, 0xbfb8aa3b, v56
	v_mul_f32_e32 v145, 0xbfb8aa3b, v61
	v_exp_f32_e32 v144, v144
	v_exp_f32_e32 v145, v145
	v_add_f32_e32 v132, 1.0, v132
	v_rcp_f32_e32 v146, v132
	v_add_f32_e32 v132, 1.0, v144
	v_rcp_f32_e32 v150, v132
	v_add_f32_e32 v132, 1.0, v145
	v_mul_f32_e32 v145, 0xbfb8aa3b, v58
	v_rcp_f32_e32 v147, v132
	v_mul_f32_e32 v132, 0xbfb8aa3b, v57
	v_mul_f32_e32 v144, 0xbfb8aa3b, v62
	v_exp_f32_e32 v145, v145
	v_mul_f32_e32 v148, 0xbfb8aa3b, v63
	v_mul_f32_e32 v149, 0xbfb8aa3b, v59
	v_exp_f32_e32 v132, v132
	v_exp_f32_e32 v144, v144
	v_exp_f32_e32 v148, v148
	v_exp_f32_e32 v149, v149
	v_add_f32_e32 v145, 1.0, v145
	v_add_f32_e32 v132, 1.0, v132
	v_add_f32_e32 v144, 1.0, v144
	v_rcp_f32_e32 v168, v145
	v_add_f32_e32 v145, 1.0, v148
	v_add_f32_e32 v148, 1.0, v149
	v_rcp_f32_e32 v144, v144
	v_rcp_f32_e32 v145, v145
	v_rcp_f32_e32 v169, v148
	v_rcp_f32_e32 v151, v132
	v_pk_mul_f32 v[148:149], v[60:61], v[146:147]
	v_pk_mul_f32 v[144:145], v[62:63], v[144:145]
	v_pk_mul_f32 v[146:147], v[58:59], v[168:169]
	v_pk_mul_f32 v[150:151], v[56:57], v[150:151]
.LBB0_118:
	s_add_i32 s23, s2, 0x400
	s_or_b32 s26, s23, s24
	s_ashr_i32 s27, s26, 31
	s_lshl_b64 s[26:27], s[26:27], 10
	v_lshl_add_u64 v[168:169], v[142:143], 0, s[26:27]
	v_cvt_pk_bf16_f32 v148, v148, v149
	v_cvt_pk_bf16_f32 v149, v144, v145
	v_cvt_pk_bf16_f32 v150, v150, v151
	v_cvt_pk_bf16_f32 v151, v146, v147
	global_store_dwordx4 v[168:169], v[148:151], off sc1
	s_and_b64 vcc, exec, s[0:1]
	v_mov_b32_e32 v147, v51
	v_mov_b32_e32 v146, v50
	v_mov_b32_e32 v151, v49
	v_mov_b32_e32 v150, v48
	v_mov_b32_e32 v145, v55
	v_mov_b32_e32 v144, v54
	v_mov_b32_e32 v149, v53
	v_mov_b32_e32 v148, v52
	s_cbranch_vccnz .LBB0_120
	v_mul_f32_e32 v132, 0xbfb8aa3b, v52
	v_exp_f32_e32 v132, v132
	v_mul_f32_e32 v144, 0xbfb8aa3b, v48
	v_mul_f32_e32 v145, 0xbfb8aa3b, v53
	v_exp_f32_e32 v144, v144
	v_exp_f32_e32 v145, v145
	v_add_f32_e32 v132, 1.0, v132
	v_rcp_f32_e32 v146, v132
	v_add_f32_e32 v132, 1.0, v144
	v_rcp_f32_e32 v150, v132
	v_add_f32_e32 v132, 1.0, v145
	v_mul_f32_e32 v145, 0xbfb8aa3b, v50
	v_rcp_f32_e32 v147, v132
	v_mul_f32_e32 v132, 0xbfb8aa3b, v49
	v_mul_f32_e32 v144, 0xbfb8aa3b, v54
	v_exp_f32_e32 v145, v145
	v_mul_f32_e32 v148, 0xbfb8aa3b, v55
	v_mul_f32_e32 v149, 0xbfb8aa3b, v51
	v_exp_f32_e32 v132, v132
	v_exp_f32_e32 v144, v144
	v_exp_f32_e32 v148, v148
	v_exp_f32_e32 v149, v149
	v_add_f32_e32 v145, 1.0, v145
	v_add_f32_e32 v132, 1.0, v132
	v_add_f32_e32 v144, 1.0, v144
	v_rcp_f32_e32 v168, v145
	v_add_f32_e32 v145, 1.0, v148
	v_add_f32_e32 v148, 1.0, v149
	v_rcp_f32_e32 v144, v144
	v_rcp_f32_e32 v145, v145
	v_rcp_f32_e32 v169, v148
	v_rcp_f32_e32 v151, v132
	v_pk_mul_f32 v[148:149], v[52:53], v[146:147]
	v_pk_mul_f32 v[144:145], v[54:55], v[144:145]
	v_pk_mul_f32 v[146:147], v[50:51], v[168:169]
	v_pk_mul_f32 v[150:151], v[48:49], v[150:151]
.LBB0_120:
	s_or_b32 s26, s22, s23
	s_ashr_i32 s27, s26, 31
	s_lshl_b64 s[26:27], s[26:27], 10
	v_lshl_add_u64 v[168:169], v[142:143], 0, s[26:27]
	v_cvt_pk_bf16_f32 v148, v148, v149
	v_cvt_pk_bf16_f32 v149, v144, v145
	v_cvt_pk_bf16_f32 v150, v150, v151
	v_cvt_pk_bf16_f32 v151, v146, v147
	global_store_dwordx4 v[168:169], v[148:151], off sc1
	s_and_b64 vcc, exec, s[0:1]
	v_mov_b32_e32 v147, v43
	v_mov_b32_e32 v146, v42
	v_mov_b32_e32 v151, v41
	v_mov_b32_e32 v150, v40
	v_mov_b32_e32 v145, v47
	v_mov_b32_e32 v144, v46
	v_mov_b32_e32 v149, v45
	v_mov_b32_e32 v148, v44
	s_cbranch_vccnz .LBB0_122
	v_mul_f32_e32 v132, 0xbfb8aa3b, v44
	v_exp_f32_e32 v132, v132
	v_mul_f32_e32 v144, 0xbfb8aa3b, v40
	v_mul_f32_e32 v145, 0xbfb8aa3b, v45
	v_exp_f32_e32 v144, v144
	v_exp_f32_e32 v145, v145
	v_add_f32_e32 v132, 1.0, v132
	v_rcp_f32_e32 v146, v132
	v_add_f32_e32 v132, 1.0, v144
	v_rcp_f32_e32 v150, v132
	v_add_f32_e32 v132, 1.0, v145
	v_mul_f32_e32 v145, 0xbfb8aa3b, v42
	v_rcp_f32_e32 v147, v132
	v_mul_f32_e32 v132, 0xbfb8aa3b, v41
	v_mul_f32_e32 v144, 0xbfb8aa3b, v46
	v_exp_f32_e32 v145, v145
	v_mul_f32_e32 v148, 0xbfb8aa3b, v47
	v_mul_f32_e32 v149, 0xbfb8aa3b, v43
	v_exp_f32_e32 v132, v132
	v_exp_f32_e32 v144, v144
	v_exp_f32_e32 v148, v148
	v_exp_f32_e32 v149, v149
	v_add_f32_e32 v145, 1.0, v145
	v_add_f32_e32 v132, 1.0, v132
	v_add_f32_e32 v144, 1.0, v144
	v_rcp_f32_e32 v168, v145
	v_add_f32_e32 v145, 1.0, v148
	v_add_f32_e32 v148, 1.0, v149
	v_rcp_f32_e32 v144, v144
	v_rcp_f32_e32 v145, v145
	v_rcp_f32_e32 v169, v148
	v_rcp_f32_e32 v151, v132
	v_pk_mul_f32 v[148:149], v[44:45], v[146:147]
	v_pk_mul_f32 v[144:145], v[46:47], v[144:145]
	v_pk_mul_f32 v[146:147], v[42:43], v[168:169]
	v_pk_mul_f32 v[150:151], v[40:41], v[150:151]
.LBB0_122:
	s_add_i32 s23, s2, 0x480
	s_or_b32 s26, s23, s24
	s_ashr_i32 s27, s26, 31
	s_lshl_b64 s[26:27], s[26:27], 10
	v_lshl_add_u64 v[168:169], v[142:143], 0, s[26:27]
	v_cvt_pk_bf16_f32 v148, v148, v149
	v_cvt_pk_bf16_f32 v149, v144, v145
	v_cvt_pk_bf16_f32 v150, v150, v151
	v_cvt_pk_bf16_f32 v151, v146, v147
	global_store_dwordx4 v[168:169], v[148:151], off sc1
	s_and_b64 vcc, exec, s[0:1]
	v_mov_b32_e32 v147, v35
	v_mov_b32_e32 v146, v34
	v_mov_b32_e32 v151, v33
	v_mov_b32_e32 v150, v32
	v_mov_b32_e32 v145, v39
	v_mov_b32_e32 v144, v38
	v_mov_b32_e32 v149, v37
	v_mov_b32_e32 v148, v36
	s_cbranch_vccnz .LBB0_124
	v_mul_f32_e32 v132, 0xbfb8aa3b, v36
	v_exp_f32_e32 v132, v132
	v_mul_f32_e32 v144, 0xbfb8aa3b, v32
	v_mul_f32_e32 v145, 0xbfb8aa3b, v37
	v_exp_f32_e32 v144, v144
	v_exp_f32_e32 v145, v145
	v_add_f32_e32 v132, 1.0, v132
	v_rcp_f32_e32 v146, v132
	v_add_f32_e32 v132, 1.0, v144
	v_rcp_f32_e32 v150, v132
	v_add_f32_e32 v132, 1.0, v145
	v_mul_f32_e32 v145, 0xbfb8aa3b, v34
	v_rcp_f32_e32 v147, v132
	v_mul_f32_e32 v132, 0xbfb8aa3b, v33
	v_mul_f32_e32 v144, 0xbfb8aa3b, v38
	v_exp_f32_e32 v145, v145
	v_mul_f32_e32 v148, 0xbfb8aa3b, v39
	v_mul_f32_e32 v149, 0xbfb8aa3b, v35
	v_exp_f32_e32 v132, v132
	v_exp_f32_e32 v144, v144
	v_exp_f32_e32 v148, v148
	v_exp_f32_e32 v149, v149
	v_add_f32_e32 v145, 1.0, v145
	v_add_f32_e32 v132, 1.0, v132
	v_add_f32_e32 v144, 1.0, v144
	v_rcp_f32_e32 v168, v145
	v_add_f32_e32 v145, 1.0, v148
	v_add_f32_e32 v148, 1.0, v149
	v_rcp_f32_e32 v144, v144
	v_rcp_f32_e32 v145, v145
	v_rcp_f32_e32 v169, v148
	v_rcp_f32_e32 v151, v132
	v_pk_mul_f32 v[148:149], v[36:37], v[146:147]
	v_pk_mul_f32 v[144:145], v[38:39], v[144:145]
	v_pk_mul_f32 v[146:147], v[34:35], v[168:169]
	v_pk_mul_f32 v[150:151], v[32:33], v[150:151]
.LBB0_124:
	s_or_b32 s26, s22, s23
	s_ashr_i32 s27, s26, 31
	s_lshl_b64 s[26:27], s[26:27], 10
	v_lshl_add_u64 v[168:169], v[142:143], 0, s[26:27]
	v_cvt_pk_bf16_f32 v148, v148, v149
	v_cvt_pk_bf16_f32 v149, v144, v145
	v_cvt_pk_bf16_f32 v150, v150, v151
	v_cvt_pk_bf16_f32 v151, v146, v147
	global_store_dwordx4 v[168:169], v[148:151], off sc1
	s_and_b64 vcc, exec, s[0:1]
	v_mov_b32_e32 v147, v27
	v_mov_b32_e32 v146, v26
	v_mov_b32_e32 v151, v25
	v_mov_b32_e32 v150, v24
	v_mov_b32_e32 v145, v31
	v_mov_b32_e32 v144, v30
	v_mov_b32_e32 v149, v29
	v_mov_b32_e32 v148, v28
	s_cbranch_vccnz .LBB0_126
	v_mul_f32_e32 v132, 0xbfb8aa3b, v28
	v_exp_f32_e32 v132, v132
	v_mul_f32_e32 v144, 0xbfb8aa3b, v24
	v_mul_f32_e32 v145, 0xbfb8aa3b, v29
	v_exp_f32_e32 v144, v144
	v_exp_f32_e32 v145, v145
	v_add_f32_e32 v132, 1.0, v132
	v_rcp_f32_e32 v146, v132
	v_add_f32_e32 v132, 1.0, v144
	v_rcp_f32_e32 v150, v132
	v_add_f32_e32 v132, 1.0, v145
	v_mul_f32_e32 v145, 0xbfb8aa3b, v26
	v_rcp_f32_e32 v147, v132
	v_mul_f32_e32 v132, 0xbfb8aa3b, v25
	v_mul_f32_e32 v144, 0xbfb8aa3b, v30
	v_exp_f32_e32 v145, v145
	v_mul_f32_e32 v148, 0xbfb8aa3b, v31
	v_mul_f32_e32 v149, 0xbfb8aa3b, v27
	v_exp_f32_e32 v132, v132
	v_exp_f32_e32 v144, v144
	v_exp_f32_e32 v148, v148
	v_exp_f32_e32 v149, v149
	v_add_f32_e32 v145, 1.0, v145
	v_add_f32_e32 v132, 1.0, v132
	v_add_f32_e32 v144, 1.0, v144
	v_rcp_f32_e32 v168, v145
	v_add_f32_e32 v145, 1.0, v148
	v_add_f32_e32 v148, 1.0, v149
	v_rcp_f32_e32 v144, v144
	v_rcp_f32_e32 v145, v145
	v_rcp_f32_e32 v169, v148
	v_rcp_f32_e32 v151, v132
	v_pk_mul_f32 v[148:149], v[28:29], v[146:147]
	v_pk_mul_f32 v[144:145], v[30:31], v[144:145]
	v_pk_mul_f32 v[146:147], v[26:27], v[168:169]
	v_pk_mul_f32 v[150:151], v[24:25], v[150:151]
.LBB0_126:
	s_add_i32 s23, s2, 0x500
	s_or_b32 s26, s23, s24
	s_ashr_i32 s27, s26, 31
	s_lshl_b64 s[26:27], s[26:27], 10
	v_lshl_add_u64 v[168:169], v[142:143], 0, s[26:27]
	v_cvt_pk_bf16_f32 v148, v148, v149
	v_cvt_pk_bf16_f32 v149, v144, v145
	v_cvt_pk_bf16_f32 v150, v150, v151
	v_cvt_pk_bf16_f32 v151, v146, v147
	global_store_dwordx4 v[168:169], v[148:151], off sc1
	s_and_b64 vcc, exec, s[0:1]
	v_mov_b32_e32 v147, v19
	v_mov_b32_e32 v146, v18
	v_mov_b32_e32 v151, v17
	v_mov_b32_e32 v150, v16
	v_mov_b32_e32 v145, v23
	v_mov_b32_e32 v144, v22
	v_mov_b32_e32 v149, v21
	v_mov_b32_e32 v148, v20
	s_cbranch_vccnz .LBB0_128
	v_mul_f32_e32 v132, 0xbfb8aa3b, v20
	v_exp_f32_e32 v132, v132
	v_mul_f32_e32 v144, 0xbfb8aa3b, v16
	v_mul_f32_e32 v145, 0xbfb8aa3b, v21
	v_exp_f32_e32 v144, v144
	v_exp_f32_e32 v145, v145
	v_add_f32_e32 v132, 1.0, v132
	v_rcp_f32_e32 v146, v132
	v_add_f32_e32 v132, 1.0, v144
	v_rcp_f32_e32 v150, v132
	v_add_f32_e32 v132, 1.0, v145
	v_mul_f32_e32 v145, 0xbfb8aa3b, v18
	v_rcp_f32_e32 v147, v132
	v_mul_f32_e32 v132, 0xbfb8aa3b, v17
	v_mul_f32_e32 v144, 0xbfb8aa3b, v22
	v_exp_f32_e32 v145, v145
	v_mul_f32_e32 v148, 0xbfb8aa3b, v23
	v_mul_f32_e32 v149, 0xbfb8aa3b, v19
	v_exp_f32_e32 v132, v132
	v_exp_f32_e32 v144, v144
	v_exp_f32_e32 v148, v148
	v_exp_f32_e32 v149, v149
	v_add_f32_e32 v145, 1.0, v145
	v_add_f32_e32 v132, 1.0, v132
	v_add_f32_e32 v144, 1.0, v144
	v_rcp_f32_e32 v168, v145
	v_add_f32_e32 v145, 1.0, v148
	v_add_f32_e32 v148, 1.0, v149
	v_rcp_f32_e32 v144, v144
	v_rcp_f32_e32 v145, v145
	v_rcp_f32_e32 v169, v148
	v_rcp_f32_e32 v151, v132
	v_pk_mul_f32 v[148:149], v[20:21], v[146:147]
	v_pk_mul_f32 v[144:145], v[22:23], v[144:145]
	v_pk_mul_f32 v[146:147], v[18:19], v[168:169]
	v_pk_mul_f32 v[150:151], v[16:17], v[150:151]
.LBB0_128:
	s_or_b32 s26, s22, s23
	s_ashr_i32 s27, s26, 31
	s_lshl_b64 s[26:27], s[26:27], 10
	v_lshl_add_u64 v[168:169], v[142:143], 0, s[26:27]
	v_cvt_pk_bf16_f32 v148, v148, v149
	v_cvt_pk_bf16_f32 v149, v144, v145
	v_cvt_pk_bf16_f32 v150, v150, v151
	v_cvt_pk_bf16_f32 v151, v146, v147
	global_store_dwordx4 v[168:169], v[148:151], off sc1
	s_and_b64 vcc, exec, s[0:1]
	v_mov_b32_e32 v147, v11
	v_mov_b32_e32 v146, v10
	v_mov_b32_e32 v151, v9
	v_mov_b32_e32 v150, v8
	v_mov_b32_e32 v145, v15
	v_mov_b32_e32 v144, v14
	v_mov_b32_e32 v149, v13
	v_mov_b32_e32 v148, v12
	s_cbranch_vccnz .LBB0_130
	v_mul_f32_e32 v132, 0xbfb8aa3b, v12
	v_exp_f32_e32 v132, v132
	v_mul_f32_e32 v144, 0xbfb8aa3b, v8
	v_mul_f32_e32 v145, 0xbfb8aa3b, v13
	v_exp_f32_e32 v144, v144
	v_exp_f32_e32 v145, v145
	v_add_f32_e32 v132, 1.0, v132
	v_rcp_f32_e32 v146, v132
	v_add_f32_e32 v132, 1.0, v144
	v_rcp_f32_e32 v150, v132
	v_add_f32_e32 v132, 1.0, v145
	v_mul_f32_e32 v145, 0xbfb8aa3b, v10
	v_rcp_f32_e32 v147, v132
	v_mul_f32_e32 v132, 0xbfb8aa3b, v9
	v_mul_f32_e32 v144, 0xbfb8aa3b, v14
	v_exp_f32_e32 v145, v145
	v_mul_f32_e32 v148, 0xbfb8aa3b, v15
	v_mul_f32_e32 v149, 0xbfb8aa3b, v11
	v_exp_f32_e32 v132, v132
	v_exp_f32_e32 v144, v144
	v_exp_f32_e32 v148, v148
	v_exp_f32_e32 v149, v149
	v_add_f32_e32 v145, 1.0, v145
	v_add_f32_e32 v132, 1.0, v132
	v_add_f32_e32 v144, 1.0, v144
	v_rcp_f32_e32 v168, v145
	v_add_f32_e32 v145, 1.0, v148
	v_add_f32_e32 v148, 1.0, v149
	v_rcp_f32_e32 v144, v144
	v_rcp_f32_e32 v145, v145
	v_rcp_f32_e32 v169, v148
	v_rcp_f32_e32 v151, v132
	v_pk_mul_f32 v[148:149], v[12:13], v[146:147]
	v_pk_mul_f32 v[144:145], v[14:15], v[144:145]
	v_pk_mul_f32 v[146:147], v[10:11], v[168:169]
	v_pk_mul_f32 v[150:151], v[8:9], v[150:151]
.LBB0_130:
	s_addk_i32 s2, 0x580
	s_or_b32 s24, s2, s24
	s_ashr_i32 s25, s24, 31
	s_lshl_b64 s[24:25], s[24:25], 10
	v_lshl_add_u64 v[168:169], v[142:143], 0, s[24:25]
	v_cvt_pk_bf16_f32 v148, v148, v149
	v_cvt_pk_bf16_f32 v149, v144, v145
	v_cvt_pk_bf16_f32 v150, v150, v151
	v_cvt_pk_bf16_f32 v151, v146, v147
	global_store_dwordx4 v[168:169], v[148:151], off sc1
	s_and_b64 vcc, exec, s[0:1]
	v_mov_b32_e32 v145, v3
	v_mov_b32_e32 v144, v2
	v_mov_b32_e32 v149, v1
	v_mov_b32_e32 v148, v0
	v_mov_b32_e32 v147, v7
	v_mov_b32_e32 v146, v6
	v_mov_b32_e32 v151, v5
	v_mov_b32_e32 v150, v4
	s_cbranch_vccnz .LBB0_132
	v_mul_f32_e32 v132, 0xbfb8aa3b, v4
	v_exp_f32_e32 v132, v132
	v_mul_f32_e32 v144, 0xbfb8aa3b, v0
	v_mul_f32_e32 v145, 0xbfb8aa3b, v5
	v_exp_f32_e32 v146, v144
	v_exp_f32_e32 v145, v145
	v_add_f32_e32 v132, 1.0, v132
	v_rcp_f32_e32 v144, v132
	v_add_f32_e32 v132, 1.0, v146
	v_rcp_f32_e32 v148, v132
	v_add_f32_e32 v132, 1.0, v145
	v_mul_f32_e32 v147, 0xbfb8aa3b, v2
	v_rcp_f32_e32 v145, v132
	v_mul_f32_e32 v132, 0xbfb8aa3b, v1
	v_mul_f32_e32 v146, 0xbfb8aa3b, v6
	v_exp_f32_e32 v147, v147
	v_mul_f32_e32 v149, 0xbfb8aa3b, v7
	v_mul_f32_e32 v150, 0xbfb8aa3b, v3
	v_exp_f32_e32 v132, v132
	v_exp_f32_e32 v146, v146
	v_exp_f32_e32 v149, v149
	v_exp_f32_e32 v150, v150
	v_add_f32_e32 v147, 1.0, v147
	v_add_f32_e32 v132, 1.0, v132
	v_add_f32_e32 v146, 1.0, v146
	v_rcp_f32_e32 v168, v147
	v_add_f32_e32 v147, 1.0, v149
	v_add_f32_e32 v149, 1.0, v150
	v_rcp_f32_e32 v146, v146
	v_rcp_f32_e32 v147, v147
	v_rcp_f32_e32 v169, v149
	v_rcp_f32_e32 v149, v132
	v_pk_mul_f32 v[150:151], v[4:5], v[144:145]
	v_pk_mul_f32 v[146:147], v[6:7], v[146:147]
	v_pk_mul_f32 v[144:145], v[2:3], v[168:169]
	v_pk_mul_f32 v[148:149], v[0:1], v[148:149]
.LBB0_132:
	s_or_b32 s0, s22, s2
	s_ashr_i32 s1, s0, 31
	s_lshl_b64 s[0:1], s[0:1], 10
	v_lshl_add_u64 v[142:143], v[142:143], 0, s[0:1]
	v_cvt_pk_bf16_f32 v168, v150, v151
	v_cvt_pk_bf16_f32 v169, v146, v147
	v_cvt_pk_bf16_f32 v170, v148, v149
	v_cvt_pk_bf16_f32 v171, v144, v145
	global_store_dwordx4 v[142:143], v[168:171], off sc1
	s_branch .LBB0_99

.LBB0_165:
	s_or_b64 exec, exec, s[0:1]
	s_cmp_lt_u32 s20, 16
	s_cselect_b64 vcc, -1, 0
	s_and_b64 s[0:1], vcc, exec
	v_readlane_b32 s0, v250, 21
	s_cselect_b32 s20, s50, s52
	v_readlane_b32 s1, v250, 22
	s_cselect_b32 s2, s51, s53
	s_cselect_b32 s1, s1, s95
	s_cselect_b32 s0, s0, s94
	s_add_u32 s22, s20, s43
	s_waitcnt lgkmcnt(0)
	s_barrier
	s_addc_u32 s23, s2, 0
	v_lshlrev_b32_e32 v132, 2, v134
	global_load_dwordx4 v[144:147], v132, s[22:23]
	global_load_dwordx4 v[148:151], v132, s[22:23] offset:16
	ds_read_b128 v[168:171], v137
	v_cndmask_b32_e32 v172, 1.0, v166, vcc
	v_lshlrev_b32_e32 v132, 1, v136
	s_waitcnt lgkmcnt(0)
	v_mov_b32_e32 v142, v169
	v_mov_b32_e32 v143, v170
	v_mov_b32_e32 v169, v171
	v_pk_add_f32 v[142:143], v[142:143], v[168:169]
	s_nop 0
	v_add_f32_e32 v142, v142, v143
	v_fmamk_f32 v142, v142, 0x3c000000, v163
	v_rsq_f32_e32 v168, v142
	v_lshl_add_u64 v[142:143], s[0:1], 0, v[132:133]
	v_lshlrev_b32_e32 v132, 1, v134
	v_lshl_add_u64 v[142:143], v[142:143], 0, v[132:133]
	v_pk_mul_f32 v[170:171], v[124:125], v[168:169] op_sel_hi:[1,0]
	v_pk_mul_f32 v[174:175], v[126:127], v[168:169] op_sel_hi:[1,0]
	v_pk_mul_f32 v[176:177], v[120:121], v[168:169] op_sel_hi:[1,0]
	v_pk_mul_f32 v[168:169], v[122:123], v[168:169] op_sel_hi:[1,0]
	s_lshl_b32 s0, s15, 3
	s_lshr_b32 s1, s13, 5
	s_or_b32 s22, s1, s0
	s_ashr_i32 s23, s22, 31
	s_lshl_b64 s[22:23], s[22:23], 10
	s_or_b32 s2, s1, 4
	s_or_b32 s13, s0, 0x80
	s_waitcnt vmcnt(0)
	v_pk_mul_f32 v[124:125], v[172:173], v[146:147] op_sel_hi:[0,1]
	v_pk_mul_f32 v[126:127], v[172:173], v[144:145] op_sel_hi:[0,1]
	v_pk_mul_f32 v[120:121], v[172:173], v[150:151] op_sel_hi:[0,1]
	v_pk_mul_f32 v[122:123], v[172:173], v[148:149] op_sel_hi:[0,1]
	v_pk_mul_f32 v[146:147], v[124:125], v[174:175]
	v_pk_mul_f32 v[144:145], v[126:127], v[170:171]
	v_pk_mul_f32 v[148:149], v[120:121], v[168:169]
	v_pk_mul_f32 v[150:151], v[122:123], v[176:177]
	v_cvt_pk_bf16_f32 v144, v144, v145
	v_cvt_pk_bf16_f32 v145, v146, v147
	s_nop 0
	v_cvt_pk_bf16_f32 v146, v150, v151
	v_cvt_pk_bf16_f32 v147, v148, v149
	ds_read_b128 v[148:151], v137 offset:16
	s_waitcnt lgkmcnt(0)
	v_mov_b32_e32 v168, v149
	v_mov_b32_e32 v169, v150
	v_mov_b32_e32 v149, v151
	v_pk_add_f32 v[148:149], v[168:169], v[148:149]
	s_nop 0
	v_add_f32_e32 v132, v148, v149
	v_fmamk_f32 v132, v132, 0x3c000000, v163
	v_rsq_f32_e32 v132, v132
	v_lshl_add_u64 v[148:149], v[142:143], 0, s[22:23]
	global_store_dwordx4 v[148:149], v[144:147], off sc1
	s_or_b32 s22, s2, s0
	v_pk_mul_f32 v[116:117], v[116:117], v[132:133] op_sel_hi:[1,0]
	v_pk_mul_f32 v[118:119], v[118:119], v[132:133] op_sel_hi:[1,0]
	v_pk_mul_f32 v[112:113], v[112:113], v[132:133] op_sel_hi:[1,0]
	v_pk_mul_f32 v[114:115], v[114:115], v[132:133] op_sel_hi:[1,0]
	v_pk_mul_f32 v[118:119], v[124:125], v[118:119]
	v_pk_mul_f32 v[116:117], v[126:127], v[116:117]
	v_pk_mul_f32 v[144:145], v[120:121], v[114:115]
	v_pk_mul_f32 v[114:115], v[122:123], v[112:113]
	v_cvt_pk_bf16_f32 v112, v116, v117
	v_cvt_pk_bf16_f32 v113, v118, v119
	s_ashr_i32 s23, s22, 31
	v_cvt_pk_bf16_f32 v114, v114, v115
	v_cvt_pk_bf16_f32 v115, v144, v145
	ds_read_b128 v[116:119], v137 offset:512
	s_lshl_b64 s[22:23], s[22:23], 10
	s_waitcnt lgkmcnt(0)
	v_mov_b32_e32 v144, v117
	v_mov_b32_e32 v145, v118
	v_mov_b32_e32 v117, v119
	v_pk_add_f32 v[116:117], v[144:145], v[116:117]
	v_lshl_add_u64 v[118:119], v[142:143], 0, s[22:23]
	v_add_f32_e32 v116, v116, v117
	v_fmamk_f32 v116, v116, 0x3c000000, v163
	v_rsq_f32_e32 v116, v116
	global_store_dwordx4 v[118:119], v[112:115], off sc1
	s_or_b32 s22, s13, s1
	s_ashr_i32 s23, s22, 31
	v_pk_mul_f32 v[108:109], v[108:109], v[116:117] op_sel_hi:[1,0]
	v_pk_mul_f32 v[110:111], v[110:111], v[116:117] op_sel_hi:[1,0]
	v_pk_mul_f32 v[104:105], v[104:105], v[116:117] op_sel_hi:[1,0]
	v_pk_mul_f32 v[106:107], v[106:107], v[116:117] op_sel_hi:[1,0]
	v_pk_mul_f32 v[110:111], v[124:125], v[110:111]
	v_pk_mul_f32 v[108:109], v[126:127], v[108:109]
	v_pk_mul_f32 v[112:113], v[120:121], v[106:107]
	v_pk_mul_f32 v[106:107], v[122:123], v[104:105]
	v_cvt_pk_bf16_f32 v104, v108, v109
	v_cvt_pk_bf16_f32 v105, v110, v111
	s_lshl_b64 s[22:23], s[22:23], 10
	v_cvt_pk_bf16_f32 v106, v106, v107
	v_cvt_pk_bf16_f32 v107, v112, v113
	ds_read_b128 v[108:111], v137 offset:528
	s_waitcnt lgkmcnt(0)
	v_mov_b32_e32 v112, v109
	v_mov_b32_e32 v113, v110
	v_mov_b32_e32 v109, v111
	v_pk_add_f32 v[108:109], v[112:113], v[108:109]
	v_lshl_add_u64 v[110:111], v[142:143], 0, s[22:23]
	v_add_f32_e32 v108, v108, v109
	v_fmamk_f32 v108, v108, 0x3c000000, v163
	v_rsq_f32_e32 v108, v108
	global_store_dwordx4 v[110:111], v[104:107], off sc1
	s_or_b32 s22, s2, s13
	s_ashr_i32 s23, s22, 31
	v_pk_mul_f32 v[100:101], v[100:101], v[108:109] op_sel_hi:[1,0]
	v_pk_mul_f32 v[102:103], v[102:103], v[108:109] op_sel_hi:[1,0]
	v_pk_mul_f32 v[96:97], v[96:97], v[108:109] op_sel_hi:[1,0]
	v_pk_mul_f32 v[98:99], v[98:99], v[108:109] op_sel_hi:[1,0]
	v_pk_mul_f32 v[102:103], v[124:125], v[102:103]
	v_pk_mul_f32 v[100:101], v[126:127], v[100:101]
	v_pk_mul_f32 v[104:105], v[120:121], v[98:99]
	v_pk_mul_f32 v[98:99], v[122:123], v[96:97]
	v_cvt_pk_bf16_f32 v96, v100, v101
	v_cvt_pk_bf16_f32 v97, v102, v103
	s_lshl_b64 s[22:23], s[22:23], 10
	v_cvt_pk_bf16_f32 v98, v98, v99
	v_cvt_pk_bf16_f32 v99, v104, v105
	ds_read_b128 v[100:103], v137 offset:1024
	s_or_b32 s13, s0, 0x100
	s_waitcnt lgkmcnt(0)
	v_mov_b32_e32 v104, v101
	v_mov_b32_e32 v105, v102
	v_mov_b32_e32 v101, v103
	v_pk_add_f32 v[100:101], v[104:105], v[100:101]
	v_lshl_add_u64 v[102:103], v[142:143], 0, s[22:23]
	v_add_f32_e32 v100, v100, v101
	v_fmamk_f32 v100, v100, 0x3c000000, v163
	v_rsq_f32_e32 v100, v100
	global_store_dwordx4 v[102:103], v[96:99], off sc1
	s_or_b32 s22, s13, s1
	s_ashr_i32 s23, s22, 31
	v_pk_mul_f32 v[92:93], v[92:93], v[100:101] op_sel_hi:[1,0]
	v_pk_mul_f32 v[94:95], v[94:95], v[100:101] op_sel_hi:[1,0]
	v_pk_mul_f32 v[88:89], v[88:89], v[100:101] op_sel_hi:[1,0]
	v_pk_mul_f32 v[90:91], v[90:91], v[100:101] op_sel_hi:[1,0]
	v_pk_mul_f32 v[94:95], v[124:125], v[94:95]
	v_pk_mul_f32 v[92:93], v[126:127], v[92:93]
	v_pk_mul_f32 v[96:97], v[120:121], v[90:91]
	v_pk_mul_f32 v[90:91], v[122:123], v[88:89]
	v_cvt_pk_bf16_f32 v88, v92, v93
	v_cvt_pk_bf16_f32 v89, v94, v95
	s_lshl_b64 s[22:23], s[22:23], 10
	v_cvt_pk_bf16_f32 v90, v90, v91
	v_cvt_pk_bf16_f32 v91, v96, v97
	ds_read_b128 v[92:95], v137 offset:1040
	s_waitcnt lgkmcnt(0)
	v_mov_b32_e32 v96, v93
	v_mov_b32_e32 v97, v94
	v_mov_b32_e32 v93, v95
	v_pk_add_f32 v[92:93], v[96:97], v[92:93]
	v_lshl_add_u64 v[94:95], v[142:143], 0, s[22:23]
	v_add_f32_e32 v92, v92, v93
	v_fmamk_f32 v92, v92, 0x3c000000, v163
	v_rsq_f32_e32 v92, v92
	global_store_dwordx4 v[94:95], v[88:91], off sc1
	s_or_b32 s22, s2, s13
	s_ashr_i32 s23, s22, 31
	v_pk_mul_f32 v[84:85], v[84:85], v[92:93] op_sel_hi:[1,0]
	v_pk_mul_f32 v[86:87], v[86:87], v[92:93] op_sel_hi:[1,0]
	v_pk_mul_f32 v[80:81], v[80:81], v[92:93] op_sel_hi:[1,0]
	v_pk_mul_f32 v[82:83], v[82:83], v[92:93] op_sel_hi:[1,0]
	v_pk_mul_f32 v[86:87], v[124:125], v[86:87]
	v_pk_mul_f32 v[84:85], v[126:127], v[84:85]
	v_pk_mul_f32 v[88:89], v[120:121], v[82:83]
	v_pk_mul_f32 v[82:83], v[122:123], v[80:81]
	v_cvt_pk_bf16_f32 v80, v84, v85
	v_cvt_pk_bf16_f32 v81, v86, v87
	s_lshl_b64 s[22:23], s[22:23], 10
	v_cvt_pk_bf16_f32 v82, v82, v83
	v_cvt_pk_bf16_f32 v83, v88, v89
	ds_read_b128 v[84:87], v137 offset:1536
	s_or_b32 s13, s0, 0x180
	s_waitcnt lgkmcnt(0)
	v_mov_b32_e32 v88, v85
	v_mov_b32_e32 v89, v86
	v_mov_b32_e32 v85, v87
	v_pk_add_f32 v[84:85], v[88:89], v[84:85]
	v_lshl_add_u64 v[86:87], v[142:143], 0, s[22:23]
	v_add_f32_e32 v84, v84, v85
	v_fmamk_f32 v84, v84, 0x3c000000, v163
	v_rsq_f32_e32 v84, v84
	global_store_dwordx4 v[86:87], v[80:83], off sc1
	s_or_b32 s22, s13, s1
	s_ashr_i32 s23, s22, 31
	v_pk_mul_f32 v[76:77], v[76:77], v[84:85] op_sel_hi:[1,0]
	v_pk_mul_f32 v[78:79], v[78:79], v[84:85] op_sel_hi:[1,0]
	v_pk_mul_f32 v[72:73], v[72:73], v[84:85] op_sel_hi:[1,0]
	v_pk_mul_f32 v[74:75], v[74:75], v[84:85] op_sel_hi:[1,0]
	v_pk_mul_f32 v[78:79], v[124:125], v[78:79]
	v_pk_mul_f32 v[76:77], v[126:127], v[76:77]
	v_pk_mul_f32 v[80:81], v[120:121], v[74:75]
	v_pk_mul_f32 v[74:75], v[122:123], v[72:73]
	v_cvt_pk_bf16_f32 v72, v76, v77
	v_cvt_pk_bf16_f32 v73, v78, v79
	s_lshl_b64 s[22:23], s[22:23], 10
	v_cvt_pk_bf16_f32 v74, v74, v75
	v_cvt_pk_bf16_f32 v75, v80, v81
	ds_read_b128 v[76:79], v137 offset:1552
	s_waitcnt lgkmcnt(0)
	v_mov_b32_e32 v80, v77
	v_mov_b32_e32 v81, v78
	v_mov_b32_e32 v77, v79
	v_pk_add_f32 v[76:77], v[80:81], v[76:77]
	v_lshl_add_u64 v[78:79], v[142:143], 0, s[22:23]
	v_add_f32_e32 v76, v76, v77
	v_fmamk_f32 v76, v76, 0x3c000000, v163
	v_rsq_f32_e32 v76, v76
	global_store_dwordx4 v[78:79], v[72:75], off sc1
	s_or_b32 s22, s2, s13
	s_ashr_i32 s23, s22, 31
	v_pk_mul_f32 v[68:69], v[68:69], v[76:77] op_sel_hi:[1,0]
	v_pk_mul_f32 v[70:71], v[70:71], v[76:77] op_sel_hi:[1,0]
	v_pk_mul_f32 v[64:65], v[64:65], v[76:77] op_sel_hi:[1,0]
	v_pk_mul_f32 v[66:67], v[66:67], v[76:77] op_sel_hi:[1,0]
	v_pk_mul_f32 v[70:71], v[124:125], v[70:71]
	v_pk_mul_f32 v[68:69], v[126:127], v[68:69]
	v_pk_mul_f32 v[72:73], v[120:121], v[66:67]
	v_pk_mul_f32 v[66:67], v[122:123], v[64:65]
	v_cvt_pk_bf16_f32 v64, v68, v69
	v_cvt_pk_bf16_f32 v65, v70, v71
	s_lshl_b64 s[22:23], s[22:23], 10
	v_cvt_pk_bf16_f32 v66, v66, v67
	v_cvt_pk_bf16_f32 v67, v72, v73
	ds_read_b128 v[68:71], v137 offset:4096
	s_add_i32 s13, s0, 0x400
	s_waitcnt lgkmcnt(0)
	v_mov_b32_e32 v72, v69
	v_mov_b32_e32 v73, v70
	v_mov_b32_e32 v69, v71
	v_pk_add_f32 v[68:69], v[72:73], v[68:69]
	v_lshl_add_u64 v[70:71], v[142:143], 0, s[22:23]
	v_add_f32_e32 v68, v68, v69
	v_fmamk_f32 v68, v68, 0x3c000000, v163
	v_rsq_f32_e32 v68, v68
	global_store_dwordx4 v[70:71], v[64:67], off sc1
	s_or_b32 s22, s13, s1
	s_ashr_i32 s23, s22, 31
	v_pk_mul_f32 v[60:61], v[60:61], v[68:69] op_sel_hi:[1,0]
	v_pk_mul_f32 v[62:63], v[62:63], v[68:69] op_sel_hi:[1,0]
	v_pk_mul_f32 v[56:57], v[56:57], v[68:69] op_sel_hi:[1,0]
	v_pk_mul_f32 v[58:59], v[58:59], v[68:69] op_sel_hi:[1,0]
	v_pk_mul_f32 v[62:63], v[124:125], v[62:63]
	v_pk_mul_f32 v[60:61], v[126:127], v[60:61]
	v_pk_mul_f32 v[64:65], v[120:121], v[58:59]
	v_pk_mul_f32 v[58:59], v[122:123], v[56:57]
	v_cvt_pk_bf16_f32 v56, v60, v61
	v_cvt_pk_bf16_f32 v57, v62, v63
	s_lshl_b64 s[22:23], s[22:23], 10
	v_cvt_pk_bf16_f32 v58, v58, v59
	v_cvt_pk_bf16_f32 v59, v64, v65
	ds_read_b128 v[60:63], v137 offset:4112
	s_waitcnt lgkmcnt(0)
	v_mov_b32_e32 v64, v61
	v_mov_b32_e32 v65, v62
	v_mov_b32_e32 v61, v63
	v_pk_add_f32 v[60:61], v[64:65], v[60:61]
	v_lshl_add_u64 v[62:63], v[142:143], 0, s[22:23]
	v_add_f32_e32 v60, v60, v61
	v_fmamk_f32 v60, v60, 0x3c000000, v163
	v_rsq_f32_e32 v60, v60
	global_store_dwordx4 v[62:63], v[56:59], off sc1
	s_or_b32 s22, s2, s13
	s_ashr_i32 s23, s22, 31
	v_pk_mul_f32 v[52:53], v[52:53], v[60:61] op_sel_hi:[1,0]
	v_pk_mul_f32 v[54:55], v[54:55], v[60:61] op_sel_hi:[1,0]
	v_pk_mul_f32 v[48:49], v[48:49], v[60:61] op_sel_hi:[1,0]
	v_pk_mul_f32 v[50:51], v[50:51], v[60:61] op_sel_hi:[1,0]
	v_pk_mul_f32 v[54:55], v[124:125], v[54:55]
	v_pk_mul_f32 v[52:53], v[126:127], v[52:53]
	v_pk_mul_f32 v[56:57], v[120:121], v[50:51]
	v_pk_mul_f32 v[50:51], v[122:123], v[48:49]
	v_cvt_pk_bf16_f32 v48, v52, v53
	v_cvt_pk_bf16_f32 v49, v54, v55
	s_lshl_b64 s[22:23], s[22:23], 10
	v_cvt_pk_bf16_f32 v50, v50, v51
	v_cvt_pk_bf16_f32 v51, v56, v57
	ds_read_b128 v[52:55], v137 offset:4608
	s_add_i32 s13, s0, 0x480
	s_waitcnt lgkmcnt(0)
	v_mov_b32_e32 v56, v53
	v_mov_b32_e32 v57, v54
	v_mov_b32_e32 v53, v55
	v_pk_add_f32 v[52:53], v[56:57], v[52:53]
	v_lshl_add_u64 v[54:55], v[142:143], 0, s[22:23]
	v_add_f32_e32 v52, v52, v53
	v_fmamk_f32 v52, v52, 0x3c000000, v163
	v_rsq_f32_e32 v52, v52
	global_store_dwordx4 v[54:55], v[48:51], off sc1
	s_or_b32 s22, s13, s1
	s_ashr_i32 s23, s22, 31
	v_pk_mul_f32 v[44:45], v[44:45], v[52:53] op_sel_hi:[1,0]
	v_pk_mul_f32 v[46:47], v[46:47], v[52:53] op_sel_hi:[1,0]
	v_pk_mul_f32 v[40:41], v[40:41], v[52:53] op_sel_hi:[1,0]
	v_pk_mul_f32 v[42:43], v[42:43], v[52:53] op_sel_hi:[1,0]
	v_pk_mul_f32 v[46:47], v[124:125], v[46:47]
	v_pk_mul_f32 v[44:45], v[126:127], v[44:45]
	v_pk_mul_f32 v[48:49], v[120:121], v[42:43]
	v_pk_mul_f32 v[42:43], v[122:123], v[40:41]
	v_cvt_pk_bf16_f32 v40, v44, v45
	v_cvt_pk_bf16_f32 v41, v46, v47
	s_lshl_b64 s[22:23], s[22:23], 10
	v_cvt_pk_bf16_f32 v42, v42, v43
	v_cvt_pk_bf16_f32 v43, v48, v49
	ds_read_b128 v[44:47], v137 offset:4624
	s_waitcnt lgkmcnt(0)
	v_mov_b32_e32 v48, v45
	v_mov_b32_e32 v49, v46
	v_mov_b32_e32 v45, v47
	v_pk_add_f32 v[44:45], v[48:49], v[44:45]
	v_lshl_add_u64 v[46:47], v[142:143], 0, s[22:23]
	v_add_f32_e32 v44, v44, v45
	v_fmamk_f32 v44, v44, 0x3c000000, v163
	v_rsq_f32_e32 v44, v44
	global_store_dwordx4 v[46:47], v[40:43], off sc1
	s_or_b32 s22, s2, s13
	s_ashr_i32 s23, s22, 31
	v_pk_mul_f32 v[36:37], v[36:37], v[44:45] op_sel_hi:[1,0]
	v_pk_mul_f32 v[38:39], v[38:39], v[44:45] op_sel_hi:[1,0]
	v_pk_mul_f32 v[32:33], v[32:33], v[44:45] op_sel_hi:[1,0]
	v_pk_mul_f32 v[34:35], v[34:35], v[44:45] op_sel_hi:[1,0]
	v_pk_mul_f32 v[38:39], v[124:125], v[38:39]
	v_pk_mul_f32 v[36:37], v[126:127], v[36:37]
	v_pk_mul_f32 v[40:41], v[120:121], v[34:35]
	v_pk_mul_f32 v[34:35], v[122:123], v[32:33]
	v_cvt_pk_bf16_f32 v32, v36, v37
	v_cvt_pk_bf16_f32 v33, v38, v39
	s_lshl_b64 s[22:23], s[22:23], 10
	v_cvt_pk_bf16_f32 v34, v34, v35
	v_cvt_pk_bf16_f32 v35, v40, v41
	ds_read_b128 v[36:39], v137 offset:5120
	s_add_i32 s13, s0, 0x500
	s_waitcnt lgkmcnt(0)
	v_mov_b32_e32 v40, v37
	v_mov_b32_e32 v41, v38
	v_mov_b32_e32 v37, v39
	v_pk_add_f32 v[36:37], v[40:41], v[36:37]
	v_lshl_add_u64 v[38:39], v[142:143], 0, s[22:23]
	v_add_f32_e32 v36, v36, v37
	v_fmamk_f32 v36, v36, 0x3c000000, v163
	v_rsq_f32_e32 v36, v36
	global_store_dwordx4 v[38:39], v[32:35], off sc1
	s_or_b32 s22, s13, s1
	s_ashr_i32 s23, s22, 31
	v_pk_mul_f32 v[28:29], v[28:29], v[36:37] op_sel_hi:[1,0]
	v_pk_mul_f32 v[30:31], v[30:31], v[36:37] op_sel_hi:[1,0]
	v_pk_mul_f32 v[24:25], v[24:25], v[36:37] op_sel_hi:[1,0]
	v_pk_mul_f32 v[26:27], v[26:27], v[36:37] op_sel_hi:[1,0]
	v_pk_mul_f32 v[30:31], v[124:125], v[30:31]
	v_pk_mul_f32 v[28:29], v[126:127], v[28:29]
	v_pk_mul_f32 v[32:33], v[120:121], v[26:27]
	v_pk_mul_f32 v[26:27], v[122:123], v[24:25]
	v_cvt_pk_bf16_f32 v24, v28, v29
	v_cvt_pk_bf16_f32 v25, v30, v31
	s_lshl_b64 s[22:23], s[22:23], 10
	v_cvt_pk_bf16_f32 v26, v26, v27
	v_cvt_pk_bf16_f32 v27, v32, v33
	ds_read_b128 v[28:31], v137 offset:5136
	s_waitcnt lgkmcnt(0)
	v_mov_b32_e32 v32, v29
	v_mov_b32_e32 v33, v30
	v_mov_b32_e32 v29, v31
	v_pk_add_f32 v[28:29], v[32:33], v[28:29]
	v_lshl_add_u64 v[30:31], v[142:143], 0, s[22:23]
	v_add_f32_e32 v28, v28, v29
	v_fmamk_f32 v28, v28, 0x3c000000, v163
	v_rsq_f32_e32 v28, v28
	global_store_dwordx4 v[30:31], v[24:27], off sc1
	s_or_b32 s22, s2, s13
	s_ashr_i32 s23, s22, 31
	v_pk_mul_f32 v[20:21], v[20:21], v[28:29] op_sel_hi:[1,0]
	v_pk_mul_f32 v[22:23], v[22:23], v[28:29] op_sel_hi:[1,0]
	v_pk_mul_f32 v[16:17], v[16:17], v[28:29] op_sel_hi:[1,0]
	v_pk_mul_f32 v[18:19], v[18:19], v[28:29] op_sel_hi:[1,0]
	v_pk_mul_f32 v[22:23], v[124:125], v[22:23]
	v_pk_mul_f32 v[20:21], v[126:127], v[20:21]
	v_pk_mul_f32 v[24:25], v[120:121], v[18:19]
	v_pk_mul_f32 v[18:19], v[122:123], v[16:17]
	v_cvt_pk_bf16_f32 v16, v20, v21
	v_cvt_pk_bf16_f32 v17, v22, v23
	s_lshl_b64 s[22:23], s[22:23], 10
	v_cvt_pk_bf16_f32 v18, v18, v19
	v_cvt_pk_bf16_f32 v19, v24, v25
	ds_read_b128 v[20:23], v137 offset:5632
	v_lshl_add_u64 v[24:25], v[142:143], 0, s[22:23]
	global_store_dwordx4 v[24:25], v[16:19], off sc1
	s_add_i32 s13, s0, 0x580
	s_or_b32 s0, s13, s1
	s_waitcnt lgkmcnt(0)
	v_mov_b32_e32 v26, v21
	v_mov_b32_e32 v27, v22
	v_mov_b32_e32 v21, v23
	v_pk_add_f32 v[20:21], v[26:27], v[20:21]
	s_ashr_i32 s1, s0, 31
	v_add_f32_e32 v20, v20, v21
	v_fmamk_f32 v20, v20, 0x3c000000, v163
	v_rsq_f32_e32 v20, v20
	s_lshl_b64 s[0:1], s[0:1], 10
	v_pk_mul_f32 v[12:13], v[12:13], v[20:21] op_sel_hi:[1,0]
	v_pk_mul_f32 v[14:15], v[14:15], v[20:21] op_sel_hi:[1,0]
	v_pk_mul_f32 v[8:9], v[8:9], v[20:21] op_sel_hi:[1,0]
	v_pk_mul_f32 v[10:11], v[10:11], v[20:21] op_sel_hi:[1,0]
	v_pk_mul_f32 v[14:15], v[124:125], v[14:15]
	v_pk_mul_f32 v[12:13], v[126:127], v[12:13]
	v_pk_mul_f32 v[16:17], v[120:121], v[10:11]
	v_pk_mul_f32 v[10:11], v[122:123], v[8:9]
	v_cvt_pk_bf16_f32 v8, v12, v13
	v_cvt_pk_bf16_f32 v9, v14, v15
	s_nop 0
	v_cvt_pk_bf16_f32 v10, v10, v11
	v_cvt_pk_bf16_f32 v11, v16, v17
	ds_read_b128 v[12:15], v137 offset:5648
	v_lshl_add_u64 v[16:17], v[142:143], 0, s[0:1]
	global_store_dwordx4 v[16:17], v[8:11], off sc1
	s_or_b32 s0, s2, s13
	s_ashr_i32 s1, s0, 31
	s_waitcnt lgkmcnt(0)
	v_mov_b32_e32 v8, v13
	v_mov_b32_e32 v9, v14
	v_mov_b32_e32 v13, v15
	v_pk_add_f32 v[8:9], v[8:9], v[12:13]
	s_lshl_b64 s[0:1], s[0:1], 10
	v_add_f32_e32 v8, v8, v9
	v_fmamk_f32 v8, v8, 0x3c000000, v163
	v_rsq_f32_e32 v8, v8
	v_lshl_add_u64 v[10:11], v[142:143], 0, s[0:1]
	v_pk_mul_f32 v[0:1], v[0:1], v[8:9] op_sel_hi:[1,0]
	v_pk_mul_f32 v[2:3], v[2:3], v[8:9] op_sel_hi:[1,0]
	v_pk_mul_f32 v[4:5], v[4:5], v[8:9] op_sel_hi:[1,0]
	v_pk_mul_f32 v[6:7], v[6:7], v[8:9] op_sel_hi:[1,0]
	v_pk_mul_f32 v[8:9], v[120:121], v[2:3]
	v_pk_mul_f32 v[2:3], v[122:123], v[0:1]
	v_pk_mul_f32 v[6:7], v[124:125], v[6:7]
	v_pk_mul_f32 v[4:5], v[126:127], v[4:5]
	s_nop 0
	v_cvt_pk_bf16_f32 v0, v4, v5
	v_cvt_pk_bf16_f32 v1, v6, v7
	v_cvt_pk_bf16_f32 v2, v2, v3
	v_cvt_pk_bf16_f32 v3, v8, v9
	global_store_dwordx4 v[10:11], v[0:3], off sc1
	s_andn2_b64 vcc, exec, s[4:5]
	s_mov_b64 s[0:1], -1
	s_cbranch_vccnz .LBB0_86

.LBB0_376:
	s_lshl_b32 s2, s12, 8
	s_or_b32 s13, s2, s43
	s_lshl_b32 s2, s26, 8
	s_add_i32 s19, s2, s42
	v_or_b32_e32 v128, s13, v161
	v_or_b32_e32 v156, s19, v160
	v_ashrrev_i32_e32 v129, 31, v128
	v_ashrrev_i32_e32 v157, 31, v156
	v_lshl_add_u64 v[154:155], v[128:129], 2, s[44:45]
	v_lshlrev_b64 v[128:129], 14, v[156:157]
	v_lshl_add_u64 v[128:129], v[154:155], 0, v[128:129]
	global_load_dwordx4 v[170:173], v[128:129], off offset:16 nt
	global_load_dwordx4 v[174:177], v[128:129], off nt
	global_load_dwordx4 v[178:181], v[128:129], off offset:528 nt
	global_load_dwordx4 v[182:185], v[128:129], off offset:512 nt
	v_or_b32_e32 v158, 16, v156
	v_ashrrev_i32_e32 v159, 31, v158
	v_lshlrev_b64 v[128:129], 14, v[158:159]
	v_lshl_add_u64 v[132:133], v[154:155], 0, v[128:129]
	global_load_dwordx4 v[136:139], v[132:133], off offset:16 nt
	global_load_dwordx4 v[140:143], v[132:133], off nt
	global_load_dwordx4 v[128:131], v[132:133], off offset:528 nt
	s_nop 0
	global_load_dwordx4 v[132:135], v[132:133], off offset:512 nt
	s_ashr_i32 s19, s19, 2
	s_and_b32 s21, s19, 0xffffffc0
	v_lshlrev_b32_e32 v157, 5, v156
	s_movk_i32 s19, 0x1e0
	v_and_or_b32 v148, v157, s19, v161
	s_ashr_i32 s19, s13, 6
	v_lshlrev_b32_e32 v159, 1, v156
	s_add_i32 s26, s21, s19
	v_and_b32_e32 v159, 16, v159
	s_ashr_i32 s27, s26, 31
	v_bitop3_b32 v148, v148, s54, v159 bitop3:0xde
	s_lshl_b64 s[26:27], s[26:27], 15
	v_readlane_b32 s30, v250, 27
	v_or_b32_e32 v169, s53, v148
	v_readlane_b32 s31, v250, 28
	s_add_u32 s26, s30, s26
	s_addc_u32 s27, s31, s27
	v_lshlrev_b32_e32 v169, 1, v169
	s_or_b32 s13, s19, 2
	s_add_i32 s28, s21, s13
	s_ashr_i32 s29, s28, 31
	s_lshl_b64 s[28:29], s[28:29], 15
	s_add_u32 s28, s30, s28
	s_addc_u32 s29, s31, s29
	s_waitcnt vmcnt(0)
	v_pk_add_f32 v[172:173], v[122:123], v[172:173]
	v_pk_add_f32 v[126:127], v[126:127], v[176:177]
	v_pk_add_f32 v[124:125], v[124:125], v[174:175]
	v_pk_add_f32 v[122:123], v[120:121], v[170:171]
	v_mul_f32_e32 v120, v125, v125
	v_mul_f32_e32 v121, v127, v127
	v_fmac_f32_e32 v120, v124, v124
	v_fmac_f32_e32 v121, v126, v126
	v_add_f32_e32 v120, v120, v121
	v_mul_f32_e32 v121, v123, v123
	v_mul_f32_e32 v170, v173, v173
	v_fmac_f32_e32 v121, v122, v122
	v_fmac_f32_e32 v170, v172, v172
	v_add_f32_e32 v121, v121, v170
	v_add_f32_e32 v170, v120, v121
	v_cvt_pk_bf16_f32 v120, v124, v125
	v_cvt_pk_bf16_f32 v121, v126, v127
	v_pk_add_f32 v[118:119], v[118:119], v[184:185]
	v_pk_add_f32 v[116:117], v[116:117], v[182:183]
	v_cvt_pk_bf16_f32 v122, v122, v123
	v_cvt_pk_bf16_f32 v123, v172, v173
	global_store_dwordx4 v169, v[120:123], s[26:27] sc1
	s_nop 1
	v_pk_add_f32 v[120:121], v[114:115], v[180:181]
	v_pk_add_f32 v[114:115], v[112:113], v[178:179]
	v_mul_f32_e32 v112, v117, v117
	v_mul_f32_e32 v113, v119, v119
	v_fmac_f32_e32 v112, v116, v116
	v_fmac_f32_e32 v113, v118, v118
	v_add_f32_e32 v112, v112, v113
	v_mul_f32_e32 v113, v115, v115
	v_mul_f32_e32 v122, v121, v121
	v_fmac_f32_e32 v113, v114, v114
	v_fmac_f32_e32 v122, v120, v120
	v_add_f32_e32 v113, v113, v122
	v_add_f32_e32 v112, v112, v113
	v_add_f32_e32 v122, v170, v112
	v_cvt_pk_bf16_f32 v112, v116, v117
	v_cvt_pk_bf16_f32 v113, v118, v119
	v_cvt_pk_bf16_f32 v114, v114, v115
	v_cvt_pk_bf16_f32 v115, v120, v121
	global_store_dwordx4 v169, v[112:115], s[28:29] sc1
	s_nop 1
	v_and_b32_e32 v113, 64, v167
	v_xor_b32_e32 v112, 16, v167
	v_add_u32_e32 v113, 64, v113
	v_cmp_lt_i32_e32 vcc, v112, v113
	v_xor_b32_e32 v115, 32, v167
	s_nop 0
	v_cndmask_b32_e32 v112, v167, v112, vcc
	v_lshlrev_b32_e32 v114, 2, v112
	ds_bpermute_b32 v112, v114, v122
	v_cmp_lt_i32_e32 vcc, v115, v113
	s_waitcnt lgkmcnt(0)
	v_add_f32_e32 v112, v122, v112
	v_cndmask_b32_e32 v113, v167, v115, vcc
	v_lshlrev_b32_e32 v115, 2, v113
	ds_bpermute_b32 v113, v115, v112
	s_and_saveexec_b64 s[30:31], s[4:5]
	s_cbranch_execz .LBB0_378
	s_waitcnt lgkmcnt(0)
	v_add_f32_e32 v112, v112, v113
	ds_write_b32 v163, v112
.LBB0_378:
	s_or_b64 exec, exec, s[30:31]
	v_lshrrev_b32_e32 v112, 3, v158
	s_waitcnt lgkmcnt(0)
	v_lshlrev_b32_e32 v113, 5, v158
	v_lshlrev_b32_e32 v116, 1, v158
	v_and_or_b32 v112, v112, 10, s52
	v_and_b32_e32 v113, 0x1e0, v113
	v_and_b32_e32 v116, 16, v116
	v_lshlrev_b32_e32 v112, 9, v112
	v_bitop3_b32 v113, v113, v116, v161 bitop3:0x36
	v_pk_add_f32 v[110:111], v[110:111], v[142:143]
	v_pk_add_f32 v[108:109], v[108:109], v[140:141]
	v_or3_b32 v116, v113, v112, s53
	v_pk_add_f32 v[112:113], v[106:107], v[138:139]
	v_pk_add_f32 v[106:107], v[104:105], v[136:137]
	v_mul_f32_e32 v104, v109, v109
	v_mul_f32_e32 v105, v111, v111
	v_fmac_f32_e32 v104, v108, v108
	v_fmac_f32_e32 v105, v110, v110
	v_add_f32_e32 v104, v104, v105
	v_mul_f32_e32 v105, v107, v107
	v_mul_f32_e32 v117, v113, v113
	v_fmac_f32_e32 v105, v106, v106
	v_fmac_f32_e32 v117, v112, v112
	v_add_f32_e32 v105, v105, v117
	v_pk_add_f32 v[102:103], v[102:103], v[134:135]
	v_pk_add_f32 v[100:101], v[100:101], v[132:133]
	v_add_f32_e32 v117, v104, v105
	v_cvt_pk_bf16_f32 v104, v108, v109
	v_cvt_pk_bf16_f32 v105, v110, v111
	v_pk_add_f32 v[110:111], v[96:97], v[128:129]
	v_mul_f32_e32 v96, v101, v101
	v_mul_f32_e32 v97, v103, v103
	v_pk_add_f32 v[108:109], v[98:99], v[130:131]
	v_fmac_f32_e32 v96, v100, v100
	v_fmac_f32_e32 v97, v102, v102
	v_add_f32_e32 v96, v96, v97
	v_mul_f32_e32 v97, v111, v111
	v_mul_f32_e32 v98, v109, v109
	v_fmac_f32_e32 v97, v110, v110
	v_fmac_f32_e32 v98, v108, v108
	v_add_f32_e32 v97, v97, v98
	v_add_f32_e32 v96, v96, v97
	v_add_f32_e32 v96, v117, v96
	ds_bpermute_b32 v97, v114, v96
	v_lshlrev_b32_e32 v116, 1, v116
	v_cvt_pk_bf16_f32 v106, v106, v107
	v_cvt_pk_bf16_f32 v107, v112, v113
	global_store_dwordx4 v116, v[104:107], s[26:27] sc1
	s_waitcnt lgkmcnt(0)
	v_add_f32_e32 v96, v96, v97
	ds_bpermute_b32 v97, v115, v96
	v_cvt_pk_bf16_f32 v98, v100, v101
	v_cvt_pk_bf16_f32 v99, v102, v103
	v_cvt_pk_bf16_f32 v100, v110, v111
	v_cvt_pk_bf16_f32 v101, v108, v109
	global_store_dwordx4 v116, v[98:101], s[28:29] sc1
	s_and_saveexec_b64 s[30:31], s[4:5]
	s_cbranch_execz .LBB0_380
	s_waitcnt lgkmcnt(0)
	v_add_f32_e32 v96, v96, v97
	ds_write_b32 v163, v96 offset:256
.LBB0_380:
	s_or_b64 exec, exec, s[30:31]
	v_or_b32_e32 v132, 32, v156
	v_ashrrev_i32_e32 v133, 31, v132
	s_waitcnt lgkmcnt(0)
	v_lshlrev_b64 v[96:97], 14, v[132:133]
	v_lshl_add_u64 v[96:97], v[154:155], 0, v[96:97]
	global_load_dwordx4 v[116:119], v[96:97], off nt
	global_load_dwordx4 v[120:123], v[96:97], off offset:16 nt
	global_load_dwordx4 v[124:127], v[96:97], off offset:512 nt
	global_load_dwordx4 v[128:131], v[96:97], off offset:528 nt
	v_or_b32_e32 v112, 48, v156
	v_ashrrev_i32_e32 v113, 31, v112
	v_lshlrev_b64 v[96:97], 14, v[112:113]
	v_lshl_add_u64 v[100:101], v[154:155], 0, v[96:97]
	global_load_dwordx4 v[104:107], v[100:101], off offset:16 nt
	global_load_dwordx4 v[108:111], v[100:101], off nt
	global_load_dwordx4 v[96:99], v[100:101], off offset:528 nt
	s_nop 0
	global_load_dwordx4 v[100:103], v[100:101], off offset:512 nt
	v_lshrrev_b32_e32 v132, 3, v132
	v_and_b32_e32 v113, 0x1e0, v157
	v_and_or_b32 v132, v132, 12, s52
	v_bitop3_b32 v113, v113, v159, v161 bitop3:0x36
	v_lshlrev_b32_e32 v132, 9, v132
	v_or3_b32 v113, v113, v132, s53
	v_lshlrev_b32_e32 v113, 1, v113
	s_waitcnt vmcnt(7)
	v_pk_add_f32 v[94:95], v[94:95], v[118:119]
	v_pk_add_f32 v[92:93], v[92:93], v[116:117]
	s_waitcnt vmcnt(6)
	v_pk_add_f32 v[90:91], v[90:91], v[122:123]
	v_pk_add_f32 v[88:89], v[88:89], v[120:121]
	s_waitcnt vmcnt(5)
	v_pk_add_f32 v[86:87], v[86:87], v[126:127]
	v_pk_add_f32 v[84:85], v[84:85], v[124:125]
	s_waitcnt vmcnt(4)
	v_pk_add_f32 v[116:117], v[82:83], v[130:131]
	v_pk_add_f32 v[118:119], v[80:81], v[128:129]
	v_mul_f32_e32 v82, v93, v93
	v_mul_f32_e32 v83, v95, v95
	v_mul_f32_e32 v120, v89, v89
	v_mul_f32_e32 v121, v91, v91
	v_cvt_pk_bf16_f32 v80, v92, v93
	v_cvt_pk_bf16_f32 v81, v94, v95
	v_mul_f32_e32 v93, v85, v85
	v_mul_f32_e32 v95, v87, v87
	v_mul_f32_e32 v122, v119, v119
	v_mul_f32_e32 v123, v117, v117
	v_fmac_f32_e32 v82, v92, v92
	v_fmac_f32_e32 v83, v94, v94
	v_fmac_f32_e32 v120, v88, v88
	v_fmac_f32_e32 v121, v90, v90
	v_fmac_f32_e32 v93, v84, v84
	v_fmac_f32_e32 v95, v86, v86
	v_fmac_f32_e32 v122, v118, v118
	v_fmac_f32_e32 v123, v116, v116
	v_add_f32_e32 v82, v82, v83
	v_add_f32_e32 v83, v120, v121
	v_add_f32_e32 v92, v93, v95
	v_add_f32_e32 v93, v122, v123
	v_add_f32_e32 v82, v82, v83
	v_add_f32_e32 v83, v92, v93
	v_add_f32_e32 v92, v82, v83
	ds_bpermute_b32 v93, v114, v92
	v_cvt_pk_bf16_f32 v82, v88, v89
	v_cvt_pk_bf16_f32 v83, v90, v91
	global_store_dwordx4 v113, v[80:83], s[26:27] sc1
	s_waitcnt lgkmcnt(0)
	s_nop 0
	v_add_f32_e32 v80, v92, v93
	ds_bpermute_b32 v81, v115, v80
	v_cvt_pk_bf16_f32 v82, v84, v85
	v_cvt_pk_bf16_f32 v83, v86, v87
	v_cvt_pk_bf16_f32 v84, v118, v119
	v_cvt_pk_bf16_f32 v85, v116, v117
	global_store_dwordx4 v113, v[82:85], s[28:29] sc1
	s_and_saveexec_b64 s[30:31], s[4:5]
	s_cbranch_execz .LBB0_382
	s_waitcnt lgkmcnt(0)
	v_add_f32_e32 v80, v80, v81
	ds_write_b32 v163, v80 offset:512
.LBB0_382:
	s_or_b64 exec, exec, s[30:31]
	v_lshrrev_b32_e32 v80, 3, v112
	s_waitcnt lgkmcnt(0)
	v_lshlrev_b32_e32 v81, 5, v112
	v_lshlrev_b32_e32 v82, 1, v112
	v_and_or_b32 v80, v80, 14, s52
	v_and_b32_e32 v81, 0x1e0, v81
	v_and_b32_e32 v82, 16, v82
	v_lshlrev_b32_e32 v80, 9, v80
	v_bitop3_b32 v81, v81, v82, v161 bitop3:0x36
	s_waitcnt vmcnt(4)
	v_pk_add_f32 v[78:79], v[78:79], v[110:111]
	v_pk_add_f32 v[76:77], v[76:77], v[108:109]
	v_or3_b32 v82, v81, v80, s53
	v_pk_add_f32 v[80:81], v[74:75], v[106:107]
	v_pk_add_f32 v[74:75], v[72:73], v[104:105]
	v_mul_f32_e32 v72, v77, v77
	v_mul_f32_e32 v73, v79, v79
	v_fmac_f32_e32 v72, v76, v76
	v_fmac_f32_e32 v73, v78, v78
	v_add_f32_e32 v72, v72, v73
	v_mul_f32_e32 v73, v75, v75
	v_mul_f32_e32 v83, v81, v81
	v_fmac_f32_e32 v73, v74, v74
	v_fmac_f32_e32 v83, v80, v80
	v_add_f32_e32 v73, v73, v83
	s_waitcnt vmcnt(2)
	v_pk_add_f32 v[70:71], v[70:71], v[102:103]
	v_pk_add_f32 v[68:69], v[68:69], v[100:101]
	v_add_f32_e32 v83, v72, v73
	v_cvt_pk_bf16_f32 v72, v76, v77
	v_cvt_pk_bf16_f32 v73, v78, v79
	v_pk_add_f32 v[78:79], v[64:65], v[96:97]
	v_mul_f32_e32 v64, v69, v69
	v_mul_f32_e32 v65, v71, v71
	v_pk_add_f32 v[76:77], v[66:67], v[98:99]
	v_fmac_f32_e32 v64, v68, v68
	v_fmac_f32_e32 v65, v70, v70
	v_add_f32_e32 v64, v64, v65
	v_mul_f32_e32 v65, v79, v79
	v_mul_f32_e32 v66, v77, v77
	v_fmac_f32_e32 v65, v78, v78
	v_fmac_f32_e32 v66, v76, v76
	v_add_f32_e32 v65, v65, v66
	v_add_f32_e32 v64, v64, v65
	v_add_f32_e32 v64, v83, v64
	ds_bpermute_b32 v65, v114, v64
	v_lshlrev_b32_e32 v82, 1, v82
	v_cvt_pk_bf16_f32 v74, v74, v75
	v_cvt_pk_bf16_f32 v75, v80, v81
	global_store_dwordx4 v82, v[72:75], s[26:27] sc1
	s_waitcnt lgkmcnt(0)
	v_add_f32_e32 v64, v64, v65
	ds_bpermute_b32 v65, v115, v64
	v_cvt_pk_bf16_f32 v66, v68, v69
	v_cvt_pk_bf16_f32 v67, v70, v71
	v_cvt_pk_bf16_f32 v68, v78, v79
	v_cvt_pk_bf16_f32 v69, v76, v77
	global_store_dwordx4 v82, v[66:69], s[28:29] sc1
	s_and_saveexec_b64 s[26:27], s[4:5]
	s_cbranch_execz .LBB0_384
	s_waitcnt lgkmcnt(0)
	v_add_f32_e32 v64, v64, v65
	ds_write_b32 v163, v64 offset:768
.LBB0_384:
	s_or_b64 exec, exec, s[26:27]
	v_add_u32_e32 v98, 0x80, v156
	v_ashrrev_i32_e32 v99, 31, v98
	s_waitcnt lgkmcnt(0)
	v_lshlrev_b64 v[64:65], 14, v[98:99]
	v_lshl_add_u64 v[64:65], v[154:155], 0, v[64:65]
	global_load_dwordx4 v[82:85], v[64:65], off nt
	global_load_dwordx4 v[86:89], v[64:65], off offset:16 nt
	global_load_dwordx4 v[90:93], v[64:65], off offset:512 nt
	global_load_dwordx4 v[94:97], v[64:65], off offset:528 nt
	v_add_u32_e32 v80, 0x90, v156
	v_ashrrev_i32_e32 v81, 31, v80
	v_lshlrev_b64 v[64:65], 14, v[80:81]
	v_lshl_add_u64 v[68:69], v[154:155], 0, v[64:65]
	global_load_dwordx4 v[72:75], v[68:69], off offset:16 nt
	global_load_dwordx4 v[76:79], v[68:69], off nt
	global_load_dwordx4 v[64:67], v[68:69], off offset:528 nt
	s_nop 0
	global_load_dwordx4 v[68:71], v[68:69], off offset:512 nt
	v_ashrrev_i32_e32 v81, 2, v98
	s_movk_i32 s21, 0x2000
	v_lshlrev_b32_e32 v98, 6, v98
	v_and_b32_e32 v81, 0xffffffc0, v81
	v_and_or_b32 v99, v98, s21, v148
	v_add_u32_e32 v98, s19, v81
	v_lshlrev_b32_e32 v148, 1, v99
	v_ashrrev_i32_e32 v99, 31, v98
	v_readlane_b32 s26, v250, 27
	v_lshlrev_b64 v[98:99], 15, v[98:99]
	v_readlane_b32 s27, v250, 28
	v_add_u32_e32 v100, s13, v81
	v_ashrrev_i32_e32 v101, 31, v100
	v_lshl_add_u64 v[98:99], s[26:27], 0, v[98:99]
	v_lshl_add_u64 v[98:99], v[98:99], 0, v[148:149]
	s_waitcnt vmcnt(7)
	v_pk_add_f32 v[62:63], v[62:63], v[84:85]
	v_pk_add_f32 v[60:61], v[60:61], v[82:83]
	s_waitcnt vmcnt(6)
	v_pk_add_f32 v[58:59], v[58:59], v[88:89]
	v_pk_add_f32 v[56:57], v[56:57], v[86:87]
	s_waitcnt vmcnt(5)
	v_pk_add_f32 v[54:55], v[54:55], v[92:93]
	v_pk_add_f32 v[52:53], v[52:53], v[90:91]
	s_waitcnt vmcnt(4)
	v_pk_add_f32 v[82:83], v[50:51], v[96:97]
	v_pk_add_f32 v[84:85], v[48:49], v[94:95]
	v_mul_f32_e32 v81, v61, v61
	v_mul_f32_e32 v86, v63, v63
	v_mul_f32_e32 v87, v57, v57
	v_mul_f32_e32 v88, v59, v59
	v_cvt_pk_bf16_f32 v48, v60, v61
	v_cvt_pk_bf16_f32 v49, v62, v63
	v_cvt_pk_bf16_f32 v50, v56, v57
	v_cvt_pk_bf16_f32 v51, v58, v59
	v_mul_f32_e32 v57, v53, v53
	v_mul_f32_e32 v59, v55, v55
	v_mul_f32_e32 v61, v85, v85
	v_mul_f32_e32 v63, v83, v83
	v_fmac_f32_e32 v81, v60, v60
	v_fmac_f32_e32 v86, v62, v62
	v_fmac_f32_e32 v87, v56, v56
	v_fmac_f32_e32 v88, v58, v58
	v_fmac_f32_e32 v57, v52, v52
	v_fmac_f32_e32 v59, v54, v54
	v_fmac_f32_e32 v61, v84, v84
	v_fmac_f32_e32 v63, v82, v82
	global_store_dwordx4 v[98:99], v[48:51], off sc1
	s_nop 1
	v_add_f32_e32 v48, v81, v86
	v_add_f32_e32 v49, v87, v88
	v_add_f32_e32 v50, v57, v59
	v_add_f32_e32 v51, v61, v63
	v_add_f32_e32 v48, v48, v49
	v_add_f32_e32 v49, v50, v51
	v_add_f32_e32 v51, v48, v49
	ds_bpermute_b32 v58, v114, v51
	v_lshlrev_b64 v[48:49], 15, v[100:101]
	v_lshl_add_u64 v[48:49], s[26:27], 0, v[48:49]
	v_lshl_add_u64 v[56:57], v[48:49], 0, v[148:149]
	v_cvt_pk_bf16_f32 v50, v52, v53
	s_waitcnt lgkmcnt(0)
	v_add_f32_e32 v48, v51, v58
	ds_bpermute_b32 v49, v115, v48
	v_cvt_pk_bf16_f32 v51, v54, v55
	v_cvt_pk_bf16_f32 v52, v84, v85
	v_cvt_pk_bf16_f32 v53, v82, v83
	global_store_dwordx4 v[56:57], v[50:53], off sc1
	s_and_saveexec_b64 s[26:27], s[4:5]
	s_cbranch_execz .LBB0_386
	s_waitcnt lgkmcnt(0)
	v_add_f32_e32 v48, v48, v49
	ds_write_b32 v163, v48 offset:2048
.LBB0_386:
	s_or_b64 exec, exec, s[26:27]
	v_ashrrev_i32_e32 v48, 2, v80
	s_waitcnt lgkmcnt(0)
	v_lshrrev_b32_e32 v49, 3, v80
	v_lshlrev_b32_e32 v50, 5, v80
	v_lshlrev_b32_e32 v51, 1, v80
	v_and_b32_e32 v52, 0xffffffc0, v48
	v_lshlrev_b32_e32 v48, 6, v80
	v_and_or_b32 v49, v49, 10, s52
	v_and_b32_e32 v50, 0x1e0, v50
	v_and_b32_e32 v51, 16, v51
	v_and_b32_e32 v48, 0x2000, v48
	v_lshlrev_b32_e32 v49, 9, v49
	v_bitop3_b32 v50, v50, v51, v161 bitop3:0x36
	s_waitcnt vmcnt(4)
	v_pk_add_f32 v[46:47], v[46:47], v[78:79]
	v_pk_add_f32 v[44:45], v[44:45], v[76:77]
	v_or3_b32 v50, v50, v49, v48
	v_pk_add_f32 v[48:49], v[42:43], v[74:75]
	v_pk_add_f32 v[42:43], v[40:41], v[72:73]
	v_mul_f32_e32 v40, v45, v45
	v_mul_f32_e32 v41, v47, v47
	v_fmac_f32_e32 v40, v44, v44
	v_fmac_f32_e32 v41, v46, v46
	v_add_f32_e32 v40, v40, v41
	v_mul_f32_e32 v41, v43, v43
	v_mul_f32_e32 v51, v49, v49
	v_fmac_f32_e32 v41, v42, v42
	v_fmac_f32_e32 v51, v48, v48
	v_add_f32_e32 v41, v41, v51
	v_add_f32_e32 v53, v40, v41
	v_add_u32_e32 v40, s19, v52
	v_ashrrev_i32_e32 v41, 31, v40
	v_readlane_b32 s26, v250, 27
	v_lshlrev_b64 v[40:41], 15, v[40:41]
	v_readlane_b32 s27, v250, 28
	v_lshlrev_b32_e32 v148, 1, v50
	s_waitcnt vmcnt(2)
	v_pk_add_f32 v[38:39], v[38:39], v[70:71]
	v_lshl_add_u64 v[40:41], s[26:27], 0, v[40:41]
	v_lshl_add_u64 v[50:51], v[40:41], 0, v[148:149]
	v_cvt_pk_bf16_f32 v40, v44, v45
	v_cvt_pk_bf16_f32 v41, v46, v47
	v_cvt_pk_bf16_f32 v42, v42, v43
	v_cvt_pk_bf16_f32 v43, v48, v49
	v_pk_add_f32 v[36:37], v[36:37], v[68:69]
	global_store_dwordx4 v[50:51], v[40:43], off sc1
	s_nop 1
	v_pk_add_f32 v[42:43], v[32:33], v[64:65]
	v_mul_f32_e32 v32, v37, v37
	v_mul_f32_e32 v33, v39, v39
	v_pk_add_f32 v[40:41], v[34:35], v[66:67]
	v_fmac_f32_e32 v32, v36, v36
	v_fmac_f32_e32 v33, v38, v38
	v_add_f32_e32 v32, v32, v33
	v_mul_f32_e32 v33, v43, v43
	v_mul_f32_e32 v34, v41, v41
	v_fmac_f32_e32 v33, v42, v42
	v_fmac_f32_e32 v34, v40, v40
	v_add_f32_e32 v33, v33, v34
	v_add_f32_e32 v32, v32, v33
	v_add_f32_e32 v35, v53, v32
	ds_bpermute_b32 v46, v114, v35
	v_add_u32_e32 v32, s13, v52
	v_ashrrev_i32_e32 v33, 31, v32
	v_lshlrev_b64 v[32:33], 15, v[32:33]
	v_lshl_add_u64 v[32:33], s[26:27], 0, v[32:33]
	v_lshl_add_u64 v[44:45], v[32:33], 0, v[148:149]
	s_waitcnt lgkmcnt(0)
	v_add_f32_e32 v32, v35, v46
	ds_bpermute_b32 v33, v115, v32
	v_cvt_pk_bf16_f32 v34, v36, v37
	v_cvt_pk_bf16_f32 v35, v38, v39
	v_cvt_pk_bf16_f32 v36, v42, v43
	v_cvt_pk_bf16_f32 v37, v40, v41
	global_store_dwordx4 v[44:45], v[34:37], off sc1
	s_and_saveexec_b64 s[26:27], s[4:5]
	s_cbranch_execz .LBB0_388
	s_waitcnt lgkmcnt(0)
	v_add_f32_e32 v32, v32, v33
	ds_write_b32 v163, v32 offset:2304
.LBB0_388:
	s_or_b64 exec, exec, s[26:27]
	v_add_u32_e32 v66, 0xa0, v156
	v_ashrrev_i32_e32 v67, 31, v66
	s_waitcnt lgkmcnt(0)
	v_lshlrev_b64 v[32:33], 14, v[66:67]
	v_lshl_add_u64 v[32:33], v[154:155], 0, v[32:33]
	global_load_dwordx4 v[50:53], v[32:33], off nt
	global_load_dwordx4 v[54:57], v[32:33], off offset:16 nt
	global_load_dwordx4 v[58:61], v[32:33], off offset:512 nt
	global_load_dwordx4 v[62:65], v[32:33], off offset:528 nt
	v_add_u32_e32 v48, 0xb0, v156
	v_ashrrev_i32_e32 v49, 31, v48
	v_lshlrev_b64 v[32:33], 14, v[48:49]
	v_lshl_add_u64 v[36:37], v[154:155], 0, v[32:33]
	global_load_dwordx4 v[40:43], v[36:37], off offset:16 nt
	global_load_dwordx4 v[44:47], v[36:37], off nt
	global_load_dwordx4 v[32:35], v[36:37], off offset:528 nt
	s_nop 0
	global_load_dwordx4 v[36:39], v[36:37], off offset:512 nt
	v_ashrrev_i32_e32 v49, 2, v66
	v_lshlrev_b32_e32 v67, 6, v66
	v_lshrrev_b32_e32 v68, 3, v66
	v_lshlrev_b32_e32 v69, 5, v66
	v_lshlrev_b32_e32 v66, 1, v66
	v_and_b32_e32 v49, 0xffffffc0, v49
	v_and_or_b32 v68, v68, 12, s52
	v_and_b32_e32 v69, 0x1e0, v69
	v_and_b32_e32 v66, 16, v66
	v_and_b32_e32 v67, 0x2000, v67
	v_lshlrev_b32_e32 v70, 9, v68
	v_bitop3_b32 v69, v69, v66, v161 bitop3:0x36
	v_add_u32_e32 v66, s19, v49
	v_add_u32_e32 v68, s13, v49
	v_or3_b32 v49, v69, v70, v67
	v_ashrrev_i32_e32 v67, 31, v66
	v_readlane_b32 s26, v250, 27
	v_lshlrev_b64 v[66:67], 15, v[66:67]
	v_readlane_b32 s27, v250, 28
	v_lshlrev_b32_e32 v148, 1, v49
	v_ashrrev_i32_e32 v69, 31, v68
	v_lshl_add_u64 v[66:67], s[26:27], 0, v[66:67]
	v_lshl_add_u64 v[66:67], v[66:67], 0, v[148:149]
	s_waitcnt vmcnt(7)
	v_pk_add_f32 v[30:31], v[30:31], v[52:53]
	v_pk_add_f32 v[28:29], v[28:29], v[50:51]
	s_waitcnt vmcnt(6)
	v_pk_add_f32 v[26:27], v[26:27], v[56:57]
	v_pk_add_f32 v[24:25], v[24:25], v[54:55]
	s_waitcnt vmcnt(5)
	v_pk_add_f32 v[22:23], v[22:23], v[60:61]
	v_pk_add_f32 v[20:21], v[20:21], v[58:59]
	s_waitcnt vmcnt(4)
	v_pk_add_f32 v[50:51], v[18:19], v[64:65]
	v_pk_add_f32 v[52:53], v[16:17], v[62:63]
	v_mul_f32_e32 v49, v29, v29
	v_mul_f32_e32 v54, v31, v31
	v_mul_f32_e32 v55, v25, v25
	v_mul_f32_e32 v56, v27, v27
	v_cvt_pk_bf16_f32 v16, v28, v29
	v_cvt_pk_bf16_f32 v17, v30, v31
	v_cvt_pk_bf16_f32 v18, v24, v25
	v_cvt_pk_bf16_f32 v19, v26, v27
	v_mul_f32_e32 v25, v21, v21
	v_mul_f32_e32 v27, v23, v23
	v_mul_f32_e32 v29, v53, v53
	v_mul_f32_e32 v31, v51, v51
	v_fmac_f32_e32 v49, v28, v28
	v_fmac_f32_e32 v54, v30, v30
	v_fmac_f32_e32 v55, v24, v24
	v_fmac_f32_e32 v56, v26, v26
	v_fmac_f32_e32 v25, v20, v20
	v_fmac_f32_e32 v27, v22, v22
	v_fmac_f32_e32 v29, v52, v52
	v_fmac_f32_e32 v31, v50, v50
	global_store_dwordx4 v[66:67], v[16:19], off sc1
	s_nop 1
	v_add_f32_e32 v16, v49, v54
	v_add_f32_e32 v17, v55, v56
	v_add_f32_e32 v18, v25, v27
	v_add_f32_e32 v19, v29, v31
	v_add_f32_e32 v16, v16, v17
	v_add_f32_e32 v17, v18, v19
	v_add_f32_e32 v19, v16, v17
	ds_bpermute_b32 v26, v114, v19
	v_lshlrev_b64 v[16:17], 15, v[68:69]
	v_lshl_add_u64 v[16:17], s[26:27], 0, v[16:17]
	v_lshl_add_u64 v[24:25], v[16:17], 0, v[148:149]
	v_cvt_pk_bf16_f32 v18, v20, v21
	s_waitcnt lgkmcnt(0)
	v_add_f32_e32 v16, v19, v26
	ds_bpermute_b32 v17, v115, v16
	v_cvt_pk_bf16_f32 v19, v22, v23
	v_cvt_pk_bf16_f32 v20, v52, v53
	v_cvt_pk_bf16_f32 v21, v50, v51
	global_store_dwordx4 v[24:25], v[18:21], off sc1
	s_and_saveexec_b64 s[26:27], s[4:5]
	s_cbranch_execz .LBB0_390
	s_waitcnt lgkmcnt(0)
	v_add_f32_e32 v16, v16, v17
	ds_write_b32 v163, v16 offset:2560
.LBB0_390:
	s_or_b64 exec, exec, s[26:27]
	v_ashrrev_i32_e32 v16, 2, v48
	s_waitcnt lgkmcnt(0)
	v_lshrrev_b32_e32 v17, 3, v48
	v_lshlrev_b32_e32 v18, 5, v48
	v_lshlrev_b32_e32 v19, 1, v48
	v_and_b32_e32 v20, 0xffffffc0, v16
	v_lshlrev_b32_e32 v16, 6, v48
	v_and_or_b32 v17, v17, 14, s52
	v_and_b32_e32 v18, 0x1e0, v18
	v_and_b32_e32 v19, 16, v19
	v_and_b32_e32 v16, 0x2000, v16
	v_lshlrev_b32_e32 v17, 9, v17
	v_bitop3_b32 v18, v18, v19, v161 bitop3:0x36
	s_waitcnt vmcnt(4)
	v_pk_add_f32 v[14:15], v[14:15], v[46:47]
	v_pk_add_f32 v[12:13], v[12:13], v[44:45]
	v_or3_b32 v18, v18, v17, v16
	v_pk_add_f32 v[16:17], v[10:11], v[42:43]
	v_pk_add_f32 v[10:11], v[8:9], v[40:41]
	v_mul_f32_e32 v8, v13, v13
	v_mul_f32_e32 v9, v15, v15
	v_fmac_f32_e32 v8, v12, v12
	v_fmac_f32_e32 v9, v14, v14
	v_add_f32_e32 v8, v8, v9
	v_mul_f32_e32 v9, v11, v11
	v_mul_f32_e32 v19, v17, v17
	v_fmac_f32_e32 v9, v10, v10
	v_fmac_f32_e32 v19, v16, v16
	v_add_f32_e32 v9, v9, v19
	v_add_f32_e32 v21, v8, v9
	v_add_u32_e32 v8, s19, v20
	v_ashrrev_i32_e32 v9, 31, v8
	v_readlane_b32 s26, v250, 27
	v_lshlrev_b64 v[8:9], 15, v[8:9]
	v_readlane_b32 s27, v250, 28
	v_lshlrev_b32_e32 v148, 1, v18
	s_waitcnt vmcnt(2)
	v_pk_add_f32 v[6:7], v[6:7], v[38:39]
	v_lshl_add_u64 v[8:9], s[26:27], 0, v[8:9]
	v_lshl_add_u64 v[18:19], v[8:9], 0, v[148:149]
	v_cvt_pk_bf16_f32 v8, v12, v13
	v_cvt_pk_bf16_f32 v9, v14, v15
	v_cvt_pk_bf16_f32 v10, v10, v11
	v_cvt_pk_bf16_f32 v11, v16, v17
	v_pk_add_f32 v[4:5], v[4:5], v[36:37]
	global_store_dwordx4 v[18:19], v[8:11], off sc1
	s_nop 1
	v_pk_add_f32 v[10:11], v[0:1], v[32:33]
	v_mul_f32_e32 v0, v5, v5
	v_mul_f32_e32 v1, v7, v7
	v_pk_add_f32 v[8:9], v[2:3], v[34:35]
	v_fmac_f32_e32 v0, v4, v4
	v_fmac_f32_e32 v1, v6, v6
	v_add_f32_e32 v0, v0, v1
	v_mul_f32_e32 v1, v11, v11
	v_mul_f32_e32 v2, v9, v9
	v_fmac_f32_e32 v1, v10, v10
	v_fmac_f32_e32 v2, v8, v8
	v_add_f32_e32 v1, v1, v2
	v_add_f32_e32 v0, v0, v1
	v_add_f32_e32 v3, v21, v0
	ds_bpermute_b32 v14, v114, v3
	v_add_u32_e32 v0, s13, v20
	v_ashrrev_i32_e32 v1, 31, v0
	v_lshlrev_b64 v[0:1], 15, v[0:1]
	v_lshl_add_u64 v[0:1], s[26:27], 0, v[0:1]
	v_lshl_add_u64 v[12:13], v[0:1], 0, v[148:149]
	s_waitcnt lgkmcnt(0)
	v_add_f32_e32 v0, v3, v14
	ds_bpermute_b32 v1, v115, v0
	v_cvt_pk_bf16_f32 v2, v4, v5
	v_cvt_pk_bf16_f32 v3, v6, v7
	v_cvt_pk_bf16_f32 v4, v10, v11
	v_cvt_pk_bf16_f32 v5, v8, v9
	global_store_dwordx4 v[12:13], v[2:5], off sc1
	s_and_saveexec_b64 s[26:27], s[4:5]
	s_cbranch_execz .LBB0_392
	s_waitcnt lgkmcnt(0)
	v_add_f32_e32 v0, v0, v1
	ds_write_b32 v163, v0 offset:2816

.LBB0_474:
	s_lshl_b32 s0, s0, 8
	s_and_b32 s0, s0, 0xf00
	s_or_b32 s0, s0, s41
	s_and_b64 s[26:27], exec, s[26:27]
	s_cselect_b32 s27, s55, s95
	s_cselect_b32 s26, s54, s94
	s_lshl_b32 s2, s1, 3
	s_lshr_b32 s17, s0, 5
	s_or_b32 s0, s17, s2
	v_lshl_add_u64 v[120:121], s[26:27], 0, v[180:181]
	v_mov_b32_e32 v187, v181
	s_ashr_i32 s1, s0, 31
	v_cvt_pk_bf16_f32 v202, v192, v193
	v_cvt_pk_bf16_f32 v203, v126, v127
	v_cvt_pk_bf16_f32 v204, v124, v125
	v_cvt_pk_bf16_f32 v205, v122, v123
	v_mov_b32_e32 v122, v190
	v_mov_b32_e32 v123, v190
	v_mov_b32_e32 v191, v190
	v_lshl_add_u64 v[120:121], v[120:121], 0, v[186:187]
	s_lshl_b64 s[0:1], s[0:1], 10
	v_pk_mul_f32 v[118:119], v[118:119], v[122:123]
	v_pk_mul_f32 v[114:115], v[114:115], v[122:123]
	v_cndmask_b32_e64 v122, 0, 1, s[24:25]
	v_lshl_add_u64 v[206:207], v[120:121], 0, s[0:1]
	v_pk_mul_f32 v[116:117], v[116:117], v[190:191]
	v_cmp_ne_u32_e64 s[0:1], 1, v122
	s_andn2_b64 vcc, exec, s[24:25]
	v_pk_mul_f32 v[122:123], v[112:113], v[190:191]
	global_store_dwordx4 v[206:207], v[202:205], off sc1
	s_cbranch_vccnz .LBB0_476
	v_mul_f32_e32 v113, 0xbfb8aa3b, v122
	v_mul_f32_e32 v124, 0xbfb8aa3b, v117
	v_exp_f32_e32 v113, v113
	v_exp_f32_e32 v125, v124
	v_mul_f32_e32 v127, 0xbfb8aa3b, v114
	v_mul_f32_e32 v112, 0xbfb8aa3b, v116
	v_add_f32_e32 v113, 1.0, v113
	v_rcp_f32_e32 v124, v113
	v_add_f32_e32 v113, 1.0, v125
	v_mul_f32_e32 v125, 0xbfb8aa3b, v123
	v_mul_f32_e32 v126, 0xbfb8aa3b, v118
	v_exp_f32_e32 v127, v127
	v_mul_f32_e32 v187, 0xbfb8aa3b, v119
	v_mul_f32_e32 v190, 0xbfb8aa3b, v115
	v_exp_f32_e32 v112, v112
	v_exp_f32_e32 v125, v125
	v_exp_f32_e32 v126, v126
	v_exp_f32_e32 v187, v187
	v_exp_f32_e32 v191, v190
	v_add_f32_e32 v127, 1.0, v127
	v_add_f32_e32 v112, 1.0, v112
	v_add_f32_e32 v125, 1.0, v125
	v_add_f32_e32 v126, 1.0, v126
	v_rcp_f32_e32 v190, v127
	v_add_f32_e32 v127, 1.0, v187
	v_add_f32_e32 v187, 1.0, v191
	v_rcp_f32_e32 v112, v112
	v_rcp_f32_e32 v113, v113
	v_rcp_f32_e32 v126, v126
	v_rcp_f32_e32 v127, v127
	v_rcp_f32_e32 v191, v187
	v_rcp_f32_e32 v125, v125
	v_pk_mul_f32 v[116:117], v[116:117], v[112:113]
	v_pk_mul_f32 v[118:119], v[118:119], v[126:127]
	v_pk_mul_f32 v[114:115], v[114:115], v[190:191]
	v_pk_mul_f32 v[122:123], v[122:123], v[124:125]
.LBB0_476:
	v_add_f32_e32 v112, v172, v173
	v_add_f32_e32 v113, v174, v175
	v_add_f32_e32 v112, v112, v113
	v_add_f32_e32 v113, v168, v169
	v_add_f32_e32 v124, v170, v171
	v_add_f32_e32 v113, v113, v124
	v_add_f32_e32 v112, v112, v113
	v_add_f32_e32 v113, v164, v165
	v_add_f32_e32 v124, v166, v167
	v_add_f32_e32 v113, v113, v124
	v_add_f32_e32 v112, v112, v113
	v_add_f32_e32 v113, v160, v161
	v_add_f32_e32 v124, v162, v163
	v_add_f32_e32 v113, v113, v124
	v_add_f32_e32 v112, v112, v113
	v_fmamk_f32 v112, v112, 0x39800000, v200
	v_rsq_f32_e32 v112, v112
	s_or_b32 s19, s17, 4
	s_or_b32 s24, s19, s2
	s_ashr_i32 s25, s24, 31
	s_lshl_b64 s[24:25], s[24:25], 10
	v_lshl_add_u64 v[124:125], v[120:121], 0, s[24:25]
	v_pk_mul_f32 v[110:111], v[110:111], v[112:113] op_sel_hi:[1,0]
	v_pk_mul_f32 v[108:109], v[108:109], v[112:113] op_sel_hi:[1,0]
	v_pk_mul_f32 v[106:107], v[106:107], v[112:113] op_sel_hi:[1,0]
	s_and_b64 vcc, exec, s[0:1]
	v_pk_mul_f32 v[104:105], v[104:105], v[112:113] op_sel_hi:[1,0]
	v_cvt_pk_bf16_f32 v116, v116, v117
	v_cvt_pk_bf16_f32 v117, v118, v119
	v_cvt_pk_bf16_f32 v118, v122, v123
	v_cvt_pk_bf16_f32 v119, v114, v115
	global_store_dwordx4 v[124:125], v[116:119], off sc1
	s_cbranch_vccnz .LBB0_478
	v_mul_f32_e32 v113, 0xbfb8aa3b, v108
	v_exp_f32_e32 v113, v113
	v_mul_f32_e32 v114, 0xbfb8aa3b, v104
	v_mul_f32_e32 v117, 0xbfb8aa3b, v110
	v_mul_f32_e32 v115, 0xbfb8aa3b, v109
	v_exp_f32_e32 v116, v114
	v_exp_f32_e32 v117, v117
	v_mul_f32_e32 v118, 0xbfb8aa3b, v106
	v_exp_f32_e32 v115, v115
	v_exp_f32_e32 v119, v118
	v_add_f32_e32 v113, 1.0, v113
	v_rcp_f32_e32 v114, v113
	v_add_f32_e32 v113, 1.0, v116
	v_add_f32_e32 v117, 1.0, v117
	v_rcp_f32_e32 v116, v113
	v_add_f32_e32 v113, 1.0, v115
	v_rcp_f32_e32 v118, v117
	v_add_f32_e32 v117, 1.0, v119
	v_mul_f32_e32 v119, 0xbfb8aa3b, v111
	v_rcp_f32_e32 v115, v113
	v_mul_f32_e32 v113, 0xbfb8aa3b, v105
	v_exp_f32_e32 v119, v119
	v_mul_f32_e32 v122, 0xbfb8aa3b, v107
	v_exp_f32_e32 v113, v113
	v_exp_f32_e32 v123, v122
	v_rcp_f32_e32 v122, v117
	v_add_f32_e32 v117, 1.0, v119
	v_add_f32_e32 v113, 1.0, v113
	v_rcp_f32_e32 v119, v117
	v_add_f32_e32 v117, 1.0, v123
	v_rcp_f32_e32 v123, v117
	v_rcp_f32_e32 v117, v113
	v_pk_mul_f32 v[110:111], v[110:111], v[118:119]
	v_pk_mul_f32 v[108:109], v[108:109], v[114:115]
	v_pk_mul_f32 v[106:107], v[106:107], v[122:123]
	v_pk_mul_f32 v[104:105], v[104:105], v[116:117]
.LBB0_478:
	s_or_b32 s24, s2, 0x80
	s_or_b32 s26, s24, s17
	s_ashr_i32 s27, s26, 31
	v_mov_b32_e32 v113, v112
	s_lshl_b64 s[26:27], s[26:27], 10
	v_cvt_pk_bf16_f32 v108, v108, v109
	v_cvt_pk_bf16_f32 v109, v110, v111
	v_cvt_pk_bf16_f32 v110, v104, v105
	v_mov_b32_e32 v104, v112
	v_mov_b32_e32 v105, v112
	v_lshl_add_u64 v[114:115], v[120:121], 0, s[26:27]
	v_pk_mul_f32 v[102:103], v[102:103], v[104:105]
	v_pk_mul_f32 v[100:101], v[100:101], v[112:113]
	v_pk_mul_f32 v[98:99], v[98:99], v[104:105]
	s_and_b64 vcc, exec, s[0:1]
	v_pk_mul_f32 v[104:105], v[96:97], v[112:113]
	v_cvt_pk_bf16_f32 v111, v106, v107
	global_store_dwordx4 v[114:115], v[108:111], off sc1
	s_cbranch_vccnz .LBB0_480
	v_mul_f32_e32 v97, 0xbfb8aa3b, v104
	v_mul_f32_e32 v106, 0xbfb8aa3b, v101
	v_exp_f32_e32 v97, v97
	v_exp_f32_e32 v107, v106
	v_mul_f32_e32 v109, 0xbfb8aa3b, v98
	v_mul_f32_e32 v110, 0xbfb8aa3b, v103
	v_add_f32_e32 v97, 1.0, v97
	v_mul_f32_e32 v96, 0xbfb8aa3b, v100
	v_rcp_f32_e32 v106, v97
	v_add_f32_e32 v97, 1.0, v107
	v_mul_f32_e32 v107, 0xbfb8aa3b, v105
	v_mul_f32_e32 v108, 0xbfb8aa3b, v102
	v_exp_f32_e32 v109, v109
	v_exp_f32_e32 v111, v110
	v_mul_f32_e32 v110, 0xbfb8aa3b, v99
	v_exp_f32_e32 v96, v96
	v_exp_f32_e32 v107, v107
	v_exp_f32_e32 v108, v108
	v_exp_f32_e32 v112, v110
	v_add_f32_e32 v109, 1.0, v109
	v_add_f32_e32 v96, 1.0, v96
	v_add_f32_e32 v107, 1.0, v107
	v_add_f32_e32 v108, 1.0, v108
	v_rcp_f32_e32 v110, v109
	v_add_f32_e32 v109, 1.0, v111
	v_add_f32_e32 v111, 1.0, v112
	v_rcp_f32_e32 v96, v96
	v_rcp_f32_e32 v97, v97
	v_rcp_f32_e32 v108, v108
	v_rcp_f32_e32 v109, v109
	v_rcp_f32_e32 v111, v111
	v_rcp_f32_e32 v107, v107
	v_pk_mul_f32 v[100:101], v[100:101], v[96:97]
	v_pk_mul_f32 v[102:103], v[102:103], v[108:109]
	v_pk_mul_f32 v[98:99], v[98:99], v[110:111]
	v_pk_mul_f32 v[104:105], v[104:105], v[106:107]
.LBB0_480:
	v_add_f32_e32 v96, v156, v157
	v_add_f32_e32 v97, v158, v159
	v_add_f32_e32 v96, v96, v97
	v_add_f32_e32 v97, v152, v153
	v_add_f32_e32 v106, v154, v155
	v_add_f32_e32 v97, v97, v106
	v_add_f32_e32 v96, v96, v97
	v_add_f32_e32 v97, v148, v149
	v_add_f32_e32 v106, v150, v151
	v_add_f32_e32 v97, v97, v106
	v_add_f32_e32 v96, v96, v97
	v_add_f32_e32 v97, v144, v145
	v_add_f32_e32 v106, v146, v147
	v_add_f32_e32 v97, v97, v106
	v_add_f32_e32 v96, v96, v97
	v_fmamk_f32 v96, v96, 0x39800000, v200
	v_rsq_f32_e32 v96, v96
	s_or_b32 s24, s19, s24
	s_ashr_i32 s25, s24, 31
	s_lshl_b64 s[24:25], s[24:25], 10
	v_lshl_add_u64 v[106:107], v[120:121], 0, s[24:25]
	v_pk_mul_f32 v[94:95], v[94:95], v[96:97] op_sel_hi:[1,0]
	v_pk_mul_f32 v[92:93], v[92:93], v[96:97] op_sel_hi:[1,0]
	v_pk_mul_f32 v[90:91], v[90:91], v[96:97] op_sel_hi:[1,0]
	s_and_b64 vcc, exec, s[0:1]
	v_pk_mul_f32 v[88:89], v[88:89], v[96:97] op_sel_hi:[1,0]
	v_cvt_pk_bf16_f32 v100, v100, v101
	v_cvt_pk_bf16_f32 v101, v102, v103
	v_cvt_pk_bf16_f32 v102, v104, v105
	v_cvt_pk_bf16_f32 v103, v98, v99
	global_store_dwordx4 v[106:107], v[100:103], off sc1
	s_cbranch_vccnz .LBB0_482
	v_mul_f32_e32 v97, 0xbfb8aa3b, v92
	v_exp_f32_e32 v97, v97
	v_mul_f32_e32 v98, 0xbfb8aa3b, v88
	v_mul_f32_e32 v101, 0xbfb8aa3b, v94
	v_mul_f32_e32 v99, 0xbfb8aa3b, v93
	v_exp_f32_e32 v100, v98
	v_exp_f32_e32 v101, v101
	v_mul_f32_e32 v102, 0xbfb8aa3b, v90
	v_exp_f32_e32 v99, v99
	v_exp_f32_e32 v103, v102
	v_add_f32_e32 v97, 1.0, v97
	v_rcp_f32_e32 v98, v97
	v_add_f32_e32 v97, 1.0, v100
	v_add_f32_e32 v101, 1.0, v101
	v_rcp_f32_e32 v100, v97
	v_add_f32_e32 v97, 1.0, v99
	v_rcp_f32_e32 v102, v101
	v_add_f32_e32 v101, 1.0, v103
	v_mul_f32_e32 v103, 0xbfb8aa3b, v95
	v_rcp_f32_e32 v99, v97
	v_mul_f32_e32 v97, 0xbfb8aa3b, v89
	v_exp_f32_e32 v103, v103
	v_mul_f32_e32 v104, 0xbfb8aa3b, v91
	v_exp_f32_e32 v97, v97
	v_exp_f32_e32 v105, v104
	v_rcp_f32_e32 v104, v101
	v_add_f32_e32 v101, 1.0, v103
	v_add_f32_e32 v97, 1.0, v97
	v_rcp_f32_e32 v103, v101
	v_add_f32_e32 v101, 1.0, v105
	v_rcp_f32_e32 v105, v101
	v_rcp_f32_e32 v101, v97
	v_pk_mul_f32 v[94:95], v[94:95], v[102:103]
	v_pk_mul_f32 v[92:93], v[92:93], v[98:99]
	v_pk_mul_f32 v[90:91], v[90:91], v[104:105]
	v_pk_mul_f32 v[88:89], v[88:89], v[100:101]
.LBB0_482:
	s_or_b32 s24, s2, 0x100
	s_or_b32 s26, s24, s17
	s_ashr_i32 s27, s26, 31
	v_mov_b32_e32 v97, v96
	s_lshl_b64 s[26:27], s[26:27], 10
	v_cvt_pk_bf16_f32 v92, v92, v93
	v_cvt_pk_bf16_f32 v93, v94, v95
	v_cvt_pk_bf16_f32 v94, v88, v89
	v_mov_b32_e32 v88, v96
	v_mov_b32_e32 v89, v96
	v_lshl_add_u64 v[98:99], v[120:121], 0, s[26:27]
	v_pk_mul_f32 v[86:87], v[86:87], v[88:89]
	v_pk_mul_f32 v[84:85], v[84:85], v[96:97]
	v_pk_mul_f32 v[82:83], v[82:83], v[88:89]
	s_and_b64 vcc, exec, s[0:1]
	v_pk_mul_f32 v[88:89], v[80:81], v[96:97]
	v_cvt_pk_bf16_f32 v95, v90, v91
	global_store_dwordx4 v[98:99], v[92:95], off sc1
	s_cbranch_vccnz .LBB0_484
	v_mul_f32_e32 v81, 0xbfb8aa3b, v88
	v_mul_f32_e32 v90, 0xbfb8aa3b, v85
	v_exp_f32_e32 v81, v81
	v_exp_f32_e32 v91, v90
	v_mul_f32_e32 v93, 0xbfb8aa3b, v82
	v_mul_f32_e32 v94, 0xbfb8aa3b, v87
	v_add_f32_e32 v81, 1.0, v81
	v_mul_f32_e32 v80, 0xbfb8aa3b, v84
	v_rcp_f32_e32 v90, v81
	v_add_f32_e32 v81, 1.0, v91
	v_mul_f32_e32 v91, 0xbfb8aa3b, v89
	v_mul_f32_e32 v92, 0xbfb8aa3b, v86
	v_exp_f32_e32 v93, v93
	v_exp_f32_e32 v95, v94
	v_mul_f32_e32 v94, 0xbfb8aa3b, v83
	v_exp_f32_e32 v80, v80
	v_exp_f32_e32 v91, v91
	v_exp_f32_e32 v92, v92
	v_exp_f32_e32 v96, v94
	v_add_f32_e32 v93, 1.0, v93
	v_add_f32_e32 v80, 1.0, v80
	v_add_f32_e32 v91, 1.0, v91
	v_add_f32_e32 v92, 1.0, v92
	v_rcp_f32_e32 v94, v93
	v_add_f32_e32 v93, 1.0, v95
	v_add_f32_e32 v95, 1.0, v96
	v_rcp_f32_e32 v80, v80
	v_rcp_f32_e32 v81, v81
	v_rcp_f32_e32 v92, v92
	v_rcp_f32_e32 v93, v93
	v_rcp_f32_e32 v95, v95
	v_rcp_f32_e32 v91, v91
	v_pk_mul_f32 v[84:85], v[84:85], v[80:81]
	v_pk_mul_f32 v[86:87], v[86:87], v[92:93]
	v_pk_mul_f32 v[82:83], v[82:83], v[94:95]
	v_pk_mul_f32 v[88:89], v[88:89], v[90:91]
.LBB0_484:
	v_add_f32_e32 v80, v140, v141
	v_add_f32_e32 v81, v142, v143
	v_add_f32_e32 v80, v80, v81
	v_add_f32_e32 v81, v136, v137
	v_add_f32_e32 v90, v138, v139
	v_add_f32_e32 v81, v81, v90
	v_add_f32_e32 v80, v80, v81
	v_add_f32_e32 v81, v132, v133
	v_add_f32_e32 v90, v134, v135
	v_add_f32_e32 v81, v81, v90
	v_add_f32_e32 v80, v80, v81
	v_add_f32_e32 v81, v128, v129
	v_add_f32_e32 v90, v130, v131
	v_add_f32_e32 v81, v81, v90
	v_add_f32_e32 v80, v80, v81
	v_fmamk_f32 v80, v80, 0x39800000, v200
	v_rsq_f32_e32 v80, v80
	s_or_b32 s24, s19, s24
	s_ashr_i32 s25, s24, 31
	s_lshl_b64 s[24:25], s[24:25], 10
	v_lshl_add_u64 v[90:91], v[120:121], 0, s[24:25]
	v_pk_mul_f32 v[78:79], v[78:79], v[80:81] op_sel_hi:[1,0]
	v_pk_mul_f32 v[76:77], v[76:77], v[80:81] op_sel_hi:[1,0]
	v_pk_mul_f32 v[74:75], v[74:75], v[80:81] op_sel_hi:[1,0]
	s_and_b64 vcc, exec, s[0:1]
	v_pk_mul_f32 v[72:73], v[72:73], v[80:81] op_sel_hi:[1,0]
	v_cvt_pk_bf16_f32 v84, v84, v85
	v_cvt_pk_bf16_f32 v85, v86, v87
	v_cvt_pk_bf16_f32 v86, v88, v89
	v_cvt_pk_bf16_f32 v87, v82, v83
	global_store_dwordx4 v[90:91], v[84:87], off sc1
	s_cbranch_vccnz .LBB0_486
	v_mul_f32_e32 v81, 0xbfb8aa3b, v76
	v_exp_f32_e32 v81, v81
	v_mul_f32_e32 v82, 0xbfb8aa3b, v72
	v_mul_f32_e32 v85, 0xbfb8aa3b, v78
	v_mul_f32_e32 v83, 0xbfb8aa3b, v77
	v_exp_f32_e32 v84, v82
	v_exp_f32_e32 v85, v85
	v_mul_f32_e32 v86, 0xbfb8aa3b, v74
	v_exp_f32_e32 v83, v83
	v_exp_f32_e32 v87, v86
	v_add_f32_e32 v81, 1.0, v81
	v_rcp_f32_e32 v82, v81
	v_add_f32_e32 v81, 1.0, v84
	v_add_f32_e32 v85, 1.0, v85
	v_rcp_f32_e32 v84, v81
	v_add_f32_e32 v81, 1.0, v83
	v_rcp_f32_e32 v86, v85
	v_add_f32_e32 v85, 1.0, v87
	v_mul_f32_e32 v87, 0xbfb8aa3b, v79
	v_rcp_f32_e32 v83, v81
	v_mul_f32_e32 v81, 0xbfb8aa3b, v73
	v_exp_f32_e32 v87, v87
	v_mul_f32_e32 v88, 0xbfb8aa3b, v75
	v_exp_f32_e32 v81, v81
	v_exp_f32_e32 v89, v88
	v_rcp_f32_e32 v88, v85
	v_add_f32_e32 v85, 1.0, v87
	v_add_f32_e32 v81, 1.0, v81
	v_rcp_f32_e32 v87, v85
	v_add_f32_e32 v85, 1.0, v89
	v_rcp_f32_e32 v89, v85
	v_rcp_f32_e32 v85, v81
	v_pk_mul_f32 v[78:79], v[78:79], v[86:87]
	v_pk_mul_f32 v[76:77], v[76:77], v[82:83]
	v_pk_mul_f32 v[74:75], v[74:75], v[88:89]
	v_pk_mul_f32 v[72:73], v[72:73], v[84:85]
.LBB0_486:
	s_or_b32 s24, s2, 0x180
	s_or_b32 s26, s24, s17
	s_ashr_i32 s27, s26, 31
	v_mov_b32_e32 v81, v80
	s_lshl_b64 s[26:27], s[26:27], 10
	v_cvt_pk_bf16_f32 v76, v76, v77
	v_cvt_pk_bf16_f32 v77, v78, v79
	v_cvt_pk_bf16_f32 v78, v72, v73
	v_mov_b32_e32 v72, v80
	v_mov_b32_e32 v73, v80
	v_lshl_add_u64 v[82:83], v[120:121], 0, s[26:27]
	v_pk_mul_f32 v[70:71], v[70:71], v[72:73]
	v_pk_mul_f32 v[68:69], v[68:69], v[80:81]
	v_pk_mul_f32 v[66:67], v[66:67], v[72:73]
	s_and_b64 vcc, exec, s[0:1]
	v_pk_mul_f32 v[64:65], v[64:65], v[80:81]
	v_cvt_pk_bf16_f32 v79, v74, v75
	global_store_dwordx4 v[82:83], v[76:79], off sc1
	s_cbranch_vccnz .LBB0_488
	v_mul_f32_e32 v73, 0xbfb8aa3b, v64
	v_mul_f32_e32 v74, 0xbfb8aa3b, v69
	v_exp_f32_e32 v73, v73
	v_exp_f32_e32 v75, v74
	v_mul_f32_e32 v77, 0xbfb8aa3b, v66
	v_mul_f32_e32 v78, 0xbfb8aa3b, v71
	v_add_f32_e32 v73, 1.0, v73
	v_mul_f32_e32 v72, 0xbfb8aa3b, v68
	v_rcp_f32_e32 v74, v73
	v_add_f32_e32 v73, 1.0, v75
	v_mul_f32_e32 v75, 0xbfb8aa3b, v65
	v_mul_f32_e32 v76, 0xbfb8aa3b, v70
	v_exp_f32_e32 v77, v77
	v_exp_f32_e32 v79, v78
	v_mul_f32_e32 v78, 0xbfb8aa3b, v67
	v_exp_f32_e32 v72, v72
	v_exp_f32_e32 v75, v75
	v_exp_f32_e32 v76, v76
	v_exp_f32_e32 v80, v78
	v_add_f32_e32 v77, 1.0, v77
	v_add_f32_e32 v72, 1.0, v72
	v_add_f32_e32 v75, 1.0, v75
	v_add_f32_e32 v76, 1.0, v76
	v_rcp_f32_e32 v78, v77
	v_add_f32_e32 v77, 1.0, v79
	v_add_f32_e32 v79, 1.0, v80
	v_rcp_f32_e32 v72, v72
	v_rcp_f32_e32 v73, v73
	v_rcp_f32_e32 v76, v76
	v_rcp_f32_e32 v77, v77
	v_rcp_f32_e32 v79, v79
	v_rcp_f32_e32 v75, v75
	v_pk_mul_f32 v[68:69], v[68:69], v[72:73]
	v_pk_mul_f32 v[70:71], v[70:71], v[76:77]
	v_pk_mul_f32 v[66:67], v[66:67], v[78:79]
	v_pk_mul_f32 v[64:65], v[64:65], v[74:75]
.LBB0_488:
	s_or_b32 s24, s19, s24
	s_ashr_i32 s25, s24, 31
	s_lshl_b64 s[24:25], s[24:25], 10
	v_cvt_pk_bf16_f32 v68, v68, v69
	v_cvt_pk_bf16_f32 v69, v70, v71
	v_cvt_pk_bf16_f32 v70, v64, v65
	v_lshlrev_b64 v[64:65], 6, v[188:189]
	v_lshl_add_u64 v[72:73], v[120:121], 0, s[24:25]
	v_lshl_add_u64 v[64:65], s[10:11], 0, v[64:65]
	s_movk_i32 s24, 0x2000
	v_cvt_pk_bf16_f32 v71, v66, v67
	global_store_dwordx4 v[72:73], v[68:71], off sc1
	v_add_co_u32_e32 v66, vcc, s24, v64
	s_mov_b64 s[24:25], 0x2000
	s_nop 0
	v_addc_co_u32_e32 v67, vcc, 0, v65, vcc
	global_load_dwordx4 v[112:115], v[66:67], off
	v_lshl_add_u64 v[68:69], v[64:65], 0, s[24:25]
	s_mov_b64 s[24:25], 0x2400
	global_load_dwordx4 v[116:119], v[68:69], off offset:16
	global_load_dwordx4 v[122:125], v[68:69], off offset:32
	global_load_dwordx4 v[126:129], v[68:69], off offset:48
	v_lshl_add_u64 v[68:69], v[64:65], 0, s[24:25]
	s_mov_b64 s[24:25], 0x2800
	v_lshl_add_u64 v[76:77], v[64:65], 0, s[24:25]
	v_lshl_add_u64 v[78:79], v[64:65], 0, s[14:15]
	global_load_dwordx4 v[96:99], v[68:69], off offset:48
	global_load_dwordx4 v[100:103], v[68:69], off offset:32
	global_load_dwordx4 v[104:107], v[66:67], off offset:1024
	global_load_dwordx4 v[92:95], v[66:67], off offset:2048
	global_load_dwordx4 v[80:83], v[76:77], off offset:32
	global_load_dwordx4 v[88:91], v[76:77], off offset:16
	global_load_dwordx4 v[108:111], v[68:69], off offset:16
	global_load_dwordx4 v[72:75], v[66:67], off offset:3072
	s_nop 0
	global_load_dwordx4 v[64:67], v[78:79], off offset:48
	global_load_dwordx4 v[68:71], v[78:79], off offset:32
	global_load_dwordx4 v[84:87], v[76:77], off offset:48
	s_nop 0
	global_load_dwordx4 v[76:79], v[78:79], off offset:16
	s_and_b64 vcc, exec, s[0:1]
	s_waitcnt vmcnt(15)
	v_mov_b32_e32 v130, v113
	v_mov_b32_e32 v131, v114
	v_mov_b32_e32 v113, v115
	s_waitcnt vmcnt(14)
	v_mov_b32_e32 v114, v117
	v_mov_b32_e32 v115, v118
	v_mov_b32_e32 v117, v119
	v_pk_add_f32 v[112:113], v[130:131], v[112:113]
	v_pk_add_f32 v[114:115], v[114:115], v[116:117]
	v_pk_add_f32 v[112:113], v[112:113], v[112:113] op_sel:[0,1] op_sel_hi:[1,0]
	v_pk_add_f32 v[114:115], v[114:115], v[114:115] op_sel:[0,1] op_sel_hi:[1,0]
	s_waitcnt vmcnt(13)
	v_add_f32_e32 v118, v122, v123
	v_add_f32_e32 v122, v124, v125
	s_waitcnt vmcnt(12)
	v_mov_b32_e32 v119, v128
	v_mov_b32_e32 v123, v129
	v_mov_b32_e32 v113, v126
	v_mov_b32_e32 v115, v127
	v_pk_add_f32 v[116:117], v[118:119], v[122:123]
	v_pk_add_f32 v[112:113], v[112:113], v[114:115]
	s_nop 0
	v_pk_add_f32 v[112:113], v[112:113], v[116:117]
	s_nop 0
	v_add_f32_e32 v112, v112, v113
	v_fmamk_f32 v112, v112, 0x39800000, v200
	v_rsq_f32_e32 v112, v112
	s_nop 0
	v_pk_mul_f32 v[62:63], v[62:63], v[112:113] op_sel_hi:[1,0]
	v_pk_mul_f32 v[60:61], v[60:61], v[112:113] op_sel_hi:[1,0]
	v_pk_mul_f32 v[58:59], v[58:59], v[112:113] op_sel_hi:[1,0]
	v_pk_mul_f32 v[56:57], v[56:57], v[112:113] op_sel_hi:[1,0]
	s_cbranch_vccnz .LBB0_490
	v_mul_f32_e32 v113, 0xbfb8aa3b, v60
	v_exp_f32_e32 v113, v113
	v_mul_f32_e32 v114, 0xbfb8aa3b, v56
	v_mul_f32_e32 v117, 0xbfb8aa3b, v62
	v_mul_f32_e32 v115, 0xbfb8aa3b, v61
	v_exp_f32_e32 v116, v114
	v_exp_f32_e32 v117, v117
	v_mul_f32_e32 v118, 0xbfb8aa3b, v58
	v_exp_f32_e32 v115, v115
	v_exp_f32_e32 v119, v118
	v_add_f32_e32 v113, 1.0, v113
	v_rcp_f32_e32 v114, v113
	v_add_f32_e32 v113, 1.0, v116
	v_add_f32_e32 v117, 1.0, v117
	v_rcp_f32_e32 v116, v113
	v_add_f32_e32 v113, 1.0, v115
	v_rcp_f32_e32 v118, v117
	v_add_f32_e32 v117, 1.0, v119
	v_mul_f32_e32 v119, 0xbfb8aa3b, v63
	v_rcp_f32_e32 v115, v113
	v_mul_f32_e32 v113, 0xbfb8aa3b, v57
	v_exp_f32_e32 v119, v119
	v_mul_f32_e32 v122, 0xbfb8aa3b, v59
	v_exp_f32_e32 v113, v113
	v_exp_f32_e32 v123, v122
	v_rcp_f32_e32 v122, v117
	v_add_f32_e32 v117, 1.0, v119
	v_add_f32_e32 v113, 1.0, v113
	v_rcp_f32_e32 v119, v117
	v_add_f32_e32 v117, 1.0, v123
	v_rcp_f32_e32 v123, v117
	v_rcp_f32_e32 v117, v113
	v_pk_mul_f32 v[62:63], v[62:63], v[118:119]
	v_pk_mul_f32 v[60:61], v[60:61], v[114:115]
	v_pk_mul_f32 v[58:59], v[58:59], v[122:123]
	v_pk_mul_f32 v[56:57], v[56:57], v[116:117]
.LBB0_490:
	s_add_i32 s24, s2, 0x400
	s_or_b32 s26, s24, s17
	s_ashr_i32 s27, s26, 31
	v_mov_b32_e32 v113, v112
	s_lshl_b64 s[26:27], s[26:27], 10
	v_cvt_pk_bf16_f32 v60, v60, v61
	v_cvt_pk_bf16_f32 v61, v62, v63
	v_cvt_pk_bf16_f32 v62, v56, v57
	v_mov_b32_e32 v56, v112
	v_mov_b32_e32 v57, v112
	v_lshl_add_u64 v[114:115], v[120:121], 0, s[26:27]
	v_pk_mul_f32 v[54:55], v[54:55], v[56:57]
	v_pk_mul_f32 v[52:53], v[52:53], v[112:113]
	v_pk_mul_f32 v[50:51], v[50:51], v[56:57]
	s_and_b64 vcc, exec, s[0:1]
	v_pk_mul_f32 v[56:57], v[48:49], v[112:113]
	v_cvt_pk_bf16_f32 v63, v58, v59
	global_store_dwordx4 v[114:115], v[60:63], off sc1
	s_cbranch_vccnz .LBB0_492
	v_mul_f32_e32 v49, 0xbfb8aa3b, v56
	v_mul_f32_e32 v58, 0xbfb8aa3b, v53
	v_exp_f32_e32 v49, v49
	v_exp_f32_e32 v59, v58
	v_mul_f32_e32 v61, 0xbfb8aa3b, v50
	v_mul_f32_e32 v62, 0xbfb8aa3b, v55
	v_add_f32_e32 v49, 1.0, v49
	v_mul_f32_e32 v48, 0xbfb8aa3b, v52
	v_rcp_f32_e32 v58, v49
	v_add_f32_e32 v49, 1.0, v59
	v_mul_f32_e32 v59, 0xbfb8aa3b, v57
	v_mul_f32_e32 v60, 0xbfb8aa3b, v54
	v_exp_f32_e32 v61, v61
	v_exp_f32_e32 v63, v62
	v_mul_f32_e32 v62, 0xbfb8aa3b, v51
	v_exp_f32_e32 v48, v48
	v_exp_f32_e32 v59, v59
	v_exp_f32_e32 v60, v60
	v_exp_f32_e32 v112, v62
	v_add_f32_e32 v61, 1.0, v61
	v_add_f32_e32 v48, 1.0, v48
	v_add_f32_e32 v59, 1.0, v59
	v_add_f32_e32 v60, 1.0, v60
	v_rcp_f32_e32 v62, v61
	v_add_f32_e32 v61, 1.0, v63
	v_add_f32_e32 v63, 1.0, v112
	v_rcp_f32_e32 v48, v48
	v_rcp_f32_e32 v49, v49
	v_rcp_f32_e32 v60, v60
	v_rcp_f32_e32 v61, v61
	v_rcp_f32_e32 v63, v63
	v_rcp_f32_e32 v59, v59
	v_pk_mul_f32 v[52:53], v[52:53], v[48:49]
	v_pk_mul_f32 v[54:55], v[54:55], v[60:61]
	v_pk_mul_f32 v[50:51], v[50:51], v[62:63]
	v_pk_mul_f32 v[56:57], v[56:57], v[58:59]
.LBB0_492:
	s_waitcnt vmcnt(10)
	v_add_f32_e32 v48, v104, v105
	v_add_f32_e32 v49, v106, v107
	v_add_f32_e32 v48, v48, v49
	s_waitcnt vmcnt(6)
	v_add_f32_e32 v49, v108, v109
	v_add_f32_e32 v58, v110, v111
	v_add_f32_e32 v49, v49, v58
	v_add_f32_e32 v48, v48, v49
	v_add_f32_e32 v49, v100, v101
	v_add_f32_e32 v58, v102, v103
	v_add_f32_e32 v49, v49, v58
	v_add_f32_e32 v48, v48, v49
	v_add_f32_e32 v49, v96, v97
	v_add_f32_e32 v58, v98, v99
	v_add_f32_e32 v49, v49, v58
	v_add_f32_e32 v48, v48, v49
	v_fmamk_f32 v48, v48, 0x39800000, v200
	v_rsq_f32_e32 v48, v48
	s_or_b32 s24, s19, s24
	s_ashr_i32 s25, s24, 31
	s_lshl_b64 s[24:25], s[24:25], 10
	v_lshl_add_u64 v[58:59], v[120:121], 0, s[24:25]
	v_pk_mul_f32 v[46:47], v[46:47], v[48:49] op_sel_hi:[1,0]
	v_pk_mul_f32 v[44:45], v[44:45], v[48:49] op_sel_hi:[1,0]
	v_pk_mul_f32 v[42:43], v[42:43], v[48:49] op_sel_hi:[1,0]
	s_and_b64 vcc, exec, s[0:1]
	v_pk_mul_f32 v[40:41], v[40:41], v[48:49] op_sel_hi:[1,0]
	v_cvt_pk_bf16_f32 v52, v52, v53
	v_cvt_pk_bf16_f32 v53, v54, v55
	v_cvt_pk_bf16_f32 v54, v56, v57
	v_cvt_pk_bf16_f32 v55, v50, v51
	global_store_dwordx4 v[58:59], v[52:55], off sc1
	s_cbranch_vccnz .LBB0_494
	v_mul_f32_e32 v49, 0xbfb8aa3b, v44
	v_exp_f32_e32 v49, v49
	v_mul_f32_e32 v50, 0xbfb8aa3b, v40
	v_mul_f32_e32 v53, 0xbfb8aa3b, v46
	v_mul_f32_e32 v51, 0xbfb8aa3b, v45
	v_exp_f32_e32 v52, v50
	v_exp_f32_e32 v53, v53
	v_mul_f32_e32 v54, 0xbfb8aa3b, v42
	v_exp_f32_e32 v51, v51
	v_exp_f32_e32 v55, v54
	v_add_f32_e32 v49, 1.0, v49
	v_rcp_f32_e32 v50, v49
	v_add_f32_e32 v49, 1.0, v52
	v_add_f32_e32 v53, 1.0, v53
	v_rcp_f32_e32 v52, v49
	v_add_f32_e32 v49, 1.0, v51
	v_rcp_f32_e32 v54, v53
	v_add_f32_e32 v53, 1.0, v55
	v_mul_f32_e32 v55, 0xbfb8aa3b, v47
	v_rcp_f32_e32 v51, v49
	v_mul_f32_e32 v49, 0xbfb8aa3b, v41
	v_exp_f32_e32 v55, v55
	v_mul_f32_e32 v56, 0xbfb8aa3b, v43
	v_exp_f32_e32 v49, v49
	v_exp_f32_e32 v57, v56
	v_rcp_f32_e32 v56, v53
	v_add_f32_e32 v53, 1.0, v55
	v_add_f32_e32 v49, 1.0, v49
	v_rcp_f32_e32 v55, v53
	v_add_f32_e32 v53, 1.0, v57
	v_rcp_f32_e32 v57, v53
	v_rcp_f32_e32 v53, v49
	v_pk_mul_f32 v[46:47], v[46:47], v[54:55]
	v_pk_mul_f32 v[44:45], v[44:45], v[50:51]
	v_pk_mul_f32 v[42:43], v[42:43], v[56:57]
	v_pk_mul_f32 v[40:41], v[40:41], v[52:53]
.LBB0_494:
	s_add_i32 s24, s2, 0x480
	s_or_b32 s26, s24, s17
	s_ashr_i32 s27, s26, 31
	v_mov_b32_e32 v49, v48
	s_lshl_b64 s[26:27], s[26:27], 10
	v_cvt_pk_bf16_f32 v44, v44, v45
	v_cvt_pk_bf16_f32 v45, v46, v47
	v_cvt_pk_bf16_f32 v46, v40, v41
	v_mov_b32_e32 v40, v48
	v_mov_b32_e32 v41, v48
	v_lshl_add_u64 v[50:51], v[120:121], 0, s[26:27]
	v_pk_mul_f32 v[38:39], v[38:39], v[40:41]
	v_pk_mul_f32 v[36:37], v[36:37], v[48:49]
	v_pk_mul_f32 v[34:35], v[34:35], v[40:41]
	s_and_b64 vcc, exec, s[0:1]
	v_pk_mul_f32 v[40:41], v[32:33], v[48:49]
	v_cvt_pk_bf16_f32 v47, v42, v43
	global_store_dwordx4 v[50:51], v[44:47], off sc1
	s_cbranch_vccnz .LBB0_496
	v_mul_f32_e32 v33, 0xbfb8aa3b, v40
	v_mul_f32_e32 v42, 0xbfb8aa3b, v37
	v_exp_f32_e32 v33, v33
	v_exp_f32_e32 v43, v42
	v_mul_f32_e32 v45, 0xbfb8aa3b, v34
	v_mul_f32_e32 v46, 0xbfb8aa3b, v39
	v_add_f32_e32 v33, 1.0, v33
	v_mul_f32_e32 v32, 0xbfb8aa3b, v36
	v_rcp_f32_e32 v42, v33
	v_add_f32_e32 v33, 1.0, v43
	v_mul_f32_e32 v43, 0xbfb8aa3b, v41
	v_mul_f32_e32 v44, 0xbfb8aa3b, v38
	v_exp_f32_e32 v45, v45
	v_exp_f32_e32 v47, v46
	v_mul_f32_e32 v46, 0xbfb8aa3b, v35
	v_exp_f32_e32 v32, v32
	v_exp_f32_e32 v43, v43
	v_exp_f32_e32 v44, v44
	v_exp_f32_e32 v48, v46
	v_add_f32_e32 v45, 1.0, v45
	v_add_f32_e32 v32, 1.0, v32
	v_add_f32_e32 v43, 1.0, v43
	v_add_f32_e32 v44, 1.0, v44
	v_rcp_f32_e32 v46, v45
	v_add_f32_e32 v45, 1.0, v47
	v_add_f32_e32 v47, 1.0, v48
	v_rcp_f32_e32 v32, v32
	v_rcp_f32_e32 v33, v33
	v_rcp_f32_e32 v44, v44
	v_rcp_f32_e32 v45, v45
	v_rcp_f32_e32 v47, v47
	v_rcp_f32_e32 v43, v43
	v_pk_mul_f32 v[36:37], v[36:37], v[32:33]
	v_pk_mul_f32 v[38:39], v[38:39], v[44:45]
	v_pk_mul_f32 v[34:35], v[34:35], v[46:47]
	v_pk_mul_f32 v[40:41], v[40:41], v[42:43]
.LBB0_496:
	v_add_f32_e32 v32, v92, v93
	v_add_f32_e32 v33, v94, v95
	v_add_f32_e32 v32, v32, v33
	v_add_f32_e32 v33, v88, v89
	v_add_f32_e32 v42, v90, v91
	v_add_f32_e32 v33, v33, v42
	v_add_f32_e32 v32, v32, v33
	v_add_f32_e32 v33, v80, v81
	v_add_f32_e32 v42, v82, v83
	v_add_f32_e32 v33, v33, v42
	v_add_f32_e32 v32, v32, v33
	s_waitcnt vmcnt(4)
	v_add_f32_e32 v33, v84, v85
	v_add_f32_e32 v42, v86, v87
	v_add_f32_e32 v33, v33, v42
	v_add_f32_e32 v32, v32, v33
	v_fmamk_f32 v32, v32, 0x39800000, v200
	v_rsq_f32_e32 v32, v32
	s_or_b32 s24, s19, s24
	s_ashr_i32 s25, s24, 31
	s_lshl_b64 s[24:25], s[24:25], 10
	v_lshl_add_u64 v[42:43], v[120:121], 0, s[24:25]
	v_pk_mul_f32 v[30:31], v[30:31], v[32:33] op_sel_hi:[1,0]
	v_pk_mul_f32 v[28:29], v[28:29], v[32:33] op_sel_hi:[1,0]
	v_pk_mul_f32 v[26:27], v[26:27], v[32:33] op_sel_hi:[1,0]
	s_and_b64 vcc, exec, s[0:1]
	v_pk_mul_f32 v[24:25], v[24:25], v[32:33] op_sel_hi:[1,0]
	v_cvt_pk_bf16_f32 v36, v36, v37
	v_cvt_pk_bf16_f32 v37, v38, v39
	v_cvt_pk_bf16_f32 v38, v40, v41
	v_cvt_pk_bf16_f32 v39, v34, v35
	global_store_dwordx4 v[42:43], v[36:39], off sc1
	s_cbranch_vccnz .LBB0_498
	v_mul_f32_e32 v33, 0xbfb8aa3b, v28
	v_exp_f32_e32 v33, v33
	v_mul_f32_e32 v34, 0xbfb8aa3b, v24
	v_mul_f32_e32 v37, 0xbfb8aa3b, v30
	v_mul_f32_e32 v35, 0xbfb8aa3b, v29
	v_exp_f32_e32 v36, v34
	v_exp_f32_e32 v37, v37
	v_mul_f32_e32 v38, 0xbfb8aa3b, v26
	v_exp_f32_e32 v35, v35
	v_exp_f32_e32 v39, v38
	v_add_f32_e32 v33, 1.0, v33
	v_rcp_f32_e32 v34, v33
	v_add_f32_e32 v33, 1.0, v36
	v_add_f32_e32 v37, 1.0, v37
	v_rcp_f32_e32 v36, v33
	v_add_f32_e32 v33, 1.0, v35
	v_rcp_f32_e32 v38, v37
	v_add_f32_e32 v37, 1.0, v39
	v_mul_f32_e32 v39, 0xbfb8aa3b, v31
	v_rcp_f32_e32 v35, v33
	v_mul_f32_e32 v33, 0xbfb8aa3b, v25
	v_exp_f32_e32 v39, v39
	v_mul_f32_e32 v40, 0xbfb8aa3b, v27
	v_exp_f32_e32 v33, v33
	v_exp_f32_e32 v41, v40
	v_rcp_f32_e32 v40, v37
	v_add_f32_e32 v37, 1.0, v39
	v_add_f32_e32 v33, 1.0, v33
	v_rcp_f32_e32 v39, v37
	v_add_f32_e32 v37, 1.0, v41
	v_rcp_f32_e32 v41, v37
	v_rcp_f32_e32 v37, v33
	v_pk_mul_f32 v[30:31], v[30:31], v[38:39]
	v_pk_mul_f32 v[28:29], v[28:29], v[34:35]
	v_pk_mul_f32 v[26:27], v[26:27], v[40:41]
	v_pk_mul_f32 v[24:25], v[24:25], v[36:37]
.LBB0_498:
	s_add_i32 s24, s2, 0x500
	s_or_b32 s26, s24, s17
	s_ashr_i32 s27, s26, 31
	v_mov_b32_e32 v33, v32
	s_lshl_b64 s[26:27], s[26:27], 10
	v_cvt_pk_bf16_f32 v28, v28, v29
	v_cvt_pk_bf16_f32 v29, v30, v31
	v_cvt_pk_bf16_f32 v30, v24, v25
	v_mov_b32_e32 v24, v32
	v_mov_b32_e32 v25, v32
	v_lshl_add_u64 v[34:35], v[120:121], 0, s[26:27]
	v_pk_mul_f32 v[22:23], v[22:23], v[24:25]
	v_pk_mul_f32 v[20:21], v[20:21], v[32:33]
	v_pk_mul_f32 v[18:19], v[18:19], v[24:25]
	s_and_b64 vcc, exec, s[0:1]
	v_pk_mul_f32 v[24:25], v[16:17], v[32:33]
	v_cvt_pk_bf16_f32 v31, v26, v27
	global_store_dwordx4 v[34:35], v[28:31], off sc1
	s_cbranch_vccnz .LBB0_500
	v_mul_f32_e32 v17, 0xbfb8aa3b, v24
	v_mul_f32_e32 v26, 0xbfb8aa3b, v21
	v_exp_f32_e32 v17, v17
	v_exp_f32_e32 v27, v26
	v_mul_f32_e32 v29, 0xbfb8aa3b, v18
	v_mul_f32_e32 v30, 0xbfb8aa3b, v23
	v_add_f32_e32 v17, 1.0, v17
	v_mul_f32_e32 v16, 0xbfb8aa3b, v20
	v_rcp_f32_e32 v26, v17
	v_add_f32_e32 v17, 1.0, v27
	v_mul_f32_e32 v27, 0xbfb8aa3b, v25
	v_mul_f32_e32 v28, 0xbfb8aa3b, v22
	v_exp_f32_e32 v29, v29
	v_exp_f32_e32 v31, v30
	v_mul_f32_e32 v30, 0xbfb8aa3b, v19
	v_exp_f32_e32 v16, v16
	v_exp_f32_e32 v27, v27
	v_exp_f32_e32 v28, v28
	v_exp_f32_e32 v32, v30
	v_add_f32_e32 v29, 1.0, v29
	v_add_f32_e32 v16, 1.0, v16
	v_add_f32_e32 v27, 1.0, v27
	v_add_f32_e32 v28, 1.0, v28
	v_rcp_f32_e32 v30, v29
	v_add_f32_e32 v29, 1.0, v31
	v_add_f32_e32 v31, 1.0, v32
	v_rcp_f32_e32 v16, v16
	v_rcp_f32_e32 v17, v17
	v_rcp_f32_e32 v28, v28
	v_rcp_f32_e32 v29, v29
	v_rcp_f32_e32 v31, v31
	v_rcp_f32_e32 v27, v27
	v_pk_mul_f32 v[20:21], v[20:21], v[16:17]
	v_pk_mul_f32 v[22:23], v[22:23], v[28:29]
	v_pk_mul_f32 v[18:19], v[18:19], v[30:31]
	v_pk_mul_f32 v[24:25], v[24:25], v[26:27]
.LBB0_500:
	v_add_f32_e32 v16, v72, v73
	v_add_f32_e32 v17, v74, v75
	v_add_f32_e32 v16, v16, v17
	s_waitcnt vmcnt(5)
	v_add_f32_e32 v17, v76, v77
	v_add_f32_e32 v26, v78, v79
	v_add_f32_e32 v17, v17, v26
	v_add_f32_e32 v16, v16, v17
	v_add_f32_e32 v17, v68, v69
	v_add_f32_e32 v26, v70, v71
	v_add_f32_e32 v17, v17, v26
	v_add_f32_e32 v16, v16, v17
	v_add_f32_e32 v17, v64, v65
	v_add_f32_e32 v26, v66, v67
	v_add_f32_e32 v17, v17, v26
	v_add_f32_e32 v16, v16, v17
	v_fmamk_f32 v16, v16, 0x39800000, v200
	v_rsq_f32_e32 v16, v16
	s_or_b32 s24, s19, s24
	s_ashr_i32 s25, s24, 31
	s_lshl_b64 s[24:25], s[24:25], 10
	v_lshl_add_u64 v[26:27], v[120:121], 0, s[24:25]
	v_pk_mul_f32 v[14:15], v[14:15], v[16:17] op_sel_hi:[1,0]
	v_pk_mul_f32 v[12:13], v[12:13], v[16:17] op_sel_hi:[1,0]
	v_pk_mul_f32 v[10:11], v[10:11], v[16:17] op_sel_hi:[1,0]
	s_and_b64 vcc, exec, s[0:1]
	v_pk_mul_f32 v[8:9], v[8:9], v[16:17] op_sel_hi:[1,0]
	v_cvt_pk_bf16_f32 v20, v20, v21
	v_cvt_pk_bf16_f32 v21, v22, v23
	v_cvt_pk_bf16_f32 v22, v24, v25
	v_cvt_pk_bf16_f32 v23, v18, v19
	global_store_dwordx4 v[26:27], v[20:23], off sc1
	s_cbranch_vccnz .LBB0_502
	v_mul_f32_e32 v17, 0xbfb8aa3b, v12
	v_exp_f32_e32 v17, v17
	v_mul_f32_e32 v18, 0xbfb8aa3b, v8
	v_mul_f32_e32 v21, 0xbfb8aa3b, v14
	v_mul_f32_e32 v19, 0xbfb8aa3b, v13
	v_exp_f32_e32 v20, v18
	v_exp_f32_e32 v21, v21
	v_mul_f32_e32 v22, 0xbfb8aa3b, v10
	v_exp_f32_e32 v19, v19
	v_exp_f32_e32 v23, v22
	v_add_f32_e32 v17, 1.0, v17
	v_rcp_f32_e32 v18, v17
	v_add_f32_e32 v17, 1.0, v20
	v_add_f32_e32 v21, 1.0, v21
	v_rcp_f32_e32 v20, v17
	v_add_f32_e32 v17, 1.0, v19
	v_rcp_f32_e32 v22, v21
	v_add_f32_e32 v21, 1.0, v23
	v_mul_f32_e32 v23, 0xbfb8aa3b, v15
	v_rcp_f32_e32 v19, v17
	v_mul_f32_e32 v17, 0xbfb8aa3b, v9
	v_exp_f32_e32 v23, v23
	v_mul_f32_e32 v24, 0xbfb8aa3b, v11
	v_exp_f32_e32 v17, v17
	v_exp_f32_e32 v25, v24
	v_rcp_f32_e32 v24, v21
	v_add_f32_e32 v21, 1.0, v23
	v_add_f32_e32 v17, 1.0, v17
	v_rcp_f32_e32 v23, v21
	v_add_f32_e32 v21, 1.0, v25
	v_rcp_f32_e32 v25, v21
	v_rcp_f32_e32 v21, v17
	v_pk_mul_f32 v[14:15], v[14:15], v[22:23]
	v_pk_mul_f32 v[12:13], v[12:13], v[18:19]
	v_pk_mul_f32 v[10:11], v[10:11], v[24:25]
	v_pk_mul_f32 v[8:9], v[8:9], v[20:21]
.LBB0_502:
	s_addk_i32 s2, 0x580
	s_or_b32 s24, s2, s17
	s_ashr_i32 s25, s24, 31
	v_mov_b32_e32 v17, v16
	s_lshl_b64 s[24:25], s[24:25], 10
	v_cvt_pk_bf16_f32 v12, v12, v13
	v_cvt_pk_bf16_f32 v13, v14, v15
	v_cvt_pk_bf16_f32 v14, v8, v9
	v_mov_b32_e32 v8, v16
	v_mov_b32_e32 v9, v16
	v_lshl_add_u64 v[18:19], v[120:121], 0, s[24:25]
	v_pk_mul_f32 v[6:7], v[6:7], v[8:9]
	v_pk_mul_f32 v[4:5], v[4:5], v[16:17]
	v_pk_mul_f32 v[2:3], v[2:3], v[8:9]
	s_and_b64 vcc, exec, s[0:1]
	v_pk_mul_f32 v[0:1], v[0:1], v[16:17]
	v_cvt_pk_bf16_f32 v15, v10, v11
	global_store_dwordx4 v[18:19], v[12:15], off sc1
	s_cbranch_vccnz .LBB0_504
	v_mul_f32_e32 v9, 0xbfb8aa3b, v0
	v_mul_f32_e32 v10, 0xbfb8aa3b, v5
	v_exp_f32_e32 v9, v9
	v_exp_f32_e32 v11, v10
	v_mul_f32_e32 v13, 0xbfb8aa3b, v2
	v_mul_f32_e32 v14, 0xbfb8aa3b, v7
	v_add_f32_e32 v9, 1.0, v9
	v_mul_f32_e32 v8, 0xbfb8aa3b, v4
	v_rcp_f32_e32 v10, v9
	v_add_f32_e32 v9, 1.0, v11
	v_mul_f32_e32 v11, 0xbfb8aa3b, v1
	v_mul_f32_e32 v12, 0xbfb8aa3b, v6
	v_exp_f32_e32 v13, v13
	v_exp_f32_e32 v15, v14
	v_mul_f32_e32 v14, 0xbfb8aa3b, v3
	v_exp_f32_e32 v8, v8
	v_exp_f32_e32 v11, v11
	v_exp_f32_e32 v12, v12
	v_exp_f32_e32 v16, v14
	v_add_f32_e32 v13, 1.0, v13
	v_add_f32_e32 v8, 1.0, v8
	v_add_f32_e32 v11, 1.0, v11
	v_add_f32_e32 v12, 1.0, v12
	v_rcp_f32_e32 v14, v13
	v_add_f32_e32 v13, 1.0, v15
	v_add_f32_e32 v15, 1.0, v16
	v_rcp_f32_e32 v8, v8
	v_rcp_f32_e32 v9, v9
	v_rcp_f32_e32 v12, v12
	v_rcp_f32_e32 v13, v13
	v_rcp_f32_e32 v15, v15
	v_rcp_f32_e32 v11, v11
	v_pk_mul_f32 v[4:5], v[4:5], v[8:9]
	v_pk_mul_f32 v[6:7], v[6:7], v[12:13]
	v_pk_mul_f32 v[2:3], v[2:3], v[14:15]
	v_pk_mul_f32 v[0:1], v[0:1], v[10:11]
.LBB0_504:
	s_or_b32 s0, s19, s2
	s_ashr_i32 s1, s0, 31
	s_lshl_b64 s[0:1], s[0:1], 10
	v_lshl_add_u64 v[8:9], v[120:121], 0, s[0:1]
	v_cvt_pk_bf16_f32 v4, v4, v5
	v_cvt_pk_bf16_f32 v5, v6, v7
	v_cvt_pk_bf16_f32 v6, v0, v1
	v_cvt_pk_bf16_f32 v7, v2, v3
	global_store_dwordx4 v[8:9], v[4:7], off sc1
	s_andn2_b64 vcc, exec, s[4:5]
	s_mov_b64 s[0:1], -1
	s_cbranch_vccnz .LBB0_461
	s_andn2_b64 vcc, exec, s[6:7]
	s_cbranch_vccnz .LBB0_460
	s_barrier
	s_branch .LBB0_460

.LBB0_643:
	s_lshl_b32 s2, s2, 8
	s_or_b32 s11, s2, s38
	v_or_b32_e32 v56, s11, v177
	s_lshl_b32 s2, s18, 8
	v_ashrrev_i32_e32 v57, 31, v56
	s_add_i32 s13, s2, s37
	v_lshl_add_u64 v[60:61], v[56:57], 2, s[76:77]
	global_load_dwordx4 v[64:67], v[60:61], off offset:16
	global_load_dwordx4 v[68:71], v[60:61], off
	v_or_b32_e32 v182, s13, v176
	v_lshlrev_b32_e32 v57, 1, v182
	v_and_b32_e32 v147, 16, v57
	v_lshlrev_b32_e32 v57, 5, v182
	v_and_b32_e32 v149, 0x1e0, v57
	s_ashr_i32 s18, s13, 2
	v_or_b32_e32 v57, v149, v177
	s_ashr_i32 s2, s11, 6
	s_and_b32 s22, s18, 0xffffffc0
	v_bitop3_b32 v185, v57, s43, v147 bitop3:0xde
	v_or_b32_e32 v57, s42, v185
	s_add_i32 s18, s22, s2
	v_lshlrev_b32_e32 v164, 1, v57
	s_lshl_b32 s13, s13, 3
	s_ashr_i32 s19, s18, 31
	s_ashr_i32 s11, s11, 5
	v_lshl_add_u64 v[144:145], s[90:91], 0, v[164:165]
	s_lshl_b64 s[20:21], s[18:19], 15
	s_add_i32 s18, s13, s11
	v_lshl_add_u64 v[58:59], v[144:145], 0, s[20:21]
	s_ashr_i32 s19, s18, 31
	global_load_dwordx4 v[188:191], v[58:59], off nt
	s_lshl_b64 s[18:19], s[18:19], 10
	v_lshl_add_u64 v[58:59], v[166:167], 0, s[18:19]
	global_load_dwordx4 v[196:199], v[58:59], off nt
	v_or_b32_e32 v56, 0x80, v56
	v_or_b32_e32 v57, 16, v182
	v_ashrrev_i32_e32 v184, 6, v56
	v_ashrrev_i32_e32 v183, 5, v56
	v_lshrrev_b32_e32 v150, 3, v57
	v_lshlrev_b32_e32 v151, 3, v57
	global_load_dwordx4 v[56:59], v[60:61], off offset:528
	s_nop 0
	global_load_dwordx4 v[60:63], v[60:61], off offset:512
	v_add_u32_e32 v146, s22, v184
	v_add_u32_e32 v148, s13, v183
	v_and_or_b32 v150, v150, 10, s41
	v_bitop3_b32 v186, v149, v147, v177 bitop3:0x36
	v_and_b32_e32 v151, 0xfffffe80, v151
	v_ashrrev_i32_e32 v147, 31, v146
	v_ashrrev_i32_e32 v149, 31, v148
	v_lshlrev_b32_e32 v153, 9, v150
	v_add_u32_e32 v150, s11, v151
	v_add_u32_e32 v152, v151, v183
	v_lshlrev_b64 v[172:173], 15, v[146:147]
	v_lshlrev_b64 v[146:147], 10, v[148:149]
	v_or3_b32 v148, v186, v153, s42
	v_mov_b32_e32 v175, v165
	v_ashrrev_i32_e32 v151, 31, v150
	v_ashrrev_i32_e32 v153, 31, v152
	v_lshlrev_b32_e32 v174, 1, v148
	v_lshlrev_b64 v[148:149], 10, v[150:151]
	v_lshlrev_b64 v[150:151], 10, v[152:153]
	v_lshl_add_u64 v[152:153], s[90:91], 0, v[174:175]
	v_lshl_add_u64 v[146:147], v[166:167], 0, v[146:147]
	v_lshl_add_u64 v[148:149], v[166:167], 0, v[148:149]
	v_lshl_add_u64 v[192:193], v[166:167], 0, v[150:151]
	v_lshl_add_u64 v[144:145], v[144:145], 0, v[172:173]
	v_lshl_add_u64 v[150:151], v[152:153], 0, s[20:21]
	v_lshl_add_u64 v[208:209], v[152:153], 0, v[172:173]
	global_load_dwordx4 v[200:203], v[144:145], off nt
	global_load_dwordx4 v[204:207], v[146:147], off nt
	global_load_dwordx4 v[156:159], v[150:151], off nt
	global_load_dwordx4 v[152:155], v[148:149], off nt
	s_nop 0
	global_load_dwordx4 v[148:151], v[208:209], off nt
	global_load_dwordx4 v[144:147], v[192:193], off nt
	s_add_u32 s18, s58, s20
	s_addc_u32 s19, s59, s21
	s_andn2_b64 vcc, exec, s[4:5]
	s_mov_b64 s[4:5], -1
	s_waitcnt vmcnt(0)
	v_pk_add_f32 v[136:137], v[136:137], v[64:65]
	v_pk_add_f32 v[140:141], v[140:141], v[68:69]
	v_pk_add_f32 v[142:143], v[142:143], v[70:71]
	v_mul_f32_e32 v140, 0xbfb8aa3b, v140
	v_mul_f32_e32 v142, 0xbfb8aa3b, v142
	v_exp_f32_e32 v140, v140
	v_exp_f32_e32 v142, v142
	v_mul_f32_e32 v143, 0xbfb8aa3b, v143
	v_exp_f32_e32 v143, v143
	v_add_f32_e32 v140, 1.0, v140
	v_mul_f32_e32 v136, 0xbfb8aa3b, v136
	v_rcp_f32_e32 v140, v140
	v_add_f32_e32 v142, 1.0, v142
	v_exp_f32_e32 v136, v136
	v_rcp_f32_e32 v142, v142
	v_add_f32_e32 v143, 1.0, v143
	v_rcp_f32_e32 v143, v143
	v_add_f32_e32 v136, 1.0, v136
	v_rcp_f32_e32 v136, v136
	v_mul_f32_e32 v137, 0xbfb8aa3b, v137
	v_exp_f32_e32 v137, v137
	v_pk_add_f32 v[138:139], v[138:139], v[66:67]
	v_mul_f32_e32 v141, 0xbfb8aa3b, v141
	v_lshlrev_b32_e32 v187, 16, v188
	v_mul_f32_e32 v140, v140, v187
	v_lshlrev_b32_e32 v187, 16, v189
	v_mul_f32_e32 v142, v142, v187
	v_lshlrev_b32_e32 v187, 16, v197
	v_mul_f32_e32 v142, v142, v187
	v_and_b32_e32 v187, 0xffff0000, v189
	v_mul_f32_e32 v143, v143, v187
	v_and_b32_e32 v187, 0xffff0000, v197
	v_mul_f32_e32 v143, v143, v187
	v_lshlrev_b32_e32 v187, 16, v190
	v_mul_f32_e32 v136, v136, v187
	v_lshlrev_b32_e32 v187, 16, v198
	v_mul_f32_e32 v187, v136, v187
	v_add_f32_e32 v136, 1.0, v137
	v_mul_f32_e32 v137, 0xbfb8aa3b, v138
	v_exp_f32_e32 v137, v137
	v_rcp_f32_e32 v136, v136
	v_mul_f32_e32 v139, 0xbfb8aa3b, v139
	v_exp_f32_e32 v141, v141
	v_add_f32_e32 v137, 1.0, v137
	v_rcp_f32_e32 v137, v137
	v_exp_f32_e32 v139, v139
	v_and_b32_e32 v138, 0xffff0000, v190
	v_pk_add_f32 v[132:133], v[132:133], v[60:61]
	v_mul_f32_e32 v136, v136, v138
	v_and_b32_e32 v138, 0xffff0000, v198
	v_mul_f32_e32 v132, 0xbfb8aa3b, v132
	v_mul_f32_e32 v138, v136, v138
	v_lshlrev_b32_e32 v136, 16, v191
	v_exp_f32_e32 v132, v132
	v_add_f32_e32 v141, 1.0, v141
	v_mul_f32_e32 v136, v137, v136
	v_add_f32_e32 v137, 1.0, v139
	v_mul_f32_e32 v133, 0xbfb8aa3b, v133
	v_rcp_f32_e32 v141, v141
	v_rcp_f32_e32 v137, v137
	v_pk_add_f32 v[134:135], v[134:135], v[62:63]
	v_exp_f32_e32 v133, v133
	v_mul_f32_e32 v134, 0xbfb8aa3b, v134
	v_lshlrev_b32_e32 v139, 16, v199
	v_add_f32_e32 v132, 1.0, v132
	v_exp_f32_e32 v134, v134
	v_and_b32_e32 v188, 0xffff0000, v188
	v_mul_f32_e32 v139, v136, v139
	v_and_b32_e32 v136, 0xffff0000, v191
	v_rcp_f32_e32 v132, v132
	v_lshlrev_b32_e32 v192, 16, v196
	v_and_b32_e32 v193, 0xffff0000, v196
	v_mul_f32_e32 v141, v141, v188
	v_mul_f32_e32 v136, v137, v136
	v_and_b32_e32 v137, 0xffff0000, v199
	v_add_f32_e32 v133, 1.0, v133
	v_mul_f32_e32 v140, v140, v192
	v_mul_f32_e32 v141, v141, v193
	v_mul_f32_e32 v188, v136, v137
	v_cvt_pk_bf16_f32 v136, v140, v141
	v_rcp_f32_e32 v133, v133
	v_cvt_pk_bf16_f32 v137, v142, v143
	v_cvt_pk_bf16_f32 v138, v187, v138
	v_cvt_pk_bf16_f32 v139, v139, v188
	global_store_dwordx4 v164, v[136:139], s[18:19] sc1
	v_add_f32_e32 v134, 1.0, v134
	v_rcp_f32_e32 v134, v134
	v_lshlrev_b32_e32 v136, 16, v200
	v_mul_f32_e32 v132, v132, v136
	v_lshlrev_b32_e32 v136, 16, v204
	v_mul_f32_e32 v135, 0xbfb8aa3b, v135
	v_pk_add_f32 v[128:129], v[128:129], v[56:57]
	v_mul_f32_e32 v132, v132, v136
	v_and_b32_e32 v136, 0xffff0000, v200
	v_exp_f32_e32 v135, v135
	v_mul_f32_e32 v133, v133, v136
	v_and_b32_e32 v136, 0xffff0000, v204
	v_mul_f32_e32 v128, 0xbfb8aa3b, v128
	v_mul_f32_e32 v133, v133, v136
	v_lshlrev_b32_e32 v136, 16, v201
	v_exp_f32_e32 v128, v128
	v_mul_f32_e32 v134, v134, v136
	v_lshlrev_b32_e32 v136, 16, v205
	v_mul_f32_e32 v136, v134, v136
	v_add_f32_e32 v134, 1.0, v135
	v_rcp_f32_e32 v134, v134
	v_add_f32_e32 v128, 1.0, v128
	v_rcp_f32_e32 v128, v128
	v_mul_f32_e32 v129, 0xbfb8aa3b, v129
	v_and_b32_e32 v135, 0xffff0000, v201
	v_exp_f32_e32 v129, v129
	v_mul_f32_e32 v134, v134, v135
	v_and_b32_e32 v135, 0xffff0000, v205
	v_mul_f32_e32 v137, v134, v135
	v_lshlrev_b32_e32 v134, 16, v202
	v_pk_add_f32 v[130:131], v[130:131], v[58:59]
	v_mul_f32_e32 v128, v128, v134
	v_lshlrev_b32_e32 v134, 16, v206
	v_mul_f32_e32 v138, v128, v134
	v_add_f32_e32 v128, 1.0, v129
	v_mul_f32_e32 v129, 0xbfb8aa3b, v130
	v_exp_f32_e32 v129, v129
	v_rcp_f32_e32 v128, v128
	v_mul_f32_e32 v131, 0xbfb8aa3b, v131
	v_exp_f32_e32 v131, v131
	v_add_f32_e32 v129, 1.0, v129
	v_rcp_f32_e32 v129, v129
	v_and_b32_e32 v130, 0xffff0000, v202
	v_mul_f32_e32 v128, v128, v130
	v_and_b32_e32 v130, 0xffff0000, v206
	v_pk_add_f32 v[124:125], v[124:125], v[68:69]
	v_mul_f32_e32 v139, v128, v130
	v_lshlrev_b32_e32 v128, 16, v203
	v_mul_f32_e32 v124, 0xbfb8aa3b, v124
	v_mul_f32_e32 v128, v129, v128
	v_add_f32_e32 v129, 1.0, v131
	v_exp_f32_e32 v124, v124
	v_rcp_f32_e32 v129, v129
	v_mul_f32_e32 v125, 0xbfb8aa3b, v125
	v_pk_add_f32 v[126:127], v[126:127], v[70:71]
	v_exp_f32_e32 v125, v125
	v_lshlrev_b32_e32 v130, 16, v207
	v_mul_f32_e32 v126, 0xbfb8aa3b, v126
	v_mul_f32_e32 v140, v128, v130
	v_and_b32_e32 v128, 0xffff0000, v203
	v_add_f32_e32 v124, 1.0, v124
	v_exp_f32_e32 v126, v126
	v_mul_f32_e32 v128, v129, v128
	v_and_b32_e32 v129, 0xffff0000, v207
	v_rcp_f32_e32 v124, v124
	v_mul_f32_e32 v127, 0xbfb8aa3b, v127
	v_mul_f32_e32 v141, v128, v129
	v_lshl_add_u64 v[128:129], s[58:59], 0, v[172:173]
	v_pk_add_f32 v[120:121], v[120:121], v[64:65]
	v_add_f32_e32 v125, 1.0, v125
	v_exp_f32_e32 v127, v127
	v_lshl_add_u64 v[134:135], v[128:129], 0, v[164:165]
	v_cvt_pk_bf16_f32 v130, v132, v133
	v_rcp_f32_e32 v125, v125
	v_mul_f32_e32 v120, 0xbfb8aa3b, v120
	v_cvt_pk_bf16_f32 v131, v136, v137
	v_cvt_pk_bf16_f32 v132, v138, v139
	v_cvt_pk_bf16_f32 v133, v140, v141
	global_store_dwordx4 v[134:135], v[130:133], off sc1
	v_add_f32_e32 v126, 1.0, v126
	v_exp_f32_e32 v120, v120
	v_lshlrev_b32_e32 v130, 16, v156
	v_mul_f32_e32 v124, v124, v130
	v_lshlrev_b32_e32 v130, 16, v152
	v_rcp_f32_e32 v126, v126
	v_mul_f32_e32 v124, v124, v130
	v_and_b32_e32 v130, 0xffff0000, v156
	v_add_f32_e32 v127, 1.0, v127
	v_mul_f32_e32 v125, v125, v130
	v_and_b32_e32 v130, 0xffff0000, v152
	v_rcp_f32_e32 v127, v127
	v_mul_f32_e32 v125, v125, v130
	v_lshlrev_b32_e32 v130, 16, v157
	v_add_f32_e32 v120, 1.0, v120
	v_mul_f32_e32 v126, v126, v130
	v_lshlrev_b32_e32 v130, 16, v153
	v_rcp_f32_e32 v120, v120
	v_mul_f32_e32 v121, 0xbfb8aa3b, v121
	v_mul_f32_e32 v126, v126, v130
	v_and_b32_e32 v130, 0xffff0000, v157
	v_exp_f32_e32 v121, v121
	v_mul_f32_e32 v127, v127, v130
	v_and_b32_e32 v130, 0xffff0000, v153
	v_mul_f32_e32 v127, v127, v130
	v_lshlrev_b32_e32 v130, 16, v158
	v_pk_add_f32 v[122:123], v[122:123], v[66:67]
	v_mul_f32_e32 v120, v120, v130
	v_lshlrev_b32_e32 v130, 16, v154
	v_mul_f32_e32 v130, v120, v130
	v_add_f32_e32 v120, 1.0, v121
	v_mul_f32_e32 v121, 0xbfb8aa3b, v122
	v_exp_f32_e32 v121, v121
	v_rcp_f32_e32 v120, v120
	v_mul_f32_e32 v123, 0xbfb8aa3b, v123
	v_exp_f32_e32 v123, v123
	v_add_f32_e32 v121, 1.0, v121
	v_rcp_f32_e32 v121, v121
	v_and_b32_e32 v122, 0xffff0000, v158
	v_pk_add_f32 v[116:117], v[116:117], v[60:61]
	v_mul_f32_e32 v120, v120, v122
	v_and_b32_e32 v122, 0xffff0000, v154
	v_mul_f32_e32 v116, 0xbfb8aa3b, v116
	v_mul_f32_e32 v122, v120, v122
	v_lshlrev_b32_e32 v120, 16, v159
	v_exp_f32_e32 v116, v116
	v_mul_f32_e32 v120, v121, v120
	v_add_f32_e32 v121, 1.0, v123
	v_rcp_f32_e32 v121, v121
	v_lshlrev_b32_e32 v123, 16, v155
	v_add_f32_e32 v116, 1.0, v116
	v_mul_f32_e32 v123, v120, v123
	v_and_b32_e32 v120, 0xffff0000, v159
	v_rcp_f32_e32 v116, v116
	v_mul_f32_e32 v117, 0xbfb8aa3b, v117
	v_mul_f32_e32 v120, v121, v120
	v_and_b32_e32 v121, 0xffff0000, v155
	v_exp_f32_e32 v117, v117
	v_mul_f32_e32 v131, v120, v121
	v_cvt_pk_bf16_f32 v120, v124, v125
	v_cvt_pk_bf16_f32 v121, v126, v127
	v_cvt_pk_bf16_f32 v122, v130, v122
	v_cvt_pk_bf16_f32 v123, v123, v131
	global_store_dwordx4 v174, v[120:123], s[18:19] sc1
	v_pk_add_f32 v[118:119], v[118:119], v[62:63]
	v_pk_add_f32 v[112:113], v[112:113], v[56:57]
	v_lshlrev_b32_e32 v120, 16, v148
	v_mul_f32_e32 v116, v116, v120
	v_lshlrev_b32_e32 v120, 16, v144
	v_mul_f32_e32 v120, v116, v120
	v_add_f32_e32 v116, 1.0, v117
	v_rcp_f32_e32 v116, v116
	v_mul_f32_e32 v118, 0xbfb8aa3b, v118
	v_exp_f32_e32 v118, v118
	v_and_b32_e32 v117, 0xffff0000, v148
	v_mul_f32_e32 v116, v116, v117
	v_and_b32_e32 v117, 0xffff0000, v144
	v_mul_f32_e32 v121, v116, v117
	v_add_f32_e32 v116, 1.0, v118
	v_rcp_f32_e32 v116, v116
	v_mul_f32_e32 v118, 0xbfb8aa3b, v119
	v_exp_f32_e32 v118, v118
	v_mul_f32_e32 v112, 0xbfb8aa3b, v112
	v_lshlrev_b32_e32 v117, 16, v149
	v_exp_f32_e32 v112, v112
	v_mul_f32_e32 v116, v116, v117
	v_lshlrev_b32_e32 v117, 16, v145
	v_mul_f32_e32 v119, v116, v117
	v_add_f32_e32 v116, 1.0, v118
	v_rcp_f32_e32 v116, v116
	v_add_f32_e32 v112, 1.0, v112
	v_rcp_f32_e32 v112, v112
	v_mul_f32_e32 v113, 0xbfb8aa3b, v113
	v_and_b32_e32 v117, 0xffff0000, v149
	v_exp_f32_e32 v113, v113
	v_mul_f32_e32 v116, v116, v117
	v_and_b32_e32 v117, 0xffff0000, v145
	v_mul_f32_e32 v118, v116, v117
	v_lshlrev_b32_e32 v116, 16, v150
	v_pk_add_f32 v[114:115], v[114:115], v[58:59]
	v_mul_f32_e32 v112, v112, v116
	v_lshlrev_b32_e32 v116, 16, v146
	v_mul_f32_e32 v122, v112, v116
	v_add_f32_e32 v112, 1.0, v113
	v_mul_f32_e32 v113, 0xbfb8aa3b, v114
	v_exp_f32_e32 v113, v113
	v_rcp_f32_e32 v112, v112
	v_mul_f32_e32 v115, 0xbfb8aa3b, v115
	v_exp_f32_e32 v115, v115
	v_add_f32_e32 v113, 1.0, v113
	v_rcp_f32_e32 v113, v113
	v_and_b32_e32 v114, 0xffff0000, v150
	v_mul_f32_e32 v112, v112, v114
	v_and_b32_e32 v114, 0xffff0000, v146
	v_mul_f32_e32 v114, v112, v114
	v_lshlrev_b32_e32 v112, 16, v151
	v_mul_f32_e32 v112, v113, v112
	v_add_f32_e32 v113, 1.0, v115
	v_rcp_f32_e32 v113, v113
	v_lshlrev_b32_e32 v115, 16, v147
	v_mul_f32_e32 v115, v112, v115
	v_and_b32_e32 v112, 0xffff0000, v151
	v_mul_f32_e32 v112, v113, v112
	v_and_b32_e32 v113, 0xffff0000, v147
	v_mul_f32_e32 v123, v112, v113
	v_lshl_add_u64 v[116:117], v[128:129], 0, v[174:175]
	v_cvt_pk_bf16_f32 v112, v120, v121
	v_cvt_pk_bf16_f32 v113, v119, v118
	v_cvt_pk_bf16_f32 v114, v122, v114
	v_cvt_pk_bf16_f32 v115, v115, v123
	global_store_dwordx4 v[116:117], v[112:115], off sc1
	v_mov_b32_e32 v131, v165
	v_pk_add_f32 v[108:109], v[108:109], v[68:69]
	v_or_b32_e32 v114, 32, v182
	v_lshrrev_b32_e32 v112, 3, v114
	v_and_or_b32 v112, v112, 12, s41
	v_lshlrev_b32_e32 v112, 9, v112
	v_or3_b32 v112, v186, v112, s42
	v_lshlrev_b32_e32 v164, 1, v112
	v_lshl_add_u64 v[112:113], s[90:91], 0, v[164:165]
	v_lshlrev_b32_e32 v114, 3, v114
	v_and_b32_e32 v116, 0xffffff00, v114
	v_lshl_add_u64 v[114:115], v[112:113], 0, s[20:21]
	global_load_dwordx4 v[132:135], v[114:115], off nt
	v_add_u32_e32 v114, s11, v116
	v_ashrrev_i32_e32 v115, 31, v114
	v_lshlrev_b64 v[114:115], 10, v[114:115]
	v_lshl_add_u64 v[114:115], v[166:167], 0, v[114:115]
	global_load_dwordx4 v[136:139], v[114:115], off nt
	v_add_u32_e32 v114, v116, v183
	v_ashrrev_i32_e32 v115, 31, v114
	v_lshl_add_u64 v[112:113], v[112:113], 0, v[172:173]
	v_lshlrev_b64 v[114:115], 10, v[114:115]
	v_lshl_add_u64 v[114:115], v[166:167], 0, v[114:115]
	global_load_dwordx4 v[140:143], v[112:113], off nt
	global_load_dwordx4 v[144:147], v[114:115], off nt
	v_or_b32_e32 v114, 48, v182
	v_lshrrev_b32_e32 v112, 3, v114
	v_and_or_b32 v112, v112, 14, s41
	v_lshlrev_b32_e32 v112, 9, v112
	v_lshlrev_b32_e32 v114, 3, v114
	v_or3_b32 v112, v186, v112, s42
	v_and_b32_e32 v118, 0xffffff80, v114
	v_lshlrev_b32_e32 v130, 1, v112
	v_add_u32_e32 v116, s11, v118
	v_lshl_add_u64 v[112:113], s[90:91], 0, v[130:131]
	v_ashrrev_i32_e32 v117, 31, v116
	v_lshl_add_u64 v[114:115], v[112:113], 0, s[20:21]
	v_lshlrev_b64 v[116:117], 10, v[116:117]
	v_lshl_add_u64 v[116:117], v[166:167], 0, v[116:117]
	global_load_dwordx4 v[124:127], v[114:115], off nt
	global_load_dwordx4 v[120:123], v[116:117], off nt
	v_mul_f32_e32 v109, 0xbfb8aa3b, v109
	v_pk_add_f32 v[110:111], v[110:111], v[70:71]
	v_exp_f32_e32 v109, v109
	v_mul_f32_e32 v110, 0xbfb8aa3b, v110
	v_exp_f32_e32 v110, v110
	v_mul_f32_e32 v111, 0xbfb8aa3b, v111
	v_pk_add_f32 v[104:105], v[104:105], v[64:65]
	v_add_f32_e32 v109, 1.0, v109
	v_exp_f32_e32 v111, v111
	v_rcp_f32_e32 v109, v109
	v_mul_f32_e32 v104, 0xbfb8aa3b, v104
	v_add_f32_e32 v110, 1.0, v110
	v_exp_f32_e32 v104, v104
	v_rcp_f32_e32 v110, v110
	v_add_f32_e32 v111, 1.0, v111
	v_rcp_f32_e32 v111, v111
	v_add_f32_e32 v104, 1.0, v104
	v_rcp_f32_e32 v104, v104
	v_mul_f32_e32 v105, 0xbfb8aa3b, v105
	v_exp_f32_e32 v105, v105
	v_pk_add_f32 v[106:107], v[106:107], v[66:67]
	v_add_u32_e32 v114, v118, v183
	v_ashrrev_i32_e32 v115, 31, v114
	v_lshlrev_b64 v[114:115], 10, v[114:115]
	v_lshl_add_u64 v[112:113], v[112:113], 0, v[172:173]
	v_lshl_add_u64 v[114:115], v[166:167], 0, v[114:115]
	global_load_dwordx4 v[116:119], v[112:113], off nt
	s_nop 0
	global_load_dwordx4 v[112:115], v[114:115], off nt
	v_mul_f32_e32 v108, 0xbfb8aa3b, v108
	v_mul_f32_e32 v107, 0xbfb8aa3b, v107
	v_exp_f32_e32 v108, v108
	v_exp_f32_e32 v107, v107
	v_pk_add_f32 v[100:101], v[100:101], v[60:61]
	v_pk_add_f32 v[102:103], v[102:103], v[62:63]
	v_mul_f32_e32 v100, 0xbfb8aa3b, v100
	v_exp_f32_e32 v100, v100
	v_add_f32_e32 v108, 1.0, v108
	v_rcp_f32_e32 v108, v108
	v_mul_f32_e32 v101, 0xbfb8aa3b, v101
	v_add_f32_e32 v100, 1.0, v100
	v_rcp_f32_e32 v100, v100
	v_exp_f32_e32 v101, v101
	v_mul_f32_e32 v102, 0xbfb8aa3b, v102
	v_exp_f32_e32 v102, v102
	v_pk_add_f32 v[96:97], v[96:97], v[56:57]
	v_pk_add_f32 v[98:99], v[98:99], v[58:59]
	v_mul_f32_e32 v96, 0xbfb8aa3b, v96
	v_exp_f32_e32 v96, v96
	v_mul_f32_e32 v97, 0xbfb8aa3b, v97
	v_exp_f32_e32 v97, v97
	v_mul_f32_e32 v99, 0xbfb8aa3b, v99
	v_add_f32_e32 v96, 1.0, v96
	v_rcp_f32_e32 v96, v96
	v_exp_f32_e32 v99, v99
	s_waitcnt vmcnt(7)
	v_lshlrev_b32_e32 v148, 16, v132
	v_and_b32_e32 v132, 0xffff0000, v132
	v_mul_f32_e32 v109, v109, v132
	v_mul_f32_e32 v108, v108, v148
	v_pk_add_f32 v[92:93], v[92:93], v[68:69]
	s_waitcnt vmcnt(6)
	v_and_b32_e32 v132, 0xffff0000, v136
	v_mul_f32_e32 v109, v109, v132
	v_lshlrev_b32_e32 v132, 16, v133
	v_mul_f32_e32 v110, v110, v132
	v_lshlrev_b32_e32 v132, 16, v137
	v_mul_f32_e32 v110, v110, v132
	v_and_b32_e32 v132, 0xffff0000, v133
	v_mul_f32_e32 v111, v111, v132
	v_and_b32_e32 v132, 0xffff0000, v137
	v_mul_f32_e32 v111, v111, v132
	v_lshlrev_b32_e32 v132, 16, v134
	v_mul_f32_e32 v104, v104, v132
	v_lshlrev_b32_e32 v132, 16, v138
	v_mul_f32_e32 v132, v104, v132
	v_add_f32_e32 v104, 1.0, v105
	v_mul_f32_e32 v105, 0xbfb8aa3b, v106
	v_exp_f32_e32 v105, v105
	v_rcp_f32_e32 v104, v104
	v_and_b32_e32 v106, 0xffff0000, v134
	v_lshlrev_b32_e32 v148, 16, v136
	v_add_f32_e32 v105, 1.0, v105
	v_rcp_f32_e32 v105, v105
	v_mul_f32_e32 v104, v104, v106
	v_and_b32_e32 v106, 0xffff0000, v138
	v_mul_f32_e32 v106, v104, v106
	v_lshlrev_b32_e32 v104, 16, v135
	v_mul_f32_e32 v104, v105, v104
	v_add_f32_e32 v105, 1.0, v107
	v_rcp_f32_e32 v105, v105
	v_lshlrev_b32_e32 v107, 16, v139
	v_mul_f32_e32 v107, v104, v107
	v_and_b32_e32 v104, 0xffff0000, v135
	v_mul_f32_e32 v104, v105, v104
	v_and_b32_e32 v105, 0xffff0000, v139
	v_mul_f32_e32 v108, v108, v148
	v_mul_f32_e32 v133, v104, v105
	v_cvt_pk_bf16_f32 v104, v108, v109
	v_cvt_pk_bf16_f32 v105, v110, v111
	v_cvt_pk_bf16_f32 v106, v132, v106
	v_cvt_pk_bf16_f32 v107, v107, v133
	global_store_dwordx4 v164, v[104:107], s[18:19] sc1
	v_mul_f32_e32 v92, 0xbfb8aa3b, v92
	v_exp_f32_e32 v92, v92
	s_waitcnt vmcnt(6)
	v_lshlrev_b32_e32 v104, 16, v140
	v_mul_f32_e32 v100, v100, v104
	s_waitcnt vmcnt(5)
	v_lshlrev_b32_e32 v104, 16, v144
	v_mul_f32_e32 v104, v100, v104
	v_add_f32_e32 v100, 1.0, v101
	v_rcp_f32_e32 v100, v100
	v_and_b32_e32 v101, 0xffff0000, v140
	v_mul_f32_e32 v93, 0xbfb8aa3b, v93
	v_pk_add_f32 v[94:95], v[94:95], v[70:71]
	v_mul_f32_e32 v100, v100, v101
	v_and_b32_e32 v101, 0xffff0000, v144
	v_mul_f32_e32 v105, v100, v101
	v_add_f32_e32 v100, 1.0, v102
	v_rcp_f32_e32 v100, v100
	v_mul_f32_e32 v102, 0xbfb8aa3b, v103
	v_exp_f32_e32 v102, v102
	v_lshlrev_b32_e32 v101, 16, v141
	v_mul_f32_e32 v100, v100, v101
	v_lshlrev_b32_e32 v101, 16, v145
	v_mul_f32_e32 v103, v100, v101
	v_add_f32_e32 v100, 1.0, v102
	v_rcp_f32_e32 v100, v100
	v_and_b32_e32 v101, 0xffff0000, v141
	v_exp_f32_e32 v93, v93
	v_mul_f32_e32 v94, 0xbfb8aa3b, v94
	v_mul_f32_e32 v100, v100, v101
	v_and_b32_e32 v101, 0xffff0000, v145
	v_mul_f32_e32 v102, v100, v101
	v_lshlrev_b32_e32 v100, 16, v142
	v_mul_f32_e32 v96, v96, v100
	v_lshlrev_b32_e32 v100, 16, v146
	v_mul_f32_e32 v106, v96, v100
	v_add_f32_e32 v96, 1.0, v97
	v_mul_f32_e32 v97, 0xbfb8aa3b, v98
	v_exp_f32_e32 v97, v97
	v_rcp_f32_e32 v96, v96
	v_and_b32_e32 v98, 0xffff0000, v142
	v_add_f32_e32 v92, 1.0, v92
	v_add_f32_e32 v97, 1.0, v97
	v_rcp_f32_e32 v97, v97
	v_mul_f32_e32 v96, v96, v98
	v_and_b32_e32 v98, 0xffff0000, v146
	v_mul_f32_e32 v98, v96, v98
	v_lshlrev_b32_e32 v96, 16, v143
	v_mul_f32_e32 v96, v97, v96
	v_add_f32_e32 v97, 1.0, v99
	v_rcp_f32_e32 v97, v97
	v_lshlrev_b32_e32 v99, 16, v147
	v_exp_f32_e32 v94, v94
	v_mul_f32_e32 v99, v96, v99
	v_and_b32_e32 v96, 0xffff0000, v143
	v_rcp_f32_e32 v92, v92
	v_mul_f32_e32 v95, 0xbfb8aa3b, v95
	v_mul_f32_e32 v96, v97, v96
	v_and_b32_e32 v97, 0xffff0000, v147
	v_pk_add_f32 v[88:89], v[88:89], v[64:65]
	v_add_f32_e32 v93, 1.0, v93
	v_exp_f32_e32 v95, v95
	v_mul_f32_e32 v107, v96, v97
	v_lshl_add_u64 v[100:101], v[128:129], 0, v[164:165]
	v_cvt_pk_bf16_f32 v96, v104, v105
	v_rcp_f32_e32 v93, v93
	v_mul_f32_e32 v88, 0xbfb8aa3b, v88
	v_cvt_pk_bf16_f32 v97, v103, v102
	v_cvt_pk_bf16_f32 v98, v106, v98
	v_cvt_pk_bf16_f32 v99, v99, v107
	global_store_dwordx4 v[100:101], v[96:99], off sc1
	v_add_f32_e32 v94, 1.0, v94
	v_exp_f32_e32 v88, v88
	s_waitcnt vmcnt(5)
	v_lshlrev_b32_e32 v96, 16, v124
	v_mul_f32_e32 v92, v92, v96
	s_waitcnt vmcnt(4)
	v_lshlrev_b32_e32 v96, 16, v120
	v_rcp_f32_e32 v94, v94
	v_mul_f32_e32 v92, v92, v96
	v_and_b32_e32 v96, 0xffff0000, v124
	v_add_f32_e32 v95, 1.0, v95
	v_mul_f32_e32 v93, v93, v96
	v_and_b32_e32 v96, 0xffff0000, v120
	v_rcp_f32_e32 v95, v95
	v_mul_f32_e32 v93, v93, v96
	v_lshlrev_b32_e32 v96, 16, v125
	v_add_f32_e32 v88, 1.0, v88
	v_mul_f32_e32 v94, v94, v96
	v_lshlrev_b32_e32 v96, 16, v121
	v_rcp_f32_e32 v88, v88
	v_mul_f32_e32 v89, 0xbfb8aa3b, v89
	v_mul_f32_e32 v94, v94, v96
	v_and_b32_e32 v96, 0xffff0000, v125
	v_exp_f32_e32 v89, v89
	v_mul_f32_e32 v95, v95, v96
	v_and_b32_e32 v96, 0xffff0000, v121
	v_mul_f32_e32 v95, v95, v96
	v_lshlrev_b32_e32 v96, 16, v126
	v_pk_add_f32 v[90:91], v[90:91], v[66:67]
	v_mul_f32_e32 v88, v88, v96
	v_lshlrev_b32_e32 v96, 16, v122
	v_mul_f32_e32 v96, v88, v96
	v_add_f32_e32 v88, 1.0, v89
	v_mul_f32_e32 v89, 0xbfb8aa3b, v90
	v_exp_f32_e32 v89, v89
	v_rcp_f32_e32 v88, v88
	v_mul_f32_e32 v91, 0xbfb8aa3b, v91
	v_exp_f32_e32 v91, v91
	v_add_f32_e32 v89, 1.0, v89
	v_rcp_f32_e32 v89, v89
	v_and_b32_e32 v90, 0xffff0000, v126
	v_pk_add_f32 v[84:85], v[84:85], v[60:61]
	v_mul_f32_e32 v88, v88, v90
	v_and_b32_e32 v90, 0xffff0000, v122
	v_mul_f32_e32 v84, 0xbfb8aa3b, v84
	v_mul_f32_e32 v90, v88, v90
	v_lshlrev_b32_e32 v88, 16, v127
	v_exp_f32_e32 v84, v84
	v_mul_f32_e32 v88, v89, v88
	v_add_f32_e32 v89, 1.0, v91
	v_rcp_f32_e32 v89, v89
	v_lshlrev_b32_e32 v91, 16, v123
	v_add_f32_e32 v84, 1.0, v84
	v_mul_f32_e32 v91, v88, v91
	v_and_b32_e32 v88, 0xffff0000, v127
	v_rcp_f32_e32 v84, v84
	v_mul_f32_e32 v85, 0xbfb8aa3b, v85
	v_mul_f32_e32 v88, v89, v88
	v_and_b32_e32 v89, 0xffff0000, v123
	v_exp_f32_e32 v85, v85
	v_mul_f32_e32 v97, v88, v89
	v_cvt_pk_bf16_f32 v88, v92, v93
	v_cvt_pk_bf16_f32 v89, v94, v95
	v_cvt_pk_bf16_f32 v90, v96, v90
	v_cvt_pk_bf16_f32 v91, v91, v97
	global_store_dwordx4 v130, v[88:91], s[18:19] sc1
	v_pk_add_f32 v[86:87], v[86:87], v[62:63]
	v_pk_add_f32 v[80:81], v[80:81], v[56:57]
	s_waitcnt vmcnt(4)
	v_lshlrev_b32_e32 v88, 16, v116
	v_mul_f32_e32 v84, v84, v88
	s_waitcnt vmcnt(3)
	v_lshlrev_b32_e32 v88, 16, v112
	v_mul_f32_e32 v88, v84, v88
	v_add_f32_e32 v84, 1.0, v85
	v_rcp_f32_e32 v84, v84
	v_mul_f32_e32 v86, 0xbfb8aa3b, v86
	v_exp_f32_e32 v86, v86
	v_and_b32_e32 v85, 0xffff0000, v116
	v_mul_f32_e32 v84, v84, v85
	v_and_b32_e32 v85, 0xffff0000, v112
	v_mul_f32_e32 v89, v84, v85
	v_add_f32_e32 v84, 1.0, v86
	v_rcp_f32_e32 v84, v84
	v_mul_f32_e32 v86, 0xbfb8aa3b, v87
	v_exp_f32_e32 v86, v86
	v_mul_f32_e32 v80, 0xbfb8aa3b, v80
	v_lshlrev_b32_e32 v85, 16, v117
	v_exp_f32_e32 v80, v80
	v_mul_f32_e32 v84, v84, v85
	v_lshlrev_b32_e32 v85, 16, v113
	v_mul_f32_e32 v87, v84, v85
	v_add_f32_e32 v84, 1.0, v86
	v_rcp_f32_e32 v84, v84
	v_add_f32_e32 v80, 1.0, v80
	v_rcp_f32_e32 v80, v80
	v_mul_f32_e32 v81, 0xbfb8aa3b, v81
	v_and_b32_e32 v85, 0xffff0000, v117
	v_exp_f32_e32 v81, v81
	v_mul_f32_e32 v84, v84, v85
	v_and_b32_e32 v85, 0xffff0000, v113
	v_mul_f32_e32 v86, v84, v85
	v_lshlrev_b32_e32 v84, 16, v118
	v_pk_add_f32 v[82:83], v[82:83], v[58:59]
	v_mul_f32_e32 v80, v80, v84
	v_lshlrev_b32_e32 v84, 16, v114
	v_mul_f32_e32 v90, v80, v84
	v_add_f32_e32 v80, 1.0, v81
	v_mul_f32_e32 v81, 0xbfb8aa3b, v82
	v_exp_f32_e32 v81, v81
	v_rcp_f32_e32 v80, v80
	v_mul_f32_e32 v83, 0xbfb8aa3b, v83
	v_exp_f32_e32 v83, v83
	v_add_f32_e32 v81, 1.0, v81
	v_rcp_f32_e32 v81, v81
	v_and_b32_e32 v82, 0xffff0000, v118
	v_mul_f32_e32 v80, v80, v82
	v_and_b32_e32 v82, 0xffff0000, v114
	v_mul_f32_e32 v82, v80, v82
	v_lshlrev_b32_e32 v80, 16, v119
	v_mul_f32_e32 v80, v81, v80
	v_add_f32_e32 v81, 1.0, v83
	v_rcp_f32_e32 v81, v81
	v_lshlrev_b32_e32 v83, 16, v115
	v_mul_f32_e32 v83, v80, v83
	v_and_b32_e32 v80, 0xffff0000, v119
	v_mul_f32_e32 v80, v81, v80
	v_and_b32_e32 v81, 0xffff0000, v115
	v_mul_f32_e32 v91, v80, v81
	v_lshl_add_u64 v[84:85], v[128:129], 0, v[130:131]
	v_cvt_pk_bf16_f32 v80, v88, v89
	v_cvt_pk_bf16_f32 v81, v87, v86
	v_cvt_pk_bf16_f32 v82, v90, v82
	v_cvt_pk_bf16_f32 v83, v83, v91
	global_store_dwordx4 v[84:85], v[80:83], off sc1
	v_pk_add_f32 v[76:77], v[76:77], v[68:69]
	v_mov_b32_e32 v105, v165
	v_add_u32_e32 v82, 0x80, v182
	v_ashrrev_i32_e32 v80, 2, v82
	v_and_b32_e32 v84, 0xffffffc0, v80
	v_lshlrev_b32_e32 v80, 6, v82
	v_lshlrev_b32_e32 v82, 3, v82
	v_and_or_b32 v80, v80, s35, v185
	v_and_b32_e32 v85, 0xfffffe00, v82
	v_add_u32_e32 v82, s2, v84
	v_lshlrev_b32_e32 v164, 1, v80
	v_ashrrev_i32_e32 v83, 31, v82
	v_lshl_add_u64 v[80:81], s[90:91], 0, v[164:165]
	v_lshlrev_b64 v[120:121], 15, v[82:83]
	v_lshl_add_u64 v[82:83], v[80:81], 0, v[120:121]
	global_load_dwordx4 v[112:115], v[82:83], off nt
	v_add_u32_e32 v82, s11, v85
	v_ashrrev_i32_e32 v83, 31, v82
	v_lshlrev_b64 v[82:83], 10, v[82:83]
	v_lshl_add_u64 v[82:83], v[166:167], 0, v[82:83]
	global_load_dwordx4 v[116:119], v[82:83], off nt
	v_add_u32_e32 v82, v84, v184
	v_ashrrev_i32_e32 v83, 31, v82
	v_lshlrev_b64 v[110:111], 15, v[82:83]
	v_add_u32_e32 v82, v85, v183
	v_ashrrev_i32_e32 v83, 31, v82
	v_lshl_add_u64 v[80:81], v[80:81], 0, v[110:111]
	v_lshlrev_b64 v[82:83], 10, v[82:83]
	v_lshl_add_u64 v[82:83], v[166:167], 0, v[82:83]
	global_load_dwordx4 v[100:103], v[80:81], off nt
	global_load_dwordx4 v[96:99], v[82:83], off nt
	v_mul_f32_e32 v76, 0xbfb8aa3b, v76
	v_exp_f32_e32 v76, v76
	v_add_u32_e32 v82, 0x90, v182
	v_ashrrev_i32_e32 v80, 2, v82
	v_lshrrev_b32_e32 v81, 3, v82
	v_lshlrev_b32_e32 v83, 5, v82
	v_lshlrev_b32_e32 v84, 1, v82
	v_and_b32_e32 v86, 0xffffffc0, v80
	v_lshlrev_b32_e32 v80, 6, v82
	v_and_or_b32 v81, v81, 10, s41
	v_and_b32_e32 v83, 0x1e0, v83
	v_and_b32_e32 v84, 16, v84
	v_and_b32_e32 v80, 0x2000, v80
	v_lshlrev_b32_e32 v81, 9, v81
	v_bitop3_b32 v83, v83, v84, v177 bitop3:0x36
	v_lshlrev_b32_e32 v82, 3, v82
	v_add_f32_e32 v76, 1.0, v76
	v_or3_b32 v80, v83, v81, v80
	v_and_b32_e32 v87, 0xfffffe80, v82
	v_add_u32_e32 v82, s2, v86
	v_rcp_f32_e32 v76, v76
	v_mul_f32_e32 v77, 0xbfb8aa3b, v77
	v_lshlrev_b32_e32 v104, 1, v80
	v_ashrrev_i32_e32 v83, 31, v82
	v_add_u32_e32 v84, s11, v87
	v_exp_f32_e32 v77, v77
	v_lshl_add_u64 v[80:81], s[90:91], 0, v[104:105]
	v_lshlrev_b64 v[108:109], 15, v[82:83]
	v_ashrrev_i32_e32 v85, 31, v84
	v_lshl_add_u64 v[82:83], v[80:81], 0, v[108:109]
	v_lshlrev_b64 v[84:85], 10, v[84:85]
	v_lshl_add_u64 v[84:85], v[166:167], 0, v[84:85]
	global_load_dwordx4 v[92:95], v[82:83], off nt
	global_load_dwordx4 v[88:91], v[84:85], off nt
	v_pk_add_f32 v[78:79], v[78:79], v[70:71]
	v_pk_add_f32 v[72:73], v[72:73], v[64:65]
	v_mul_f32_e32 v78, 0xbfb8aa3b, v78
	v_exp_f32_e32 v78, v78
	v_mul_f32_e32 v72, 0xbfb8aa3b, v72
	v_exp_f32_e32 v72, v72
	v_mul_f32_e32 v73, 0xbfb8aa3b, v73
	v_exp_f32_e32 v73, v73
	v_pk_add_f32 v[74:75], v[74:75], v[66:67]
	v_add_f32_e32 v72, 1.0, v72
	v_rcp_f32_e32 v72, v72
	v_mul_f32_e32 v75, 0xbfb8aa3b, v75
	v_exp_f32_e32 v75, v75
	v_pk_add_f32 v[52:53], v[52:53], v[60:61]
	v_add_u32_e32 v82, v86, v184
	v_mul_f32_e32 v52, 0xbfb8aa3b, v52
	v_exp_f32_e32 v52, v52
	v_ashrrev_i32_e32 v83, 31, v82
	v_lshlrev_b64 v[106:107], 15, v[82:83]
	v_add_u32_e32 v82, v87, v183
	v_ashrrev_i32_e32 v83, 31, v82
	v_add_f32_e32 v52, 1.0, v52
	v_lshlrev_b64 v[82:83], 10, v[82:83]
	v_rcp_f32_e32 v52, v52
	v_mul_f32_e32 v53, 0xbfb8aa3b, v53
	v_lshl_add_u64 v[80:81], v[80:81], 0, v[106:107]
	v_lshl_add_u64 v[82:83], v[166:167], 0, v[82:83]
	v_exp_f32_e32 v53, v53
	global_load_dwordx4 v[84:87], v[80:81], off nt
	s_nop 0
	global_load_dwordx4 v[80:83], v[82:83], off nt
	v_pk_add_f32 v[54:55], v[54:55], v[62:63]
	v_pk_add_f32 v[48:49], v[48:49], v[56:57]
	v_mul_f32_e32 v54, 0xbfb8aa3b, v54
	s_waitcnt vmcnt(7)
	v_lshlrev_b32_e32 v122, 16, v112
	v_mul_f32_e32 v76, v76, v122
	v_exp_f32_e32 v54, v54
	v_mul_f32_e32 v48, 0xbfb8aa3b, v48
	v_exp_f32_e32 v48, v48
	s_waitcnt vmcnt(6)
	v_lshlrev_b32_e32 v122, 16, v116
	v_mul_f32_e32 v122, v76, v122
	v_add_f32_e32 v76, 1.0, v77
	v_rcp_f32_e32 v76, v76
	v_and_b32_e32 v77, 0xffff0000, v112
	v_add_f32_e32 v48, 1.0, v48
	v_rcp_f32_e32 v48, v48
	v_mul_f32_e32 v76, v76, v77
	v_and_b32_e32 v77, 0xffff0000, v116
	v_mul_f32_e32 v112, v76, v77
	v_add_f32_e32 v76, 1.0, v78
	v_rcp_f32_e32 v76, v76
	v_mul_f32_e32 v78, 0xbfb8aa3b, v79
	v_exp_f32_e32 v78, v78
	v_lshlrev_b32_e32 v77, 16, v113
	v_mul_f32_e32 v76, v76, v77
	v_lshlrev_b32_e32 v77, 16, v117
	v_mul_f32_e32 v79, v76, v77
	v_add_f32_e32 v76, 1.0, v78
	v_rcp_f32_e32 v76, v76
	v_and_b32_e32 v77, 0xffff0000, v113
	v_mul_f32_e32 v49, 0xbfb8aa3b, v49
	v_exp_f32_e32 v49, v49
	v_mul_f32_e32 v76, v76, v77
	v_and_b32_e32 v77, 0xffff0000, v117
	v_mul_f32_e32 v78, v76, v77
	v_lshlrev_b32_e32 v76, 16, v114
	v_mul_f32_e32 v72, v72, v76
	v_lshlrev_b32_e32 v76, 16, v118
	v_mul_f32_e32 v113, v72, v76
	v_add_f32_e32 v72, 1.0, v73
	v_mul_f32_e32 v73, 0xbfb8aa3b, v74
	v_exp_f32_e32 v73, v73
	v_rcp_f32_e32 v72, v72
	v_and_b32_e32 v74, 0xffff0000, v114
	v_pk_add_f32 v[50:51], v[50:51], v[58:59]
	v_add_f32_e32 v73, 1.0, v73
	v_rcp_f32_e32 v73, v73
	v_mul_f32_e32 v72, v72, v74
	v_and_b32_e32 v74, 0xffff0000, v118
	v_mul_f32_e32 v74, v72, v74
	v_lshlrev_b32_e32 v72, 16, v115
	v_mul_f32_e32 v72, v73, v72
	v_add_f32_e32 v73, 1.0, v75
	v_rcp_f32_e32 v73, v73
	v_lshlrev_b32_e32 v75, 16, v119
	v_mul_f32_e32 v75, v72, v75
	v_and_b32_e32 v72, 0xffff0000, v115
	v_mul_f32_e32 v72, v73, v72
	v_and_b32_e32 v73, 0xffff0000, v119
	v_mul_f32_e32 v114, v72, v73
	v_lshl_add_u64 v[72:73], s[58:59], 0, v[120:121]
	v_lshl_add_u64 v[76:77], v[72:73], 0, v[164:165]
	v_cvt_pk_bf16_f32 v72, v122, v112
	v_cvt_pk_bf16_f32 v73, v79, v78
	v_cvt_pk_bf16_f32 v74, v113, v74
	v_cvt_pk_bf16_f32 v75, v75, v114
	global_store_dwordx4 v[76:77], v[72:75], off sc1
	v_mul_f32_e32 v51, 0xbfb8aa3b, v51
	v_exp_f32_e32 v51, v51
	s_waitcnt vmcnt(6)
	v_lshlrev_b32_e32 v72, 16, v100
	v_mul_f32_e32 v52, v52, v72
	s_waitcnt vmcnt(5)
	v_lshlrev_b32_e32 v72, 16, v96
	v_mul_f32_e32 v72, v52, v72
	v_add_f32_e32 v52, 1.0, v53
	v_rcp_f32_e32 v52, v52
	v_and_b32_e32 v53, 0xffff0000, v100
	v_pk_add_f32 v[44:45], v[44:45], v[68:69]
	v_pk_add_f32 v[46:47], v[46:47], v[70:71]
	v_mul_f32_e32 v52, v52, v53
	v_and_b32_e32 v53, 0xffff0000, v96
	v_mul_f32_e32 v73, v52, v53
	v_add_f32_e32 v52, 1.0, v54
	v_rcp_f32_e32 v52, v52
	v_mul_f32_e32 v54, 0xbfb8aa3b, v55
	v_exp_f32_e32 v54, v54
	v_lshlrev_b32_e32 v53, 16, v101
	v_mul_f32_e32 v52, v52, v53
	v_lshlrev_b32_e32 v53, 16, v97
	v_mul_f32_e32 v55, v52, v53
	v_add_f32_e32 v52, 1.0, v54
	v_rcp_f32_e32 v52, v52
	v_and_b32_e32 v53, 0xffff0000, v101
	v_mul_f32_e32 v44, 0xbfb8aa3b, v44
	v_exp_f32_e32 v44, v44
	v_mul_f32_e32 v52, v52, v53
	v_and_b32_e32 v53, 0xffff0000, v97
	v_mul_f32_e32 v54, v52, v53
	v_lshlrev_b32_e32 v52, 16, v102
	v_mul_f32_e32 v48, v48, v52
	v_lshlrev_b32_e32 v52, 16, v98
	v_mul_f32_e32 v74, v48, v52
	v_add_f32_e32 v48, 1.0, v49
	v_mul_f32_e32 v49, 0xbfb8aa3b, v50
	v_exp_f32_e32 v49, v49
	v_rcp_f32_e32 v48, v48
	v_and_b32_e32 v50, 0xffff0000, v102
	v_add_f32_e32 v44, 1.0, v44
	v_add_f32_e32 v49, 1.0, v49
	v_rcp_f32_e32 v49, v49
	v_mul_f32_e32 v48, v48, v50
	v_and_b32_e32 v50, 0xffff0000, v98
	v_mul_f32_e32 v50, v48, v50
	v_lshlrev_b32_e32 v48, 16, v103
	v_mul_f32_e32 v48, v49, v48
	v_add_f32_e32 v49, 1.0, v51
	v_rcp_f32_e32 v49, v49
	v_lshlrev_b32_e32 v51, 16, v99
	v_mul_f32_e32 v51, v48, v51
	v_and_b32_e32 v48, 0xffff0000, v103
	v_mul_f32_e32 v48, v49, v48
	v_and_b32_e32 v49, 0xffff0000, v99
	v_rcp_f32_e32 v44, v44
	v_mul_f32_e32 v45, 0xbfb8aa3b, v45
	v_mul_f32_e32 v75, v48, v49
	v_lshl_add_u64 v[48:49], s[58:59], 0, v[110:111]
	v_exp_f32_e32 v45, v45
	v_lshl_add_u64 v[52:53], v[48:49], 0, v[164:165]
	v_cvt_pk_bf16_f32 v48, v72, v73
	v_cvt_pk_bf16_f32 v49, v55, v54
	v_cvt_pk_bf16_f32 v50, v74, v50
	v_cvt_pk_bf16_f32 v51, v51, v75
	global_store_dwordx4 v[52:53], v[48:51], off sc1
	v_mul_f32_e32 v46, 0xbfb8aa3b, v46
	v_exp_f32_e32 v46, v46
	s_waitcnt vmcnt(5)
	v_lshlrev_b32_e32 v48, 16, v92
	v_mul_f32_e32 v44, v44, v48
	s_waitcnt vmcnt(4)
	v_lshlrev_b32_e32 v48, 16, v88
	v_mul_f32_e32 v48, v44, v48
	v_add_f32_e32 v44, 1.0, v45
	v_rcp_f32_e32 v44, v44
	v_and_b32_e32 v45, 0xffff0000, v92
	v_pk_add_f32 v[40:41], v[40:41], v[64:65]
	v_pk_add_f32 v[42:43], v[42:43], v[66:67]
	v_mul_f32_e32 v44, v44, v45
	v_and_b32_e32 v45, 0xffff0000, v88
	v_mul_f32_e32 v49, v44, v45
	v_add_f32_e32 v44, 1.0, v46
	v_rcp_f32_e32 v44, v44
	v_mul_f32_e32 v46, 0xbfb8aa3b, v47
	v_exp_f32_e32 v46, v46
	v_mul_f32_e32 v40, 0xbfb8aa3b, v40
	v_lshlrev_b32_e32 v45, 16, v93
	v_exp_f32_e32 v40, v40
	v_mul_f32_e32 v44, v44, v45
	v_lshlrev_b32_e32 v45, 16, v89
	v_mul_f32_e32 v47, v44, v45
	v_add_f32_e32 v44, 1.0, v46
	v_rcp_f32_e32 v44, v44
	v_add_f32_e32 v40, 1.0, v40
	v_rcp_f32_e32 v40, v40
	v_mul_f32_e32 v41, 0xbfb8aa3b, v41
	v_and_b32_e32 v45, 0xffff0000, v93
	v_exp_f32_e32 v41, v41
	v_mul_f32_e32 v44, v44, v45
	v_and_b32_e32 v45, 0xffff0000, v89
	v_mul_f32_e32 v46, v44, v45
	v_lshlrev_b32_e32 v44, 16, v94
	v_mul_f32_e32 v40, v40, v44
	v_lshlrev_b32_e32 v44, 16, v90
	v_mul_f32_e32 v50, v40, v44
	v_add_f32_e32 v40, 1.0, v41
	v_mul_f32_e32 v41, 0xbfb8aa3b, v42
	v_exp_f32_e32 v41, v41
	v_rcp_f32_e32 v40, v40
	v_mul_f32_e32 v43, 0xbfb8aa3b, v43
	v_exp_f32_e32 v43, v43
	v_add_f32_e32 v41, 1.0, v41
	v_rcp_f32_e32 v41, v41
	v_and_b32_e32 v42, 0xffff0000, v94
	v_mul_f32_e32 v40, v40, v42
	v_and_b32_e32 v42, 0xffff0000, v90
	v_pk_add_f32 v[36:37], v[36:37], v[60:61]
	v_mul_f32_e32 v42, v40, v42
	v_lshlrev_b32_e32 v40, 16, v95
	v_mul_f32_e32 v36, 0xbfb8aa3b, v36
	v_mul_f32_e32 v40, v41, v40
	v_add_f32_e32 v41, 1.0, v43
	v_exp_f32_e32 v36, v36
	v_rcp_f32_e32 v41, v41
	v_lshlrev_b32_e32 v43, 16, v91
	v_mul_f32_e32 v43, v40, v43
	v_and_b32_e32 v40, 0xffff0000, v95
	v_add_f32_e32 v36, 1.0, v36
	v_mul_f32_e32 v40, v41, v40
	v_and_b32_e32 v41, 0xffff0000, v91
	v_rcp_f32_e32 v36, v36
	v_mul_f32_e32 v37, 0xbfb8aa3b, v37
	v_mul_f32_e32 v51, v40, v41
	v_lshl_add_u64 v[40:41], s[58:59], 0, v[108:109]
	v_exp_f32_e32 v37, v37
	v_lshl_add_u64 v[44:45], v[40:41], 0, v[104:105]
	v_cvt_pk_bf16_f32 v40, v48, v49
	v_cvt_pk_bf16_f32 v41, v47, v46
	v_cvt_pk_bf16_f32 v42, v50, v42
	v_cvt_pk_bf16_f32 v43, v43, v51
	global_store_dwordx4 v[44:45], v[40:43], off sc1
	v_pk_add_f32 v[38:39], v[38:39], v[62:63]
	v_pk_add_f32 v[32:33], v[32:33], v[56:57]
	s_waitcnt vmcnt(4)
	v_lshlrev_b32_e32 v40, 16, v84
	v_mul_f32_e32 v36, v36, v40
	s_waitcnt vmcnt(3)
	v_lshlrev_b32_e32 v40, 16, v80
	v_mul_f32_e32 v40, v36, v40
	v_add_f32_e32 v36, 1.0, v37
	v_rcp_f32_e32 v36, v36
	v_mul_f32_e32 v38, 0xbfb8aa3b, v38
	v_exp_f32_e32 v38, v38
	v_and_b32_e32 v37, 0xffff0000, v84
	v_mul_f32_e32 v36, v36, v37
	v_and_b32_e32 v37, 0xffff0000, v80
	v_mul_f32_e32 v41, v36, v37
	v_add_f32_e32 v36, 1.0, v38
	v_rcp_f32_e32 v36, v36
	v_mul_f32_e32 v38, 0xbfb8aa3b, v39
	v_exp_f32_e32 v38, v38
	v_mul_f32_e32 v32, 0xbfb8aa3b, v32
	v_lshlrev_b32_e32 v37, 16, v85
	v_exp_f32_e32 v32, v32
	v_mul_f32_e32 v36, v36, v37
	v_lshlrev_b32_e32 v37, 16, v81
	v_mul_f32_e32 v39, v36, v37
	v_add_f32_e32 v36, 1.0, v38
	v_rcp_f32_e32 v36, v36
	v_add_f32_e32 v32, 1.0, v32
	v_rcp_f32_e32 v32, v32
	v_mul_f32_e32 v33, 0xbfb8aa3b, v33
	v_and_b32_e32 v37, 0xffff0000, v85
	v_exp_f32_e32 v33, v33
	v_mul_f32_e32 v36, v36, v37
	v_and_b32_e32 v37, 0xffff0000, v81
	v_mul_f32_e32 v38, v36, v37
	v_lshlrev_b32_e32 v36, 16, v86
	v_pk_add_f32 v[34:35], v[34:35], v[58:59]
	v_mul_f32_e32 v32, v32, v36
	v_lshlrev_b32_e32 v36, 16, v82
	v_mul_f32_e32 v42, v32, v36
	v_add_f32_e32 v32, 1.0, v33
	v_mul_f32_e32 v33, 0xbfb8aa3b, v34
	v_exp_f32_e32 v33, v33
	v_rcp_f32_e32 v32, v32
	v_mul_f32_e32 v35, 0xbfb8aa3b, v35
	v_exp_f32_e32 v35, v35
	v_add_f32_e32 v33, 1.0, v33
	v_rcp_f32_e32 v33, v33
	v_and_b32_e32 v34, 0xffff0000, v86
	v_mul_f32_e32 v32, v32, v34
	v_and_b32_e32 v34, 0xffff0000, v82
	v_mul_f32_e32 v34, v32, v34
	v_lshlrev_b32_e32 v32, 16, v87
	v_mul_f32_e32 v32, v33, v32
	v_add_f32_e32 v33, 1.0, v35
	v_rcp_f32_e32 v33, v33
	v_lshlrev_b32_e32 v35, 16, v83
	v_mul_f32_e32 v35, v32, v35
	v_and_b32_e32 v32, 0xffff0000, v87
	v_mul_f32_e32 v32, v33, v32
	v_and_b32_e32 v33, 0xffff0000, v83
	v_mul_f32_e32 v43, v32, v33
	v_lshl_add_u64 v[32:33], s[58:59], 0, v[106:107]
	v_lshl_add_u64 v[36:37], v[32:33], 0, v[104:105]
	v_cvt_pk_bf16_f32 v32, v40, v41
	v_cvt_pk_bf16_f32 v33, v39, v38
	v_cvt_pk_bf16_f32 v34, v42, v34
	v_cvt_pk_bf16_f32 v35, v35, v43
	global_store_dwordx4 v[36:37], v[32:35], off sc1
	v_pk_add_f32 v[28:29], v[28:29], v[68:69]
	v_mov_b32_e32 v73, v165
	v_add_u32_e32 v34, 0xa0, v182
	v_ashrrev_i32_e32 v32, 2, v34
	v_lshrrev_b32_e32 v33, 3, v34
	v_lshlrev_b32_e32 v35, 5, v34
	v_lshlrev_b32_e32 v37, 1, v34
	v_and_b32_e32 v36, 0xffffffc0, v32
	v_lshlrev_b32_e32 v32, 6, v34
	v_and_or_b32 v33, v33, 12, s41
	v_and_b32_e32 v35, 0x1e0, v35
	v_and_b32_e32 v37, 16, v37
	v_and_b32_e32 v32, 0x2000, v32
	v_lshlrev_b32_e32 v33, 9, v33
	v_bitop3_b32 v35, v35, v37, v177 bitop3:0x36
	v_lshlrev_b32_e32 v34, 3, v34
	v_or3_b32 v32, v35, v33, v32
	v_and_b32_e32 v37, 0xffffff00, v34
	v_add_u32_e32 v34, s2, v36
	v_lshlrev_b32_e32 v164, 1, v32
	v_ashrrev_i32_e32 v35, 31, v34
	v_lshl_add_u64 v[32:33], s[90:91], 0, v[164:165]
	v_lshlrev_b64 v[88:89], 15, v[34:35]
	v_lshl_add_u64 v[34:35], v[32:33], 0, v[88:89]
	global_load_dwordx4 v[80:83], v[34:35], off nt
	v_add_u32_e32 v34, s11, v37
	v_ashrrev_i32_e32 v35, 31, v34
	v_lshlrev_b64 v[34:35], 10, v[34:35]
	v_lshl_add_u64 v[34:35], v[166:167], 0, v[34:35]
	global_load_dwordx4 v[84:87], v[34:35], off nt
	v_add_u32_e32 v34, v36, v184
	v_ashrrev_i32_e32 v35, 31, v34
	v_lshlrev_b64 v[78:79], 15, v[34:35]
	v_add_u32_e32 v34, v37, v183
	v_ashrrev_i32_e32 v35, 31, v34
	v_lshl_add_u64 v[32:33], v[32:33], 0, v[78:79]
	v_lshlrev_b64 v[34:35], 10, v[34:35]
	v_lshl_add_u64 v[34:35], v[166:167], 0, v[34:35]
	global_load_dwordx4 v[52:55], v[32:33], off nt
	global_load_dwordx4 v[48:51], v[34:35], off nt
	v_mul_f32_e32 v28, 0xbfb8aa3b, v28
	v_exp_f32_e32 v28, v28
	v_add_u32_e32 v34, 0xb0, v182
	v_ashrrev_i32_e32 v32, 2, v34
	v_lshrrev_b32_e32 v33, 3, v34
	v_lshlrev_b32_e32 v35, 5, v34
	v_lshlrev_b32_e32 v36, 1, v34
	v_and_b32_e32 v38, 0xffffffc0, v32
	v_lshlrev_b32_e32 v32, 6, v34
	v_and_or_b32 v33, v33, 14, s41
	v_and_b32_e32 v35, 0x1e0, v35
	v_and_b32_e32 v36, 16, v36
	v_and_b32_e32 v32, 0x2000, v32
	v_lshlrev_b32_e32 v33, 9, v33
	v_bitop3_b32 v35, v35, v36, v177 bitop3:0x36
	v_lshlrev_b32_e32 v34, 3, v34
	v_add_f32_e32 v28, 1.0, v28
	v_or3_b32 v32, v35, v33, v32
	v_and_b32_e32 v39, 0xffffff80, v34
	v_add_u32_e32 v34, s2, v38
	v_rcp_f32_e32 v28, v28
	v_mul_f32_e32 v29, 0xbfb8aa3b, v29
	v_lshlrev_b32_e32 v72, 1, v32
	v_ashrrev_i32_e32 v35, 31, v34
	v_add_u32_e32 v36, s11, v39
	v_exp_f32_e32 v29, v29
	v_lshl_add_u64 v[32:33], s[90:91], 0, v[72:73]
	v_lshlrev_b64 v[76:77], 15, v[34:35]
	v_ashrrev_i32_e32 v37, 31, v36
	v_lshl_add_u64 v[34:35], v[32:33], 0, v[76:77]
	v_lshlrev_b64 v[36:37], 10, v[36:37]
	v_lshl_add_u64 v[36:37], v[166:167], 0, v[36:37]
	global_load_dwordx4 v[44:47], v[34:35], off nt
	global_load_dwordx4 v[40:43], v[36:37], off nt
	v_pk_add_f32 v[30:31], v[30:31], v[70:71]
	v_pk_add_f32 v[24:25], v[24:25], v[64:65]
	v_mul_f32_e32 v30, 0xbfb8aa3b, v30
	v_exp_f32_e32 v30, v30
	v_mul_f32_e32 v24, 0xbfb8aa3b, v24
	v_exp_f32_e32 v24, v24
	v_mul_f32_e32 v25, 0xbfb8aa3b, v25
	v_exp_f32_e32 v25, v25
	v_pk_add_f32 v[26:27], v[26:27], v[66:67]
	v_add_f32_e32 v24, 1.0, v24
	v_rcp_f32_e32 v24, v24
	v_mul_f32_e32 v27, 0xbfb8aa3b, v27
	v_exp_f32_e32 v27, v27
	v_pk_add_f32 v[20:21], v[20:21], v[60:61]
	v_add_u32_e32 v34, v38, v184
	v_mul_f32_e32 v20, 0xbfb8aa3b, v20
	v_exp_f32_e32 v20, v20
	v_ashrrev_i32_e32 v35, 31, v34
	v_lshlrev_b64 v[74:75], 15, v[34:35]
	v_add_u32_e32 v34, v39, v183
	v_ashrrev_i32_e32 v35, 31, v34
	v_add_f32_e32 v20, 1.0, v20
	v_lshlrev_b64 v[34:35], 10, v[34:35]
	v_rcp_f32_e32 v20, v20
	v_mul_f32_e32 v21, 0xbfb8aa3b, v21
	v_lshl_add_u64 v[32:33], v[32:33], 0, v[74:75]
	v_lshl_add_u64 v[34:35], v[166:167], 0, v[34:35]
	v_exp_f32_e32 v21, v21
	global_load_dwordx4 v[36:39], v[32:33], off nt
	s_nop 0
	global_load_dwordx4 v[32:35], v[34:35], off nt
	v_pk_add_f32 v[22:23], v[22:23], v[62:63]
	v_pk_add_f32 v[16:17], v[16:17], v[56:57]
	v_mul_f32_e32 v22, 0xbfb8aa3b, v22
	s_waitcnt vmcnt(7)
	v_lshlrev_b32_e32 v90, 16, v80
	v_mul_f32_e32 v28, v28, v90
	v_exp_f32_e32 v22, v22
	v_mul_f32_e32 v16, 0xbfb8aa3b, v16
	v_exp_f32_e32 v16, v16
	s_waitcnt vmcnt(6)
	v_lshlrev_b32_e32 v90, 16, v84
	v_mul_f32_e32 v90, v28, v90
	v_add_f32_e32 v28, 1.0, v29
	v_rcp_f32_e32 v28, v28
	v_and_b32_e32 v29, 0xffff0000, v80
	v_add_f32_e32 v16, 1.0, v16
	v_rcp_f32_e32 v16, v16
	v_mul_f32_e32 v28, v28, v29
	v_and_b32_e32 v29, 0xffff0000, v84
	v_mul_f32_e32 v80, v28, v29
	v_add_f32_e32 v28, 1.0, v30
	v_rcp_f32_e32 v28, v28
	v_mul_f32_e32 v30, 0xbfb8aa3b, v31
	v_exp_f32_e32 v30, v30
	v_lshlrev_b32_e32 v29, 16, v81
	v_mul_f32_e32 v28, v28, v29
	v_lshlrev_b32_e32 v29, 16, v85
	v_mul_f32_e32 v31, v28, v29
	v_add_f32_e32 v28, 1.0, v30
	v_rcp_f32_e32 v28, v28
	v_and_b32_e32 v29, 0xffff0000, v81
	v_mul_f32_e32 v17, 0xbfb8aa3b, v17
	v_exp_f32_e32 v17, v17
	v_mul_f32_e32 v28, v28, v29
	v_and_b32_e32 v29, 0xffff0000, v85
	v_mul_f32_e32 v30, v28, v29
	v_lshlrev_b32_e32 v28, 16, v82
	v_mul_f32_e32 v24, v24, v28
	v_lshlrev_b32_e32 v28, 16, v86
	v_mul_f32_e32 v81, v24, v28
	v_add_f32_e32 v24, 1.0, v25
	v_mul_f32_e32 v25, 0xbfb8aa3b, v26
	v_exp_f32_e32 v25, v25
	v_rcp_f32_e32 v24, v24
	v_and_b32_e32 v26, 0xffff0000, v82
	v_pk_add_f32 v[18:19], v[18:19], v[58:59]
	v_add_f32_e32 v25, 1.0, v25
	v_rcp_f32_e32 v25, v25
	v_mul_f32_e32 v24, v24, v26
	v_and_b32_e32 v26, 0xffff0000, v86
	v_mul_f32_e32 v26, v24, v26
	v_lshlrev_b32_e32 v24, 16, v83
	v_mul_f32_e32 v24, v25, v24
	v_add_f32_e32 v25, 1.0, v27
	v_rcp_f32_e32 v25, v25
	v_lshlrev_b32_e32 v27, 16, v87
	v_mul_f32_e32 v27, v24, v27
	v_and_b32_e32 v24, 0xffff0000, v83
	v_mul_f32_e32 v24, v25, v24
	v_and_b32_e32 v25, 0xffff0000, v87
	v_mul_f32_e32 v82, v24, v25
	v_lshl_add_u64 v[24:25], s[58:59], 0, v[88:89]
	v_lshl_add_u64 v[28:29], v[24:25], 0, v[164:165]
	v_cvt_pk_bf16_f32 v24, v90, v80
	v_cvt_pk_bf16_f32 v25, v31, v30
	v_cvt_pk_bf16_f32 v26, v81, v26
	v_cvt_pk_bf16_f32 v27, v27, v82
	global_store_dwordx4 v[28:29], v[24:27], off sc1
	v_mul_f32_e32 v19, 0xbfb8aa3b, v19
	v_exp_f32_e32 v19, v19
	s_waitcnt vmcnt(6)
	v_lshlrev_b32_e32 v24, 16, v52
	v_mul_f32_e32 v20, v20, v24
	s_waitcnt vmcnt(5)
	v_lshlrev_b32_e32 v24, 16, v48
	v_mul_f32_e32 v24, v20, v24
	v_add_f32_e32 v20, 1.0, v21
	v_rcp_f32_e32 v20, v20
	v_and_b32_e32 v21, 0xffff0000, v52
	v_pk_add_f32 v[12:13], v[12:13], v[68:69]
	v_pk_add_f32 v[14:15], v[14:15], v[70:71]
	v_mul_f32_e32 v20, v20, v21
	v_and_b32_e32 v21, 0xffff0000, v48
	v_mul_f32_e32 v25, v20, v21
	v_add_f32_e32 v20, 1.0, v22
	v_rcp_f32_e32 v20, v20
	v_mul_f32_e32 v22, 0xbfb8aa3b, v23
	v_exp_f32_e32 v22, v22
	v_lshlrev_b32_e32 v21, 16, v53
	v_mul_f32_e32 v20, v20, v21
	v_lshlrev_b32_e32 v21, 16, v49
	v_mul_f32_e32 v23, v20, v21
	v_add_f32_e32 v20, 1.0, v22
	v_rcp_f32_e32 v20, v20
	v_and_b32_e32 v21, 0xffff0000, v53
	v_mul_f32_e32 v12, 0xbfb8aa3b, v12
	v_exp_f32_e32 v12, v12
	v_mul_f32_e32 v20, v20, v21
	v_and_b32_e32 v21, 0xffff0000, v49
	v_mul_f32_e32 v22, v20, v21
	v_lshlrev_b32_e32 v20, 16, v54
	v_mul_f32_e32 v16, v16, v20
	v_lshlrev_b32_e32 v20, 16, v50
	v_mul_f32_e32 v26, v16, v20
	v_add_f32_e32 v16, 1.0, v17
	v_mul_f32_e32 v17, 0xbfb8aa3b, v18
	v_exp_f32_e32 v17, v17
	v_rcp_f32_e32 v16, v16
	v_and_b32_e32 v18, 0xffff0000, v54
	v_add_f32_e32 v12, 1.0, v12
	v_add_f32_e32 v17, 1.0, v17
	v_rcp_f32_e32 v17, v17
	v_mul_f32_e32 v16, v16, v18
	v_and_b32_e32 v18, 0xffff0000, v50
	v_mul_f32_e32 v18, v16, v18
	v_lshlrev_b32_e32 v16, 16, v55
	v_mul_f32_e32 v16, v17, v16
	v_add_f32_e32 v17, 1.0, v19
	v_rcp_f32_e32 v17, v17
	v_lshlrev_b32_e32 v19, 16, v51
	v_mul_f32_e32 v19, v16, v19
	v_and_b32_e32 v16, 0xffff0000, v55
	v_mul_f32_e32 v16, v17, v16
	v_and_b32_e32 v17, 0xffff0000, v51
	v_rcp_f32_e32 v12, v12
	v_mul_f32_e32 v13, 0xbfb8aa3b, v13
	v_mul_f32_e32 v27, v16, v17
	v_lshl_add_u64 v[16:17], s[58:59], 0, v[78:79]
	v_exp_f32_e32 v13, v13
	v_lshl_add_u64 v[20:21], v[16:17], 0, v[164:165]
	v_cvt_pk_bf16_f32 v16, v24, v25
	v_cvt_pk_bf16_f32 v17, v23, v22
	v_cvt_pk_bf16_f32 v18, v26, v18
	v_cvt_pk_bf16_f32 v19, v19, v27
	global_store_dwordx4 v[20:21], v[16:19], off sc1
	v_mul_f32_e32 v14, 0xbfb8aa3b, v14
	v_exp_f32_e32 v14, v14
	s_waitcnt vmcnt(5)
	v_lshlrev_b32_e32 v16, 16, v44
	v_mul_f32_e32 v12, v12, v16
	s_waitcnt vmcnt(4)
	v_lshlrev_b32_e32 v16, 16, v40
	v_mul_f32_e32 v16, v12, v16
	v_add_f32_e32 v12, 1.0, v13
	v_rcp_f32_e32 v12, v12
	v_and_b32_e32 v13, 0xffff0000, v44
	v_pk_add_f32 v[8:9], v[8:9], v[64:65]
	v_pk_add_f32 v[10:11], v[10:11], v[66:67]
	v_mul_f32_e32 v12, v12, v13
	v_and_b32_e32 v13, 0xffff0000, v40
	v_mul_f32_e32 v17, v12, v13
	v_add_f32_e32 v12, 1.0, v14
	v_rcp_f32_e32 v12, v12
	v_mul_f32_e32 v14, 0xbfb8aa3b, v15
	v_exp_f32_e32 v14, v14
	v_mul_f32_e32 v8, 0xbfb8aa3b, v8
	v_lshlrev_b32_e32 v13, 16, v45
	v_exp_f32_e32 v8, v8
	v_mul_f32_e32 v12, v12, v13
	v_lshlrev_b32_e32 v13, 16, v41
	v_mul_f32_e32 v15, v12, v13
	v_add_f32_e32 v12, 1.0, v14
	v_rcp_f32_e32 v12, v12
	v_add_f32_e32 v8, 1.0, v8
	v_rcp_f32_e32 v8, v8
	v_mul_f32_e32 v9, 0xbfb8aa3b, v9
	v_and_b32_e32 v13, 0xffff0000, v45
	v_exp_f32_e32 v9, v9
	v_mul_f32_e32 v12, v12, v13
	v_and_b32_e32 v13, 0xffff0000, v41
	v_mul_f32_e32 v14, v12, v13
	v_lshlrev_b32_e32 v12, 16, v46
	v_mul_f32_e32 v8, v8, v12
	v_lshlrev_b32_e32 v12, 16, v42
	v_mul_f32_e32 v18, v8, v12
	v_add_f32_e32 v8, 1.0, v9
	v_mul_f32_e32 v9, 0xbfb8aa3b, v10
	v_exp_f32_e32 v9, v9
	v_rcp_f32_e32 v8, v8
	v_mul_f32_e32 v11, 0xbfb8aa3b, v11
	v_exp_f32_e32 v11, v11
	v_add_f32_e32 v9, 1.0, v9
	v_rcp_f32_e32 v9, v9
	v_and_b32_e32 v10, 0xffff0000, v46
	v_mul_f32_e32 v8, v8, v10
	v_and_b32_e32 v10, 0xffff0000, v42
	v_pk_add_f32 v[4:5], v[4:5], v[60:61]
	v_mul_f32_e32 v10, v8, v10
	v_lshlrev_b32_e32 v8, 16, v47
	v_mul_f32_e32 v4, 0xbfb8aa3b, v4
	v_mul_f32_e32 v8, v9, v8
	v_add_f32_e32 v9, 1.0, v11
	v_exp_f32_e32 v4, v4
	v_rcp_f32_e32 v9, v9
	v_lshlrev_b32_e32 v11, 16, v43
	v_mul_f32_e32 v11, v8, v11
	v_and_b32_e32 v8, 0xffff0000, v47
	v_add_f32_e32 v4, 1.0, v4
	v_mul_f32_e32 v8, v9, v8
	v_and_b32_e32 v9, 0xffff0000, v43
	v_rcp_f32_e32 v4, v4
	v_mul_f32_e32 v5, 0xbfb8aa3b, v5
	v_mul_f32_e32 v19, v8, v9
	v_lshl_add_u64 v[8:9], s[58:59], 0, v[76:77]
	v_exp_f32_e32 v5, v5
	v_lshl_add_u64 v[12:13], v[8:9], 0, v[72:73]
	v_cvt_pk_bf16_f32 v8, v16, v17
	v_cvt_pk_bf16_f32 v9, v15, v14
	v_cvt_pk_bf16_f32 v10, v18, v10
	v_cvt_pk_bf16_f32 v11, v11, v19
	global_store_dwordx4 v[12:13], v[8:11], off sc1
	v_pk_add_f32 v[6:7], v[6:7], v[62:63]
	v_pk_add_f32 v[0:1], v[0:1], v[56:57]
	s_waitcnt vmcnt(4)
	v_lshlrev_b32_e32 v8, 16, v36
	v_mul_f32_e32 v4, v4, v8
	s_waitcnt vmcnt(3)
	v_lshlrev_b32_e32 v8, 16, v32
	v_mul_f32_e32 v8, v4, v8
	v_add_f32_e32 v4, 1.0, v5
	v_rcp_f32_e32 v4, v4
	v_mul_f32_e32 v6, 0xbfb8aa3b, v6
	v_exp_f32_e32 v6, v6
	v_and_b32_e32 v5, 0xffff0000, v36
	v_mul_f32_e32 v4, v4, v5
	v_and_b32_e32 v5, 0xffff0000, v32
	v_mul_f32_e32 v9, v4, v5
	v_add_f32_e32 v4, 1.0, v6
	v_rcp_f32_e32 v4, v4
	v_mul_f32_e32 v6, 0xbfb8aa3b, v7
	v_exp_f32_e32 v6, v6
	v_mul_f32_e32 v0, 0xbfb8aa3b, v0
	v_lshlrev_b32_e32 v5, 16, v37
	v_exp_f32_e32 v0, v0
	v_mul_f32_e32 v4, v4, v5
	v_lshlrev_b32_e32 v5, 16, v33
	v_mul_f32_e32 v7, v4, v5
	v_add_f32_e32 v4, 1.0, v6
	v_rcp_f32_e32 v4, v4
	v_add_f32_e32 v0, 1.0, v0
	v_rcp_f32_e32 v0, v0
	v_mul_f32_e32 v1, 0xbfb8aa3b, v1
	v_and_b32_e32 v5, 0xffff0000, v37
	v_exp_f32_e32 v1, v1
	v_mul_f32_e32 v4, v4, v5
	v_and_b32_e32 v5, 0xffff0000, v33
	v_mul_f32_e32 v6, v4, v5
	v_lshlrev_b32_e32 v4, 16, v38
	v_pk_add_f32 v[2:3], v[2:3], v[58:59]
	v_mul_f32_e32 v0, v0, v4
	v_lshlrev_b32_e32 v4, 16, v34
	v_mul_f32_e32 v10, v0, v4
	v_add_f32_e32 v0, 1.0, v1
	v_mul_f32_e32 v1, 0xbfb8aa3b, v2
	v_exp_f32_e32 v1, v1
	v_rcp_f32_e32 v0, v0
	v_mul_f32_e32 v3, 0xbfb8aa3b, v3
	v_exp_f32_e32 v3, v3
	v_add_f32_e32 v1, 1.0, v1
	v_rcp_f32_e32 v1, v1
	v_and_b32_e32 v2, 0xffff0000, v38
	v_mul_f32_e32 v0, v0, v2
	v_and_b32_e32 v2, 0xffff0000, v34
	v_mul_f32_e32 v2, v0, v2
	v_lshlrev_b32_e32 v0, 16, v39
	v_mul_f32_e32 v0, v1, v0
	v_add_f32_e32 v1, 1.0, v3
	v_rcp_f32_e32 v1, v1
	v_lshlrev_b32_e32 v3, 16, v35
	v_mul_f32_e32 v3, v0, v3
	v_and_b32_e32 v0, 0xffff0000, v39
	v_mul_f32_e32 v0, v1, v0
	v_and_b32_e32 v1, 0xffff0000, v35
	v_mul_f32_e32 v11, v0, v1
	v_lshl_add_u64 v[0:1], s[58:59], 0, v[74:75]
	v_lshl_add_u64 v[4:5], v[0:1], 0, v[72:73]
	v_cvt_pk_bf16_f32 v0, v8, v9
	v_cvt_pk_bf16_f32 v1, v7, v6
	v_cvt_pk_bf16_f32 v2, v10, v2
	v_cvt_pk_bf16_f32 v3, v3, v11
	global_store_dwordx4 v[4:5], v[0:3], off sc1
	s_cbranch_vccnz .LBB0_632
	s_andn2_b64 vcc, exec, s[0:1]
	s_cbranch_vccnz .LBB0_631
	s_barrier
	s_branch .LBB0_631
